# K-loop LDS-DMA loads use SGPR base + 32-bit VGPR offset (saddr) instead of 64-bit VGPR addresses, all 11 GEMM loops
# speedup vs baseline: 1.0064x; 1.0064x over previous
; #define PG8_STAGE(bufoff, gbase, voff) do { _Pragma("unroll") for (int _i = 0; _i < 2; ++_i) \
;         __builtin_amdgcn_global_load_lds((const unsigned*)((const char*)(gbase) + (voff)[_i]), (LAS unsigned*)(lds + (bufoff) + ldsw + _i * 8192), 16, 0, 0); } while (0)
; #define PG8_LDA(dst, b, h) do { _Pragma("unroll") for (int m = 0; m < 4; ++m) _Pragma("unroll") for (int k = 0; k < 2; ++k) dst[m][k] = *(const LAS bf16x8*)(lds + PG8_SA(b, h) + aoff + m * 2048 + k * 1024); } while (0)
; #define PG8_LDB(dst, b, h) do { _Pragma("unroll") for (int n = 0; n < 2; ++n) _Pragma("unroll") for (int k = 0; k < 2; ++k) dst[n][k] = *(const LAS bf16x8*)(lds + PG8_SB(b, h) + boff + n * 2048 + k * 1024); } while (0)
; #define PG8_MMA(ai, bj, At, Bt) do { __builtin_amdgcn_s_setprio(1); _Pragma("unroll") for (int m = 0; m < 4; ++m) _Pragma("unroll") for (int n = 0; n < 2; ++n) _Pragma("unroll") for (int k = 0; k < 2; ++k) \
;         acc[ai][bj][m][n] = __builtin_amdgcn_mfma_f32_16x16x32_bf16(Bt[n][k], At[m][k], acc[ai][bj][m][n], 0, 0, 0); __builtin_amdgcn_s_setprio(0); } while (0)
; #define PG8_WAIT_V(n) asm volatile("s_waitcnt vmcnt(" #n ")" ::: "memory")
; #define PG8_WAIT_L(n) asm volatile("s_waitcnt lgkmcnt(" #n ")" ::: "memory")
; #define PG8_BAR __builtin_amdgcn_s_barrier()
; #define PG8_SCHED __builtin_amdgcn_sched_barrier(0)
; template <class Epi>
; __device__ __forceinline__ void gemm_phase(ldsp lds, const Gemm g, const StaticOrder& S, const Epi& E, int wave0) {
;     ...
;             const char* a1 = cA + (size_t)(t + 1) * kstep;
;             const char* a2 = last ? nA : cA + (size_t)(t + 2) * kstep; const char* b2 = last ? nB : cB + (size_t)(t + 2) * kstep;
;             const char* a3 = a2 + kstep; const char* b3 = b2 + kstep;
;             PG8_LDB(B0, 0, 0); PG8_LDB(B1, 0, 1); PG8_SCHED; PG8_LDA(At, 0, 0); PG8_STAGE(PG8_SA(1, 1), a1 + hstep, voffA);
;             PG8_WAIT_V(8); PG8_WAIT_L(0); PG8_BAR; PG8_MMA(0, 0, At, B0); PG8_MMA(0, 1, At, B1); PG8_BAR; PG8_SCHED;
;             PG8_LDA(At, 0, 1); PG8_STAGE(PG8_SB(0, 0), b2, voffB); PG8_STAGE(PG8_SB(0, 1), b2 + hstep, voffB); PG8_STAGE(PG8_SA(0, 0), a2, voffA);
;             PG8_WAIT_V(8); PG8_WAIT_L(0); PG8_BAR; PG8_MMA(1, 0, At, B0); PG8_MMA(1, 1, At, B1); PG8_BAR; PG8_SCHED;
.LBB0_150:
	ds_read_b128 v[152:155], v149
	ds_read_b128 v[156:159], v149 offset:1024
	ds_read_b128 v[160:163], v149 offset:2048
	ds_read_b128 v[164:167], v149 offset:3072
	ds_read_b128 v[168:171], v150
	ds_read_b128 v[172:175], v150 offset:1024
	ds_read_b128 v[176:179], v150 offset:2048
	ds_read_b128 v[180:183], v150 offset:3072
	s_add_u32 s22, s20, 0xfff80080
	s_addc_u32 s23, s21, -1
	s_cmp_eq_u32 s54, 28
	s_cselect_b32 s25, s13, s23
	s_cselect_b32 s24, s50, s22
	s_cselect_b32 s23, s11, s53
	s_cselect_b32 s22, s51, s52
	s_add_i32 m0, s19, 0xc000
	ds_read_b128 v[184:187], v151
	ds_read_b128 v[188:191], v151 offset:1024
	ds_read_b128 v[192:195], v151 offset:2048
	ds_read_b128 v[196:199], v151 offset:3072
	ds_read_b128 v[200:203], v151 offset:4096
	ds_read_b128 v[204:207], v151 offset:5120
	ds_read_b128 v[208:211], v151 offset:6144
	ds_read_b128 v[212:215], v151 offset:7168
	global_load_lds_dwordx4 v138, s[20:21]
	s_add_i32 m0, s19, 0xe000
	s_nop 0
	global_load_lds_dwordx4 v136, s[20:21]
	s_waitcnt vmcnt(8)
	s_waitcnt lgkmcnt(0)
	s_barrier
	s_setprio 1
	s_waitcnt lgkmcnt(0)
	v_mfma_f32_16x16x32_bf16 v[124:127], v[152:155], v[184:187], v[124:127]
	v_mfma_f32_16x16x32_bf16 v[120:123], v[160:163], v[184:187], v[120:123]
	v_mfma_f32_16x16x32_bf16 v[108:111], v[152:155], v[192:195], v[108:111]
	v_mfma_f32_16x16x32_bf16 v[104:107], v[160:163], v[192:195], v[104:107]
	v_mfma_f32_16x16x32_bf16 v[92:95], v[152:155], v[200:203], v[92:95]
	v_mfma_f32_16x16x32_bf16 v[88:91], v[160:163], v[200:203], v[88:91]
	v_mfma_f32_16x16x32_bf16 v[76:79], v[152:155], v[208:211], v[76:79]
	v_mfma_f32_16x16x32_bf16 v[72:75], v[160:163], v[208:211], v[72:75]
	v_mfma_f32_16x16x32_bf16 v[124:127], v[156:159], v[188:191], v[124:127]
	v_mfma_f32_16x16x32_bf16 v[120:123], v[164:167], v[188:191], v[120:123]
	v_mfma_f32_16x16x32_bf16 v[108:111], v[156:159], v[196:199], v[108:111]
	v_mfma_f32_16x16x32_bf16 v[104:107], v[164:167], v[196:199], v[104:107]
	v_mfma_f32_16x16x32_bf16 v[92:95], v[156:159], v[204:207], v[92:95]
	v_mfma_f32_16x16x32_bf16 v[88:91], v[164:167], v[204:207], v[88:91]
	v_mfma_f32_16x16x32_bf16 v[76:79], v[156:159], v[212:215], v[76:79]
	v_mfma_f32_16x16x32_bf16 v[72:75], v[164:167], v[212:215], v[72:75]
	s_setprio 0
	s_setprio 1
	v_mfma_f32_16x16x32_bf16 v[116:119], v[168:171], v[184:187], v[116:119]
	v_mfma_f32_16x16x32_bf16 v[112:115], v[176:179], v[184:187], v[112:115]
	v_mfma_f32_16x16x32_bf16 v[100:103], v[168:171], v[192:195], v[100:103]
	v_mfma_f32_16x16x32_bf16 v[96:99], v[176:179], v[192:195], v[96:99]
	v_mfma_f32_16x16x32_bf16 v[84:87], v[168:171], v[200:203], v[84:87]
	v_mfma_f32_16x16x32_bf16 v[80:83], v[176:179], v[200:203], v[80:83]
	v_mfma_f32_16x16x32_bf16 v[68:71], v[168:171], v[208:211], v[68:71]
	v_mfma_f32_16x16x32_bf16 v[64:67], v[176:179], v[208:211], v[64:67]
	v_mfma_f32_16x16x32_bf16 v[116:119], v[172:175], v[188:191], v[116:119]
	v_mfma_f32_16x16x32_bf16 v[112:115], v[180:183], v[188:191], v[112:115]
	v_mfma_f32_16x16x32_bf16 v[100:103], v[172:175], v[196:199], v[100:103]
	v_mfma_f32_16x16x32_bf16 v[96:99], v[180:183], v[196:199], v[96:99]
	v_mfma_f32_16x16x32_bf16 v[84:87], v[172:175], v[204:207], v[84:87]
	v_mfma_f32_16x16x32_bf16 v[80:83], v[180:183], v[204:207], v[80:83]
	v_mfma_f32_16x16x32_bf16 v[68:71], v[172:175], v[212:215], v[68:71]
	v_mfma_f32_16x16x32_bf16 v[64:67], v[180:183], v[212:215], v[64:67]
	s_setprio 0
	s_barrier
	s_add_i32 s55, s46, s34
	s_add_u32 s100, s24, 0x80
	s_addc_u32 s101, s25, 0
	s_mov_b32 m0, s55
	ds_read_b128 v[184:187], v151 offset:16384
	ds_read_b128 v[188:191], v151 offset:17408
	ds_read_b128 v[192:195], v151 offset:18432
	ds_read_b128 v[196:199], v151 offset:19456
	ds_read_b128 v[200:203], v151 offset:20480
	ds_read_b128 v[204:207], v151 offset:21504
	ds_read_b128 v[208:211], v151 offset:22528
	ds_read_b128 v[212:215], v151 offset:23552
	global_load_lds_dwordx4 v132, s[22:23]
	s_add_i32 m0, s55, 0x2000
	s_add_u32 s56, s22, 0x80000
	s_addc_u32 s57, s23, 0
	s_add_i32 s55, s47, s34
	global_load_lds_dwordx4 v128, s[22:23]
	s_mov_b32 m0, s55
	s_nop 0
	global_load_lds_dwordx4 v132, s[56:57]
	s_add_i32 m0, s55, 0x2000
	s_nop 0
	global_load_lds_dwordx4 v128, s[56:57]
	s_mov_b32 m0, s19
	s_nop 0
	global_load_lds_dwordx4 v134, s[24:25]
	s_mov_b32 m0, s37
	s_nop 0
	global_load_lds_dwordx4 v130, s[24:25]
	s_waitcnt vmcnt(8)
	s_waitcnt lgkmcnt(0)
	s_barrier
	s_setprio 1
	s_waitcnt lgkmcnt(0)
	v_mfma_f32_16x16x32_bf16 v[60:63], v[152:155], v[184:187], v[60:63]
	v_mfma_f32_16x16x32_bf16 v[56:59], v[160:163], v[184:187], v[56:59]
	v_mfma_f32_16x16x32_bf16 v[44:47], v[152:155], v[192:195], v[44:47]
	v_mfma_f32_16x16x32_bf16 v[40:43], v[160:163], v[192:195], v[40:43]
	v_mfma_f32_16x16x32_bf16 v[28:31], v[152:155], v[200:203], v[28:31]
	v_mfma_f32_16x16x32_bf16 v[24:27], v[160:163], v[200:203], v[24:27]
	v_mfma_f32_16x16x32_bf16 v[12:15], v[152:155], v[208:211], v[12:15]
	v_mfma_f32_16x16x32_bf16 v[8:11], v[160:163], v[208:211], v[8:11]
	v_mfma_f32_16x16x32_bf16 v[60:63], v[156:159], v[188:191], v[60:63]
	v_mfma_f32_16x16x32_bf16 v[56:59], v[164:167], v[188:191], v[56:59]
	v_mfma_f32_16x16x32_bf16 v[44:47], v[156:159], v[196:199], v[44:47]
	v_mfma_f32_16x16x32_bf16 v[40:43], v[164:167], v[196:199], v[40:43]
	v_mfma_f32_16x16x32_bf16 v[28:31], v[156:159], v[204:207], v[28:31]
	v_mfma_f32_16x16x32_bf16 v[24:27], v[164:167], v[204:207], v[24:27]
	v_mfma_f32_16x16x32_bf16 v[12:15], v[156:159], v[212:215], v[12:15]
	v_mfma_f32_16x16x32_bf16 v[8:11], v[164:167], v[212:215], v[8:11]
	s_setprio 0
	s_setprio 1
	v_mfma_f32_16x16x32_bf16 v[52:55], v[168:171], v[184:187], v[52:55]
	v_mfma_f32_16x16x32_bf16 v[48:51], v[176:179], v[184:187], v[48:51]
	v_mfma_f32_16x16x32_bf16 v[36:39], v[168:171], v[192:195], v[36:39]
	v_mfma_f32_16x16x32_bf16 v[32:35], v[176:179], v[192:195], v[32:35]
	v_mfma_f32_16x16x32_bf16 v[20:23], v[168:171], v[200:203], v[20:23]
	v_mfma_f32_16x16x32_bf16 v[16:19], v[176:179], v[200:203], v[16:19]
	v_mfma_f32_16x16x32_bf16 v[4:7], v[168:171], v[208:211], v[4:7]
	v_mfma_f32_16x16x32_bf16 v[0:3], v[176:179], v[208:211], v[0:3]
	v_mfma_f32_16x16x32_bf16 v[52:55], v[172:175], v[188:191], v[52:55]
	v_mfma_f32_16x16x32_bf16 v[48:51], v[180:183], v[188:191], v[48:51]
	v_mfma_f32_16x16x32_bf16 v[36:39], v[172:175], v[196:199], v[36:39]
	v_mfma_f32_16x16x32_bf16 v[32:35], v[180:183], v[196:199], v[32:35]
	v_mfma_f32_16x16x32_bf16 v[20:23], v[172:175], v[204:207], v[20:23]
	v_mfma_f32_16x16x32_bf16 v[16:19], v[180:183], v[204:207], v[16:19]
	v_mfma_f32_16x16x32_bf16 v[4:7], v[172:175], v[212:215], v[4:7]
	v_mfma_f32_16x16x32_bf16 v[0:3], v[180:183], v[212:215], v[0:3]
	s_setprio 0
	s_barrier
; #define PG8_STAGE(bufoff, gbase, voff) do { _Pragma("unroll") for (int _i = 0; _i < 2; ++_i) \
;         __builtin_amdgcn_global_load_lds((const unsigned*)((const char*)(gbase) + (voff)[_i]), (LAS unsigned*)(lds + (bufoff) + ldsw + _i * 8192), 16, 0, 0); } while (0)
; #define PG8_LDA(dst, b, h) do { _Pragma("unroll") for (int m = 0; m < 4; ++m) _Pragma("unroll") for (int k = 0; k < 2; ++k) dst[m][k] = *(const LAS bf16x8*)(lds + PG8_SA(b, h) + aoff + m * 2048 + k * 1024); } while (0)
; #define PG8_LDB(dst, b, h) do { _Pragma("unroll") for (int n = 0; n < 2; ++n) _Pragma("unroll") for (int k = 0; k < 2; ++k) dst[n][k] = *(const LAS bf16x8*)(lds + PG8_SB(b, h) + boff + n * 2048 + k * 1024); } while (0)
; #define PG8_MMA(ai, bj, At, Bt) do { __builtin_amdgcn_s_setprio(1); _Pragma("unroll") for (int m = 0; m < 4; ++m) _Pragma("unroll") for (int n = 0; n < 2; ++n) _Pragma("unroll") for (int k = 0; k < 2; ++k) \
;         acc[ai][bj][m][n] = __builtin_amdgcn_mfma_f32_16x16x32_bf16(Bt[n][k], At[m][k], acc[ai][bj][m][n], 0, 0, 0); __builtin_amdgcn_s_setprio(0); } while (0)
; #define PG8_WAIT_V(n) asm volatile("s_waitcnt vmcnt(" #n ")" ::: "memory")
; #define PG8_WAIT_L(n) asm volatile("s_waitcnt lgkmcnt(" #n ")" ::: "memory")
; #define PG8_BAR __builtin_amdgcn_s_barrier()
; #define PG8_SCHED __builtin_amdgcn_sched_barrier(0)
; template <class Epi>
; __device__ __forceinline__ void gemm_phase(ldsp lds, const Gemm g, const StaticOrder& S, const Epi& E, int wave0) {
;     ...
;             PG8_LDB(B0, 1, 0); PG8_LDB(B1, 1, 1); PG8_SCHED; PG8_LDA(At, 1, 0); PG8_STAGE(PG8_SA(0, 1), a2 + hstep, voffA);
;             PG8_WAIT_V(8); PG8_WAIT_L(0); PG8_BAR; PG8_MMA(0, 0, At, B0); PG8_MMA(0, 1, At, B1); PG8_BAR; PG8_SCHED;
;             PG8_LDA(At, 1, 1); PG8_STAGE(PG8_SB(1, 0), b3, voffB); PG8_STAGE(PG8_SB(1, 1), b3 + hstep, voffB); PG8_STAGE(PG8_SA(1, 0), a3, voffA);
;             PG8_WAIT_V(8); PG8_WAIT_L(0); PG8_BAR; PG8_MMA(1, 0, At, B0); PG8_MMA(1, 1, At, B1); PG8_BAR; PG8_SCHED;
;         }
;         if (wr == 0) PG8_BAR;
	s_add_i32 s55, 0, 0x18000
	s_add_i32 s56, 0, 0x1c000
	v_add_u32_e32 v164, s55, v148
	v_add_u32_e32 v180, s56, v148
	ds_read_b128 v[152:155], v164
	ds_read_b128 v[156:159], v164 offset:1024
	ds_read_b128 v[160:163], v164 offset:2048
	ds_read_b128 v[164:167], v164 offset:3072
	ds_read_b128 v[168:171], v180
	ds_read_b128 v[172:175], v180 offset:1024
	ds_read_b128 v[176:179], v180 offset:2048
	ds_read_b128 v[180:183], v180 offset:3072
	s_add_u32 s24, s24, 0x80000
	s_addc_u32 s25, s25, 0
	s_mov_b32 m0, s38
	ds_read_b128 v[184:187], v151 offset:32768
	ds_read_b128 v[188:191], v151 offset:33792
	ds_read_b128 v[192:195], v151 offset:34816
	ds_read_b128 v[196:199], v151 offset:35840
	ds_read_b128 v[200:203], v151 offset:36864
	ds_read_b128 v[204:207], v151 offset:37888
	ds_read_b128 v[208:211], v151 offset:38912
	ds_read_b128 v[212:215], v151 offset:39936
	global_load_lds_dwordx4 v134, s[24:25]
	s_mov_b32 m0, s39
	s_nop 0
	global_load_lds_dwordx4 v130, s[24:25]
	s_waitcnt vmcnt(8)
	s_waitcnt lgkmcnt(0)
	s_barrier
	s_setprio 1
	s_waitcnt lgkmcnt(0)
	v_mfma_f32_16x16x32_bf16 v[124:127], v[152:155], v[184:187], v[124:127]
	v_mfma_f32_16x16x32_bf16 v[120:123], v[160:163], v[184:187], v[120:123]
	v_mfma_f32_16x16x32_bf16 v[108:111], v[152:155], v[192:195], v[108:111]
	v_mfma_f32_16x16x32_bf16 v[104:107], v[160:163], v[192:195], v[104:107]
	v_mfma_f32_16x16x32_bf16 v[92:95], v[152:155], v[200:203], v[92:95]
	v_mfma_f32_16x16x32_bf16 v[88:91], v[160:163], v[200:203], v[88:91]
	v_mfma_f32_16x16x32_bf16 v[76:79], v[152:155], v[208:211], v[76:79]
	v_mfma_f32_16x16x32_bf16 v[72:75], v[160:163], v[208:211], v[72:75]
	v_mfma_f32_16x16x32_bf16 v[124:127], v[156:159], v[188:191], v[124:127]
	v_mfma_f32_16x16x32_bf16 v[120:123], v[164:167], v[188:191], v[120:123]
	v_mfma_f32_16x16x32_bf16 v[108:111], v[156:159], v[196:199], v[108:111]
	v_mfma_f32_16x16x32_bf16 v[104:107], v[164:167], v[196:199], v[104:107]
	v_mfma_f32_16x16x32_bf16 v[92:95], v[156:159], v[204:207], v[92:95]
	v_mfma_f32_16x16x32_bf16 v[88:91], v[164:167], v[204:207], v[88:91]
	v_mfma_f32_16x16x32_bf16 v[76:79], v[156:159], v[212:215], v[76:79]
	v_mfma_f32_16x16x32_bf16 v[72:75], v[164:167], v[212:215], v[72:75]
	s_setprio 0
	s_setprio 1
	v_mfma_f32_16x16x32_bf16 v[116:119], v[168:171], v[184:187], v[116:119]
	v_mfma_f32_16x16x32_bf16 v[112:115], v[176:179], v[184:187], v[112:115]
	v_mfma_f32_16x16x32_bf16 v[100:103], v[168:171], v[192:195], v[100:103]
	v_mfma_f32_16x16x32_bf16 v[96:99], v[176:179], v[192:195], v[96:99]
	v_mfma_f32_16x16x32_bf16 v[84:87], v[168:171], v[200:203], v[84:87]
	v_mfma_f32_16x16x32_bf16 v[80:83], v[176:179], v[200:203], v[80:83]
	v_mfma_f32_16x16x32_bf16 v[68:71], v[168:171], v[208:211], v[68:71]
	v_mfma_f32_16x16x32_bf16 v[64:67], v[176:179], v[208:211], v[64:67]
	v_mfma_f32_16x16x32_bf16 v[116:119], v[172:175], v[188:191], v[116:119]
	v_mfma_f32_16x16x32_bf16 v[112:115], v[180:183], v[188:191], v[112:115]
	v_mfma_f32_16x16x32_bf16 v[100:103], v[172:175], v[196:199], v[100:103]
	v_mfma_f32_16x16x32_bf16 v[96:99], v[180:183], v[196:199], v[96:99]
	v_mfma_f32_16x16x32_bf16 v[84:87], v[172:175], v[204:207], v[84:87]
	v_mfma_f32_16x16x32_bf16 v[80:83], v[180:183], v[204:207], v[80:83]
	v_mfma_f32_16x16x32_bf16 v[68:71], v[172:175], v[212:215], v[68:71]
	v_mfma_f32_16x16x32_bf16 v[64:67], v[180:183], v[212:215], v[64:67]
	s_setprio 0
	s_barrier
	s_add_i32 s24, s55, s34
	s_add_u32 s22, s22, 0x80
	s_addc_u32 s23, s23, 0
	s_mov_b32 m0, s24
	ds_read_b128 v[184:187], v151 offset:49152
	ds_read_b128 v[188:191], v151 offset:50176
	ds_read_b128 v[192:195], v151 offset:51200
	ds_read_b128 v[196:199], v151 offset:52224
	ds_read_b128 v[200:203], v151 offset:53248
	ds_read_b128 v[204:207], v151 offset:54272
	ds_read_b128 v[208:211], v151 offset:55296
	ds_read_b128 v[212:215], v151 offset:56320
	global_load_lds_dwordx4 v132, s[22:23]
	s_add_i32 m0, s24, 0x2000
	s_add_i32 s24, s56, s34
	global_load_lds_dwordx4 v128, s[22:23]
	s_add_u32 s22, s22, 0x80000
	s_addc_u32 s23, s23, 0
	s_mov_b32 m0, s24
	s_nop 0
	global_load_lds_dwordx4 v132, s[22:23]
	s_add_i32 m0, s24, 0x2000
	s_nop 0
	global_load_lds_dwordx4 v128, s[22:23]
	s_mov_b32 m0, s42
	s_nop 0
	global_load_lds_dwordx4 v134, s[100:101]
	s_mov_b32 m0, s43
	s_nop 0
	global_load_lds_dwordx4 v130, s[100:101]
	s_waitcnt vmcnt(8)
	s_waitcnt lgkmcnt(0)
	s_barrier
	s_setprio 1
	s_waitcnt lgkmcnt(0)
	v_mfma_f32_16x16x32_bf16 v[60:63], v[152:155], v[184:187], v[60:63]
	v_mfma_f32_16x16x32_bf16 v[56:59], v[160:163], v[184:187], v[56:59]
	v_mfma_f32_16x16x32_bf16 v[44:47], v[152:155], v[192:195], v[44:47]
	v_mfma_f32_16x16x32_bf16 v[40:43], v[160:163], v[192:195], v[40:43]
	v_mfma_f32_16x16x32_bf16 v[28:31], v[152:155], v[200:203], v[28:31]
	v_mfma_f32_16x16x32_bf16 v[24:27], v[160:163], v[200:203], v[24:27]
	v_mfma_f32_16x16x32_bf16 v[12:15], v[152:155], v[208:211], v[12:15]
	v_mfma_f32_16x16x32_bf16 v[8:11], v[160:163], v[208:211], v[8:11]
	v_mfma_f32_16x16x32_bf16 v[60:63], v[156:159], v[188:191], v[60:63]
	v_mfma_f32_16x16x32_bf16 v[56:59], v[164:167], v[188:191], v[56:59]
	v_mfma_f32_16x16x32_bf16 v[44:47], v[156:159], v[196:199], v[44:47]
	v_mfma_f32_16x16x32_bf16 v[40:43], v[164:167], v[196:199], v[40:43]
	v_mfma_f32_16x16x32_bf16 v[28:31], v[156:159], v[204:207], v[28:31]
	v_mfma_f32_16x16x32_bf16 v[24:27], v[164:167], v[204:207], v[24:27]
	v_mfma_f32_16x16x32_bf16 v[12:15], v[156:159], v[212:215], v[12:15]
	v_mfma_f32_16x16x32_bf16 v[8:11], v[164:167], v[212:215], v[8:11]
	s_setprio 0
	s_setprio 1
	v_mfma_f32_16x16x32_bf16 v[52:55], v[168:171], v[184:187], v[52:55]
	v_mfma_f32_16x16x32_bf16 v[48:51], v[176:179], v[184:187], v[48:51]
	v_mfma_f32_16x16x32_bf16 v[36:39], v[168:171], v[192:195], v[36:39]
	v_mfma_f32_16x16x32_bf16 v[32:35], v[176:179], v[192:195], v[32:35]
	v_mfma_f32_16x16x32_bf16 v[20:23], v[168:171], v[200:203], v[20:23]
	v_mfma_f32_16x16x32_bf16 v[16:19], v[176:179], v[200:203], v[16:19]
	v_mfma_f32_16x16x32_bf16 v[4:7], v[168:171], v[208:211], v[4:7]
	v_mfma_f32_16x16x32_bf16 v[0:3], v[176:179], v[208:211], v[0:3]
	v_mfma_f32_16x16x32_bf16 v[52:55], v[172:175], v[188:191], v[52:55]
	v_mfma_f32_16x16x32_bf16 v[48:51], v[180:183], v[188:191], v[48:51]
	v_mfma_f32_16x16x32_bf16 v[36:39], v[172:175], v[196:199], v[36:39]
	v_mfma_f32_16x16x32_bf16 v[32:35], v[180:183], v[196:199], v[32:35]
	v_mfma_f32_16x16x32_bf16 v[20:23], v[172:175], v[204:207], v[20:23]
	v_mfma_f32_16x16x32_bf16 v[16:19], v[180:183], v[204:207], v[16:19]
	v_mfma_f32_16x16x32_bf16 v[4:7], v[172:175], v[212:215], v[4:7]
	v_mfma_f32_16x16x32_bf16 v[0:3], v[180:183], v[212:215], v[0:3]
	s_setprio 0
	s_barrier
	s_add_i32 s54, s54, 2
	s_add_u32 s52, s52, 0x100
	s_addc_u32 s53, s53, 0
	s_add_u32 s20, s20, 0x100
	s_addc_u32 s21, s21, 0
	s_cmp_gt_u32 s54, 29
	s_cbranch_scc0 .LBB0_150
	s_and_b64 vcc, exec, s[8:9]
	s_cbranch_vccz .LBB0_153
	s_barrier

; #define PG8_STAGE(bufoff, gbase, voff) do { _Pragma("unroll") for (int _i = 0; _i < 2; ++_i) \
;         __builtin_amdgcn_global_load_lds((const unsigned*)((const char*)(gbase) + (voff)[_i]), (LAS unsigned*)(lds + (bufoff) + ldsw + _i * 8192), 16, 0, 0); } while (0)
; #define PG8_LDA(dst, b, h) do { _Pragma("unroll") for (int m = 0; m < 4; ++m) _Pragma("unroll") for (int k = 0; k < 2; ++k) dst[m][k] = *(const LAS bf16x8*)(lds + PG8_SA(b, h) + aoff + m * 2048 + k * 1024); } while (0)
; #define PG8_LDB(dst, b, h) do { _Pragma("unroll") for (int n = 0; n < 2; ++n) _Pragma("unroll") for (int k = 0; k < 2; ++k) dst[n][k] = *(const LAS bf16x8*)(lds + PG8_SB(b, h) + boff + n * 2048 + k * 1024); } while (0)
; #define PG8_MMA(ai, bj, At, Bt) do { __builtin_amdgcn_s_setprio(1); _Pragma("unroll") for (int m = 0; m < 4; ++m) _Pragma("unroll") for (int n = 0; n < 2; ++n) _Pragma("unroll") for (int k = 0; k < 2; ++k) \
;         acc[ai][bj][m][n] = __builtin_amdgcn_mfma_f32_16x16x32_bf16(Bt[n][k], At[m][k], acc[ai][bj][m][n], 0, 0, 0); __builtin_amdgcn_s_setprio(0); } while (0)
; #define PG8_WAIT_V(n) asm volatile("s_waitcnt vmcnt(" #n ")" ::: "memory")
; #define PG8_WAIT_L(n) asm volatile("s_waitcnt lgkmcnt(" #n ")" ::: "memory")
; #define PG8_BAR __builtin_amdgcn_s_barrier()
; #define PG8_SCHED __builtin_amdgcn_sched_barrier(0)
; template <class Epi>
; __device__ __forceinline__ void gemm_phase(ldsp lds, const Gemm g, const StaticOrder& S, const Epi& E, int wave0) {
;     ...
;             const char* a1 = cA + (size_t)(t + 1) * kstep;
;             const char* a2 = last ? nA : cA + (size_t)(t + 2) * kstep; const char* b2 = last ? nB : cB + (size_t)(t + 2) * kstep;
;             const char* a3 = a2 + kstep; const char* b3 = b2 + kstep;
;             PG8_LDB(B0, 0, 0); PG8_LDB(B1, 0, 1); PG8_SCHED; PG8_LDA(At, 0, 0); PG8_STAGE(PG8_SA(1, 1), a1 + hstep, voffA);
;             PG8_WAIT_V(8); PG8_WAIT_L(0); PG8_BAR; PG8_MMA(0, 0, At, B0); PG8_MMA(0, 1, At, B1); PG8_BAR; PG8_SCHED;
;             PG8_LDA(At, 0, 1); PG8_STAGE(PG8_SB(0, 0), b2, voffB); PG8_STAGE(PG8_SB(0, 1), b2 + hstep, voffB); PG8_STAGE(PG8_SA(0, 0), a2, voffA);
;             PG8_WAIT_V(8); PG8_WAIT_L(0); PG8_BAR; PG8_MMA(1, 0, At, B0); PG8_MMA(1, 1, At, B1); PG8_BAR; PG8_SCHED;
.LBB0_222:
	ds_read_b128 v[152:155], v149
	ds_read_b128 v[156:159], v149 offset:1024
	ds_read_b128 v[160:163], v149 offset:2048
	ds_read_b128 v[164:167], v149 offset:3072
	ds_read_b128 v[168:171], v150
	ds_read_b128 v[172:175], v150 offset:1024
	ds_read_b128 v[176:179], v150 offset:2048
	ds_read_b128 v[180:183], v150 offset:3072
	s_add_u32 s36, s34, 0x100
	s_addc_u32 s37, s35, 0
	s_cmpk_eq_i32 s69, 0x54
	s_cselect_b32 s41, s5, s37
	s_cselect_b32 s40, s4, s36
	s_cselect_b32 s39, s31, s68
	s_cselect_b32 s38, s30, s67
	s_add_i32 m0, s49, 0xc000
	ds_read_b128 v[184:187], v151
	ds_read_b128 v[188:191], v151 offset:1024
	ds_read_b128 v[192:195], v151 offset:2048
	ds_read_b128 v[196:199], v151 offset:3072
	ds_read_b128 v[200:203], v151 offset:4096
	ds_read_b128 v[204:207], v151 offset:5120
	ds_read_b128 v[208:211], v151 offset:6144
	ds_read_b128 v[212:215], v151 offset:7168
	global_load_lds_dwordx4 v138, s[34:35]
	s_add_i32 m0, s49, 0xe000
	s_nop 0
	global_load_lds_dwordx4 v136, s[34:35]
	s_waitcnt vmcnt(8)
	s_waitcnt lgkmcnt(0)
	s_barrier
	s_setprio 1
	s_waitcnt lgkmcnt(0)
	v_mfma_f32_16x16x32_bf16 v[124:127], v[152:155], v[184:187], v[124:127]
	v_mfma_f32_16x16x32_bf16 v[120:123], v[160:163], v[184:187], v[120:123]
	v_mfma_f32_16x16x32_bf16 v[112:115], v[152:155], v[192:195], v[112:115]
	v_mfma_f32_16x16x32_bf16 v[104:107], v[160:163], v[192:195], v[104:107]
	v_mfma_f32_16x16x32_bf16 v[96:99], v[152:155], v[200:203], v[96:99]
	v_mfma_f32_16x16x32_bf16 v[88:91], v[160:163], v[200:203], v[88:91]
	v_mfma_f32_16x16x32_bf16 v[80:83], v[152:155], v[208:211], v[80:83]
	v_mfma_f32_16x16x32_bf16 v[72:75], v[160:163], v[208:211], v[72:75]
	v_mfma_f32_16x16x32_bf16 v[124:127], v[156:159], v[188:191], v[124:127]
	v_mfma_f32_16x16x32_bf16 v[120:123], v[164:167], v[188:191], v[120:123]
	v_mfma_f32_16x16x32_bf16 v[112:115], v[156:159], v[196:199], v[112:115]
	v_mfma_f32_16x16x32_bf16 v[104:107], v[164:167], v[196:199], v[104:107]
	v_mfma_f32_16x16x32_bf16 v[96:99], v[156:159], v[204:207], v[96:99]
	v_mfma_f32_16x16x32_bf16 v[88:91], v[164:167], v[204:207], v[88:91]
	v_mfma_f32_16x16x32_bf16 v[80:83], v[156:159], v[212:215], v[80:83]
	v_mfma_f32_16x16x32_bf16 v[72:75], v[164:167], v[212:215], v[72:75]
	s_setprio 0
	s_setprio 1
	v_mfma_f32_16x16x32_bf16 v[116:119], v[168:171], v[184:187], v[116:119]
	v_mfma_f32_16x16x32_bf16 v[108:111], v[176:179], v[184:187], v[108:111]
	v_mfma_f32_16x16x32_bf16 v[100:103], v[168:171], v[192:195], v[100:103]
	v_mfma_f32_16x16x32_bf16 v[92:95], v[176:179], v[192:195], v[92:95]
	v_mfma_f32_16x16x32_bf16 v[84:87], v[168:171], v[200:203], v[84:87]
	v_mfma_f32_16x16x32_bf16 v[76:79], v[176:179], v[200:203], v[76:79]
	v_mfma_f32_16x16x32_bf16 v[68:71], v[168:171], v[208:211], v[68:71]
	v_mfma_f32_16x16x32_bf16 v[64:67], v[176:179], v[208:211], v[64:67]
	v_mfma_f32_16x16x32_bf16 v[116:119], v[172:175], v[188:191], v[116:119]
	v_mfma_f32_16x16x32_bf16 v[108:111], v[180:183], v[188:191], v[108:111]
	v_mfma_f32_16x16x32_bf16 v[100:103], v[172:175], v[196:199], v[100:103]
	v_mfma_f32_16x16x32_bf16 v[92:95], v[180:183], v[196:199], v[92:95]
	v_mfma_f32_16x16x32_bf16 v[84:87], v[172:175], v[204:207], v[84:87]
	v_mfma_f32_16x16x32_bf16 v[76:79], v[180:183], v[204:207], v[76:79]
	v_mfma_f32_16x16x32_bf16 v[68:71], v[172:175], v[212:215], v[68:71]
	v_mfma_f32_16x16x32_bf16 v[64:67], v[180:183], v[212:215], v[64:67]
	s_setprio 0
	s_barrier
	s_add_i32 s34, s61, s48
	s_mov_b32 m0, s34
	ds_read_b128 v[184:187], v151 offset:16384
	ds_read_b128 v[188:191], v151 offset:17408
	ds_read_b128 v[192:195], v151 offset:18432
	ds_read_b128 v[196:199], v151 offset:19456
	ds_read_b128 v[200:203], v151 offset:20480
	ds_read_b128 v[204:207], v151 offset:21504
	ds_read_b128 v[208:211], v151 offset:22528
	ds_read_b128 v[212:215], v151 offset:23552
	global_load_lds_dwordx4 v130, s[38:39]
	s_add_i32 m0, s34, 0x2000
	s_add_u32 s34, s38, 0x160000
	s_addc_u32 s35, s39, 0
	s_add_i32 s70, s62, s48
	global_load_lds_dwordx4 v134, s[38:39]
	s_mov_b32 m0, s70
	s_nop 0
	global_load_lds_dwordx4 v130, s[34:35]
	s_add_i32 m0, s70, 0x2000
	s_nop 0
	global_load_lds_dwordx4 v134, s[34:35]
	s_mov_b32 m0, s49
	s_nop 0
	global_load_lds_dwordx4 v128, s[40:41]
	s_mov_b32 m0, s50
	s_nop 0
	global_load_lds_dwordx4 v132, s[40:41]
	s_waitcnt vmcnt(8)
	s_waitcnt lgkmcnt(0)
	s_barrier
	s_setprio 1
	s_waitcnt lgkmcnt(0)
	v_mfma_f32_16x16x32_bf16 v[60:63], v[152:155], v[184:187], v[60:63]
	v_mfma_f32_16x16x32_bf16 v[56:59], v[160:163], v[184:187], v[56:59]
	v_mfma_f32_16x16x32_bf16 v[48:51], v[152:155], v[192:195], v[48:51]
	v_mfma_f32_16x16x32_bf16 v[40:43], v[160:163], v[192:195], v[40:43]
	v_mfma_f32_16x16x32_bf16 v[32:35], v[152:155], v[200:203], v[32:35]
	v_mfma_f32_16x16x32_bf16 v[24:27], v[160:163], v[200:203], v[24:27]
	v_mfma_f32_16x16x32_bf16 v[16:19], v[152:155], v[208:211], v[16:19]
	v_mfma_f32_16x16x32_bf16 v[8:11], v[160:163], v[208:211], v[8:11]
	v_mfma_f32_16x16x32_bf16 v[60:63], v[156:159], v[188:191], v[60:63]
	v_mfma_f32_16x16x32_bf16 v[56:59], v[164:167], v[188:191], v[56:59]
	v_mfma_f32_16x16x32_bf16 v[48:51], v[156:159], v[196:199], v[48:51]
	v_mfma_f32_16x16x32_bf16 v[40:43], v[164:167], v[196:199], v[40:43]
	v_mfma_f32_16x16x32_bf16 v[32:35], v[156:159], v[204:207], v[32:35]
	v_mfma_f32_16x16x32_bf16 v[24:27], v[164:167], v[204:207], v[24:27]
	v_mfma_f32_16x16x32_bf16 v[16:19], v[156:159], v[212:215], v[16:19]
	v_mfma_f32_16x16x32_bf16 v[8:11], v[164:167], v[212:215], v[8:11]
	s_setprio 0
	s_setprio 1
	v_mfma_f32_16x16x32_bf16 v[52:55], v[168:171], v[184:187], v[52:55]
	v_mfma_f32_16x16x32_bf16 v[44:47], v[176:179], v[184:187], v[44:47]
	v_mfma_f32_16x16x32_bf16 v[36:39], v[168:171], v[192:195], v[36:39]
	v_mfma_f32_16x16x32_bf16 v[28:31], v[176:179], v[192:195], v[28:31]
	v_mfma_f32_16x16x32_bf16 v[20:23], v[168:171], v[200:203], v[20:23]
	v_mfma_f32_16x16x32_bf16 v[12:15], v[176:179], v[200:203], v[12:15]
	v_mfma_f32_16x16x32_bf16 v[4:7], v[168:171], v[208:211], v[4:7]
	v_mfma_f32_16x16x32_bf16 v[0:3], v[176:179], v[208:211], v[0:3]
	v_mfma_f32_16x16x32_bf16 v[52:55], v[172:175], v[188:191], v[52:55]
	v_mfma_f32_16x16x32_bf16 v[44:47], v[180:183], v[188:191], v[44:47]
	v_mfma_f32_16x16x32_bf16 v[36:39], v[172:175], v[196:199], v[36:39]
	v_mfma_f32_16x16x32_bf16 v[28:31], v[180:183], v[196:199], v[28:31]
	v_mfma_f32_16x16x32_bf16 v[20:23], v[172:175], v[204:207], v[20:23]
	v_mfma_f32_16x16x32_bf16 v[12:15], v[180:183], v[204:207], v[12:15]
	v_mfma_f32_16x16x32_bf16 v[4:7], v[172:175], v[212:215], v[4:7]
	v_mfma_f32_16x16x32_bf16 v[0:3], v[180:183], v[212:215], v[0:3]
	s_setprio 0
	s_barrier
; #define PG8_STAGE(bufoff, gbase, voff) do { _Pragma("unroll") for (int _i = 0; _i < 2; ++_i) \
;         __builtin_amdgcn_global_load_lds((const unsigned*)((const char*)(gbase) + (voff)[_i]), (LAS unsigned*)(lds + (bufoff) + ldsw + _i * 8192), 16, 0, 0); } while (0)
; #define PG8_LDA(dst, b, h) do { _Pragma("unroll") for (int m = 0; m < 4; ++m) _Pragma("unroll") for (int k = 0; k < 2; ++k) dst[m][k] = *(const LAS bf16x8*)(lds + PG8_SA(b, h) + aoff + m * 2048 + k * 1024); } while (0)
; #define PG8_LDB(dst, b, h) do { _Pragma("unroll") for (int n = 0; n < 2; ++n) _Pragma("unroll") for (int k = 0; k < 2; ++k) dst[n][k] = *(const LAS bf16x8*)(lds + PG8_SB(b, h) + boff + n * 2048 + k * 1024); } while (0)
; #define PG8_MMA(ai, bj, At, Bt) do { __builtin_amdgcn_s_setprio(1); _Pragma("unroll") for (int m = 0; m < 4; ++m) _Pragma("unroll") for (int n = 0; n < 2; ++n) _Pragma("unroll") for (int k = 0; k < 2; ++k) \
;         acc[ai][bj][m][n] = __builtin_amdgcn_mfma_f32_16x16x32_bf16(Bt[n][k], At[m][k], acc[ai][bj][m][n], 0, 0, 0); __builtin_amdgcn_s_setprio(0); } while (0)
; #define PG8_WAIT_V(n) asm volatile("s_waitcnt vmcnt(" #n ")" ::: "memory")
; #define PG8_WAIT_L(n) asm volatile("s_waitcnt lgkmcnt(" #n ")" ::: "memory")
; #define PG8_BAR __builtin_amdgcn_s_barrier()
; #define PG8_SCHED __builtin_amdgcn_sched_barrier(0)
; template <class Epi>
; __device__ __forceinline__ void gemm_phase(ldsp lds, const Gemm g, const StaticOrder& S, const Epi& E, int wave0) {
;     ...
;             PG8_LDB(B0, 1, 0); PG8_LDB(B1, 1, 1); PG8_SCHED; PG8_LDA(At, 1, 0); PG8_STAGE(PG8_SA(0, 1), a2 + hstep, voffA);
;             PG8_WAIT_V(8); PG8_WAIT_L(0); PG8_BAR; PG8_MMA(0, 0, At, B0); PG8_MMA(0, 1, At, B1); PG8_BAR; PG8_SCHED;
;             PG8_LDA(At, 1, 1); PG8_STAGE(PG8_SB(1, 0), b3, voffB); PG8_STAGE(PG8_SB(1, 1), b3 + hstep, voffB); PG8_STAGE(PG8_SA(1, 0), a3, voffA);
;             PG8_WAIT_V(8); PG8_WAIT_L(0); PG8_BAR; PG8_MMA(1, 0, At, B0); PG8_MMA(1, 1, At, B1); PG8_BAR; PG8_SCHED;
;         }
;         if (wr == 0) PG8_BAR;
	s_add_i32 s70, 0, 0x18000
	s_add_i32 s71, 0, 0x1c000
	v_add_u32_e32 v164, s70, v148
	v_add_u32_e32 v180, s71, v148
	ds_read_b128 v[152:155], v164
	ds_read_b128 v[156:159], v164 offset:1024
	ds_read_b128 v[160:163], v164 offset:2048
	ds_read_b128 v[164:167], v164 offset:3072
	ds_read_b128 v[168:171], v180
	ds_read_b128 v[172:175], v180 offset:1024
	ds_read_b128 v[176:179], v180 offset:2048
	ds_read_b128 v[180:183], v180 offset:3072
	s_add_u32 s34, s40, 0x160000
	s_addc_u32 s35, s41, 0
	s_mov_b32 m0, s51
	ds_read_b128 v[184:187], v151 offset:32768
	ds_read_b128 v[188:191], v151 offset:33792
	ds_read_b128 v[192:195], v151 offset:34816
	ds_read_b128 v[196:199], v151 offset:35840
	ds_read_b128 v[200:203], v151 offset:36864
	ds_read_b128 v[204:207], v151 offset:37888
	ds_read_b128 v[208:211], v151 offset:38912
	ds_read_b128 v[212:215], v151 offset:39936
	global_load_lds_dwordx4 v128, s[34:35]
	s_mov_b32 m0, s52
	s_nop 0
	global_load_lds_dwordx4 v132, s[34:35]
	s_waitcnt vmcnt(8)
	s_waitcnt lgkmcnt(0)
	s_barrier
	s_setprio 1
	s_waitcnt lgkmcnt(0)
	v_mfma_f32_16x16x32_bf16 v[124:127], v[152:155], v[184:187], v[124:127]
	v_mfma_f32_16x16x32_bf16 v[120:123], v[160:163], v[184:187], v[120:123]
	v_mfma_f32_16x16x32_bf16 v[112:115], v[152:155], v[192:195], v[112:115]
	v_mfma_f32_16x16x32_bf16 v[104:107], v[160:163], v[192:195], v[104:107]
	v_mfma_f32_16x16x32_bf16 v[96:99], v[152:155], v[200:203], v[96:99]
	v_mfma_f32_16x16x32_bf16 v[88:91], v[160:163], v[200:203], v[88:91]
	v_mfma_f32_16x16x32_bf16 v[80:83], v[152:155], v[208:211], v[80:83]
	v_mfma_f32_16x16x32_bf16 v[72:75], v[160:163], v[208:211], v[72:75]
	v_mfma_f32_16x16x32_bf16 v[124:127], v[156:159], v[188:191], v[124:127]
	v_mfma_f32_16x16x32_bf16 v[120:123], v[164:167], v[188:191], v[120:123]
	v_mfma_f32_16x16x32_bf16 v[112:115], v[156:159], v[196:199], v[112:115]
	v_mfma_f32_16x16x32_bf16 v[104:107], v[164:167], v[196:199], v[104:107]
	v_mfma_f32_16x16x32_bf16 v[96:99], v[156:159], v[204:207], v[96:99]
	v_mfma_f32_16x16x32_bf16 v[88:91], v[164:167], v[204:207], v[88:91]
	v_mfma_f32_16x16x32_bf16 v[80:83], v[156:159], v[212:215], v[80:83]
	v_mfma_f32_16x16x32_bf16 v[72:75], v[164:167], v[212:215], v[72:75]
	s_setprio 0
	s_setprio 1
	v_mfma_f32_16x16x32_bf16 v[116:119], v[168:171], v[184:187], v[116:119]
	v_mfma_f32_16x16x32_bf16 v[108:111], v[176:179], v[184:187], v[108:111]
	v_mfma_f32_16x16x32_bf16 v[100:103], v[168:171], v[192:195], v[100:103]
	v_mfma_f32_16x16x32_bf16 v[92:95], v[176:179], v[192:195], v[92:95]
	v_mfma_f32_16x16x32_bf16 v[84:87], v[168:171], v[200:203], v[84:87]
	v_mfma_f32_16x16x32_bf16 v[76:79], v[176:179], v[200:203], v[76:79]
	v_mfma_f32_16x16x32_bf16 v[68:71], v[168:171], v[208:211], v[68:71]
	v_mfma_f32_16x16x32_bf16 v[64:67], v[176:179], v[208:211], v[64:67]
	v_mfma_f32_16x16x32_bf16 v[116:119], v[172:175], v[188:191], v[116:119]
	v_mfma_f32_16x16x32_bf16 v[108:111], v[180:183], v[188:191], v[108:111]
	v_mfma_f32_16x16x32_bf16 v[100:103], v[172:175], v[196:199], v[100:103]
	v_mfma_f32_16x16x32_bf16 v[92:95], v[180:183], v[196:199], v[92:95]
	v_mfma_f32_16x16x32_bf16 v[84:87], v[172:175], v[204:207], v[84:87]
	v_mfma_f32_16x16x32_bf16 v[76:79], v[180:183], v[204:207], v[76:79]
	v_mfma_f32_16x16x32_bf16 v[68:71], v[172:175], v[212:215], v[68:71]
	v_mfma_f32_16x16x32_bf16 v[64:67], v[180:183], v[212:215], v[64:67]
	s_setprio 0
	s_barrier
	s_add_i32 s34, s70, s48
	s_add_u32 s100, s38, 0x80
	s_addc_u32 s101, s39, 0
	s_add_u32 s98, s40, 0x80
	s_addc_u32 s99, s41, 0
	s_mov_b32 m0, s34
	ds_read_b128 v[184:187], v151 offset:49152
	ds_read_b128 v[188:191], v151 offset:50176
	ds_read_b128 v[192:195], v151 offset:51200
	ds_read_b128 v[196:199], v151 offset:52224
	ds_read_b128 v[200:203], v151 offset:53248
	ds_read_b128 v[204:207], v151 offset:54272
	ds_read_b128 v[208:211], v151 offset:55296
	ds_read_b128 v[212:215], v151 offset:56320
	global_load_lds_dwordx4 v130, s[100:101]
	s_add_i32 m0, s34, 0x2000
	s_add_u32 s34, s38, 0x160080
	s_addc_u32 s35, s39, 0
	s_add_i32 s38, s71, s48
	global_load_lds_dwordx4 v134, s[100:101]
	s_mov_b32 m0, s38
	s_nop 0
	global_load_lds_dwordx4 v130, s[34:35]
	s_add_i32 m0, s38, 0x2000
	s_nop 0
	global_load_lds_dwordx4 v134, s[34:35]
	s_mov_b32 m0, s56
	s_nop 0
	global_load_lds_dwordx4 v128, s[98:99]
	s_mov_b32 m0, s57
	s_nop 0
	global_load_lds_dwordx4 v132, s[98:99]
	s_waitcnt vmcnt(8)
	s_waitcnt lgkmcnt(0)
	s_barrier
	s_setprio 1
	s_waitcnt lgkmcnt(0)
	v_mfma_f32_16x16x32_bf16 v[60:63], v[152:155], v[184:187], v[60:63]
	v_mfma_f32_16x16x32_bf16 v[56:59], v[160:163], v[184:187], v[56:59]
	v_mfma_f32_16x16x32_bf16 v[48:51], v[152:155], v[192:195], v[48:51]
	v_mfma_f32_16x16x32_bf16 v[40:43], v[160:163], v[192:195], v[40:43]
	v_mfma_f32_16x16x32_bf16 v[32:35], v[152:155], v[200:203], v[32:35]
	v_mfma_f32_16x16x32_bf16 v[24:27], v[160:163], v[200:203], v[24:27]
	v_mfma_f32_16x16x32_bf16 v[16:19], v[152:155], v[208:211], v[16:19]
	v_mfma_f32_16x16x32_bf16 v[8:11], v[160:163], v[208:211], v[8:11]
	v_mfma_f32_16x16x32_bf16 v[60:63], v[156:159], v[188:191], v[60:63]
	v_mfma_f32_16x16x32_bf16 v[56:59], v[164:167], v[188:191], v[56:59]
	v_mfma_f32_16x16x32_bf16 v[48:51], v[156:159], v[196:199], v[48:51]
	v_mfma_f32_16x16x32_bf16 v[40:43], v[164:167], v[196:199], v[40:43]
	v_mfma_f32_16x16x32_bf16 v[32:35], v[156:159], v[204:207], v[32:35]
	v_mfma_f32_16x16x32_bf16 v[24:27], v[164:167], v[204:207], v[24:27]
	v_mfma_f32_16x16x32_bf16 v[16:19], v[156:159], v[212:215], v[16:19]
	v_mfma_f32_16x16x32_bf16 v[8:11], v[164:167], v[212:215], v[8:11]
	s_setprio 0
	s_setprio 1
	v_mfma_f32_16x16x32_bf16 v[52:55], v[168:171], v[184:187], v[52:55]
	v_mfma_f32_16x16x32_bf16 v[44:47], v[176:179], v[184:187], v[44:47]
	v_mfma_f32_16x16x32_bf16 v[36:39], v[168:171], v[192:195], v[36:39]
	v_mfma_f32_16x16x32_bf16 v[28:31], v[176:179], v[192:195], v[28:31]
	v_mfma_f32_16x16x32_bf16 v[20:23], v[168:171], v[200:203], v[20:23]
	v_mfma_f32_16x16x32_bf16 v[12:15], v[176:179], v[200:203], v[12:15]
	v_mfma_f32_16x16x32_bf16 v[4:7], v[168:171], v[208:211], v[4:7]
	v_mfma_f32_16x16x32_bf16 v[0:3], v[176:179], v[208:211], v[0:3]
	v_mfma_f32_16x16x32_bf16 v[52:55], v[172:175], v[188:191], v[52:55]
	v_mfma_f32_16x16x32_bf16 v[44:47], v[180:183], v[188:191], v[44:47]
	v_mfma_f32_16x16x32_bf16 v[36:39], v[172:175], v[196:199], v[36:39]
	v_mfma_f32_16x16x32_bf16 v[28:31], v[180:183], v[196:199], v[28:31]
	v_mfma_f32_16x16x32_bf16 v[20:23], v[172:175], v[204:207], v[20:23]
	v_mfma_f32_16x16x32_bf16 v[12:15], v[180:183], v[204:207], v[12:15]
	v_mfma_f32_16x16x32_bf16 v[4:7], v[172:175], v[212:215], v[4:7]
	v_mfma_f32_16x16x32_bf16 v[0:3], v[180:183], v[212:215], v[0:3]
	s_setprio 0
	s_barrier
	s_add_i32 s69, s69, 2
	s_add_u32 s67, s67, 0x100
	s_addc_u32 s68, s68, 0
	s_cmpk_gt_u32 s69, 0x55
	s_mov_b64 s[34:35], s[36:37]
	s_cbranch_scc0 .LBB0_222
	s_and_b64 vcc, exec, s[14:15]
	s_cbranch_vccz .LBB0_225
	s_barrier

; #define PG8_STAGE(bufoff, gbase, voff) do { _Pragma("unroll") for (int _i = 0; _i < 2; ++_i) \
;         __builtin_amdgcn_global_load_lds((const unsigned*)((const char*)(gbase) + (voff)[_i]), (LAS unsigned*)(lds + (bufoff) + ldsw + _i * 8192), 16, 0, 0); } while (0)
; #define PG8_LDA(dst, b, h) do { _Pragma("unroll") for (int m = 0; m < 4; ++m) _Pragma("unroll") for (int k = 0; k < 2; ++k) dst[m][k] = *(const LAS bf16x8*)(lds + PG8_SA(b, h) + aoff + m * 2048 + k * 1024); } while (0)
; #define PG8_LDB(dst, b, h) do { _Pragma("unroll") for (int n = 0; n < 2; ++n) _Pragma("unroll") for (int k = 0; k < 2; ++k) dst[n][k] = *(const LAS bf16x8*)(lds + PG8_SB(b, h) + boff + n * 2048 + k * 1024); } while (0)
; #define PG8_MMA(ai, bj, At, Bt) do { __builtin_amdgcn_s_setprio(1); _Pragma("unroll") for (int m = 0; m < 4; ++m) _Pragma("unroll") for (int n = 0; n < 2; ++n) _Pragma("unroll") for (int k = 0; k < 2; ++k) \
;         acc[ai][bj][m][n] = __builtin_amdgcn_mfma_f32_16x16x32_bf16(Bt[n][k], At[m][k], acc[ai][bj][m][n], 0, 0, 0); __builtin_amdgcn_s_setprio(0); } while (0)
; #define PG8_WAIT_V(n) asm volatile("s_waitcnt vmcnt(" #n ")" ::: "memory")
; #define PG8_WAIT_L(n) asm volatile("s_waitcnt lgkmcnt(" #n ")" ::: "memory")
; #define PG8_BAR __builtin_amdgcn_s_barrier()
; #define PG8_SCHED __builtin_amdgcn_sched_barrier(0)
; template <class Epi>
; __device__ __forceinline__ void gemm_phase(ldsp lds, const Gemm g, const StaticOrder& S, const Epi& E, int wave0) {
;     ...
;             const char* a1 = cA + (size_t)(t + 1) * kstep;
;             const char* a2 = last ? nA : cA + (size_t)(t + 2) * kstep; const char* b2 = last ? nB : cB + (size_t)(t + 2) * kstep;
;             const char* a3 = a2 + kstep; const char* b3 = b2 + kstep;
;             PG8_LDB(B0, 0, 0); PG8_LDB(B1, 0, 1); PG8_SCHED; PG8_LDA(At, 0, 0); PG8_STAGE(PG8_SA(1, 1), a1 + hstep, voffA);
;             PG8_WAIT_V(8); PG8_WAIT_L(0); PG8_BAR; PG8_MMA(0, 0, At, B0); PG8_MMA(0, 1, At, B1); PG8_BAR; PG8_SCHED;
;             PG8_LDA(At, 0, 1); PG8_STAGE(PG8_SB(0, 0), b2, voffB); PG8_STAGE(PG8_SB(0, 1), b2 + hstep, voffB); PG8_STAGE(PG8_SA(0, 0), a2, voffA);
;             PG8_WAIT_V(8); PG8_WAIT_L(0); PG8_BAR; PG8_MMA(1, 0, At, B0); PG8_MMA(1, 1, At, B1); PG8_BAR; PG8_SCHED;
.LBB0_332:
	ds_read_b128 v[128:131], v171
	ds_read_b128 v[132:135], v171 offset:1024
	ds_read_b128 v[136:139], v171 offset:2048
	ds_read_b128 v[140:143], v171 offset:3072
	ds_read_b128 v[160:163], v172
	ds_read_b128 v[164:167], v172 offset:1024
	ds_read_b128 v[176:179], v172 offset:2048
	ds_read_b128 v[180:183], v172 offset:3072
	s_add_u32 s48, s46, 0xfff80080
	s_addc_u32 s49, s47, -1
	s_cmp_eq_u32 s89, 28
	s_cselect_b32 s51, s37, s49
	s_cselect_b32 s50, s45, s48
	s_cselect_b32 s49, s35, s88
	s_cselect_b32 s48, s52, s53
	s_add_i32 m0, s43, 0xc000
	ds_read_b128 v[184:187], v173
	ds_read_b128 v[188:191], v173 offset:1024
	ds_read_b128 v[192:195], v173 offset:2048
	ds_read_b128 v[196:199], v173 offset:3072
	ds_read_b128 v[200:203], v173 offset:4096
	ds_read_b128 v[204:207], v173 offset:5120
	ds_read_b128 v[208:211], v173 offset:6144
	ds_read_b128 v[212:215], v173 offset:7168
	global_load_lds_dwordx4 v154, s[46:47]
	s_add_i32 m0, s43, 0xe000
	s_nop 0
	global_load_lds_dwordx4 v152, s[46:47]
	s_waitcnt vmcnt(8)
	s_waitcnt lgkmcnt(0)
	s_barrier
	s_setprio 1
	s_waitcnt lgkmcnt(0)
	v_mfma_f32_16x16x32_bf16 v[124:127], v[128:131], v[184:187], v[124:127]
	v_mfma_f32_16x16x32_bf16 v[120:123], v[136:139], v[184:187], v[120:123]
	v_mfma_f32_16x16x32_bf16 v[108:111], v[128:131], v[192:195], v[108:111]
	v_mfma_f32_16x16x32_bf16 v[104:107], v[136:139], v[192:195], v[104:107]
	v_mfma_f32_16x16x32_bf16 v[92:95], v[128:131], v[200:203], v[92:95]
	v_mfma_f32_16x16x32_bf16 v[88:91], v[136:139], v[200:203], v[88:91]
	v_mfma_f32_16x16x32_bf16 v[76:79], v[128:131], v[208:211], v[76:79]
	v_mfma_f32_16x16x32_bf16 v[72:75], v[136:139], v[208:211], v[72:75]
	v_mfma_f32_16x16x32_bf16 v[124:127], v[132:135], v[188:191], v[124:127]
	v_mfma_f32_16x16x32_bf16 v[120:123], v[140:143], v[188:191], v[120:123]
	v_mfma_f32_16x16x32_bf16 v[108:111], v[132:135], v[196:199], v[108:111]
	v_mfma_f32_16x16x32_bf16 v[104:107], v[140:143], v[196:199], v[104:107]
	v_mfma_f32_16x16x32_bf16 v[92:95], v[132:135], v[204:207], v[92:95]
	v_mfma_f32_16x16x32_bf16 v[88:91], v[140:143], v[204:207], v[88:91]
	v_mfma_f32_16x16x32_bf16 v[76:79], v[132:135], v[212:215], v[76:79]
	v_mfma_f32_16x16x32_bf16 v[72:75], v[140:143], v[212:215], v[72:75]
	s_setprio 0
	s_setprio 1
	v_mfma_f32_16x16x32_bf16 v[116:119], v[160:163], v[184:187], v[116:119]
	v_mfma_f32_16x16x32_bf16 v[112:115], v[176:179], v[184:187], v[112:115]
	v_mfma_f32_16x16x32_bf16 v[100:103], v[160:163], v[192:195], v[100:103]
	v_mfma_f32_16x16x32_bf16 v[96:99], v[176:179], v[192:195], v[96:99]
	v_mfma_f32_16x16x32_bf16 v[84:87], v[160:163], v[200:203], v[84:87]
	v_mfma_f32_16x16x32_bf16 v[80:83], v[176:179], v[200:203], v[80:83]
	v_mfma_f32_16x16x32_bf16 v[68:71], v[160:163], v[208:211], v[68:71]
	v_mfma_f32_16x16x32_bf16 v[64:67], v[176:179], v[208:211], v[64:67]
	v_mfma_f32_16x16x32_bf16 v[116:119], v[164:167], v[188:191], v[116:119]
	v_mfma_f32_16x16x32_bf16 v[112:115], v[180:183], v[188:191], v[112:115]
	v_mfma_f32_16x16x32_bf16 v[100:103], v[164:167], v[196:199], v[100:103]
	v_mfma_f32_16x16x32_bf16 v[96:99], v[180:183], v[196:199], v[96:99]
	v_mfma_f32_16x16x32_bf16 v[84:87], v[164:167], v[204:207], v[84:87]
	v_mfma_f32_16x16x32_bf16 v[80:83], v[180:183], v[204:207], v[80:83]
	v_mfma_f32_16x16x32_bf16 v[68:71], v[164:167], v[212:215], v[68:71]
	v_mfma_f32_16x16x32_bf16 v[64:67], v[180:183], v[212:215], v[64:67]
	s_setprio 0
	s_barrier
	s_add_i32 s90, s79, s62
	s_add_u32 s100, s50, 0x80
	s_addc_u32 s101, s51, 0
	s_mov_b32 m0, s90
	ds_read_b128 v[184:187], v173 offset:16384
	ds_read_b128 v[188:191], v173 offset:17408
	ds_read_b128 v[192:195], v173 offset:18432
	ds_read_b128 v[196:199], v173 offset:19456
	ds_read_b128 v[200:203], v173 offset:20480
	ds_read_b128 v[204:207], v173 offset:21504
	ds_read_b128 v[208:211], v173 offset:22528
	ds_read_b128 v[212:215], v173 offset:23552
	global_load_lds_dwordx4 v146, s[48:49]
	s_add_i32 m0, s90, 0x2000
	s_add_u32 s90, s48, 0x80000
	s_addc_u32 s91, s49, 0
	s_add_i32 s92, s80, s62
	global_load_lds_dwordx4 v150, s[48:49]
	s_mov_b32 m0, s92
	s_nop 0
	global_load_lds_dwordx4 v146, s[90:91]
	s_add_i32 m0, s92, 0x2000
	s_nop 0
	global_load_lds_dwordx4 v150, s[90:91]
	s_mov_b32 m0, s43
	s_nop 0
	global_load_lds_dwordx4 v144, s[50:51]
	s_mov_b32 m0, s63
	s_nop 0
	global_load_lds_dwordx4 v148, s[50:51]
	s_waitcnt vmcnt(8)
	s_waitcnt lgkmcnt(0)
	s_barrier
	s_setprio 1
	s_waitcnt lgkmcnt(0)
	v_mfma_f32_16x16x32_bf16 v[60:63], v[128:131], v[184:187], v[60:63]
	v_mfma_f32_16x16x32_bf16 v[56:59], v[136:139], v[184:187], v[56:59]
	v_mfma_f32_16x16x32_bf16 v[44:47], v[128:131], v[192:195], v[44:47]
	v_mfma_f32_16x16x32_bf16 v[40:43], v[136:139], v[192:195], v[40:43]
	v_mfma_f32_16x16x32_bf16 v[28:31], v[128:131], v[200:203], v[28:31]
	v_mfma_f32_16x16x32_bf16 v[24:27], v[136:139], v[200:203], v[24:27]
	v_mfma_f32_16x16x32_bf16 v[12:15], v[128:131], v[208:211], v[12:15]
	v_mfma_f32_16x16x32_bf16 v[8:11], v[136:139], v[208:211], v[8:11]
	v_mfma_f32_16x16x32_bf16 v[60:63], v[132:135], v[188:191], v[60:63]
	v_mfma_f32_16x16x32_bf16 v[56:59], v[140:143], v[188:191], v[56:59]
	v_mfma_f32_16x16x32_bf16 v[44:47], v[132:135], v[196:199], v[44:47]
	v_mfma_f32_16x16x32_bf16 v[40:43], v[140:143], v[196:199], v[40:43]
	v_mfma_f32_16x16x32_bf16 v[28:31], v[132:135], v[204:207], v[28:31]
	v_mfma_f32_16x16x32_bf16 v[24:27], v[140:143], v[204:207], v[24:27]
	v_mfma_f32_16x16x32_bf16 v[12:15], v[132:135], v[212:215], v[12:15]
	v_mfma_f32_16x16x32_bf16 v[8:11], v[140:143], v[212:215], v[8:11]
	s_setprio 0
	s_setprio 1
	v_mfma_f32_16x16x32_bf16 v[52:55], v[160:163], v[184:187], v[52:55]
	v_mfma_f32_16x16x32_bf16 v[48:51], v[176:179], v[184:187], v[48:51]
	v_mfma_f32_16x16x32_bf16 v[36:39], v[160:163], v[192:195], v[36:39]
	v_mfma_f32_16x16x32_bf16 v[32:35], v[176:179], v[192:195], v[32:35]
	v_mfma_f32_16x16x32_bf16 v[20:23], v[160:163], v[200:203], v[20:23]
	v_mfma_f32_16x16x32_bf16 v[16:19], v[176:179], v[200:203], v[16:19]
	v_mfma_f32_16x16x32_bf16 v[4:7], v[160:163], v[208:211], v[4:7]
	v_mfma_f32_16x16x32_bf16 v[0:3], v[176:179], v[208:211], v[0:3]
	v_mfma_f32_16x16x32_bf16 v[52:55], v[164:167], v[188:191], v[52:55]
	v_mfma_f32_16x16x32_bf16 v[48:51], v[180:183], v[188:191], v[48:51]
	v_mfma_f32_16x16x32_bf16 v[36:39], v[164:167], v[196:199], v[36:39]
	v_mfma_f32_16x16x32_bf16 v[32:35], v[180:183], v[196:199], v[32:35]
	v_mfma_f32_16x16x32_bf16 v[20:23], v[164:167], v[204:207], v[20:23]
	v_mfma_f32_16x16x32_bf16 v[16:19], v[180:183], v[204:207], v[16:19]
	v_mfma_f32_16x16x32_bf16 v[4:7], v[164:167], v[212:215], v[4:7]
	v_mfma_f32_16x16x32_bf16 v[0:3], v[180:183], v[212:215], v[0:3]
	s_setprio 0
	s_barrier
; #define PG8_STAGE(bufoff, gbase, voff) do { _Pragma("unroll") for (int _i = 0; _i < 2; ++_i) \
;         __builtin_amdgcn_global_load_lds((const unsigned*)((const char*)(gbase) + (voff)[_i]), (LAS unsigned*)(lds + (bufoff) + ldsw + _i * 8192), 16, 0, 0); } while (0)
; #define PG8_LDA(dst, b, h) do { _Pragma("unroll") for (int m = 0; m < 4; ++m) _Pragma("unroll") for (int k = 0; k < 2; ++k) dst[m][k] = *(const LAS bf16x8*)(lds + PG8_SA(b, h) + aoff + m * 2048 + k * 1024); } while (0)
; #define PG8_LDB(dst, b, h) do { _Pragma("unroll") for (int n = 0; n < 2; ++n) _Pragma("unroll") for (int k = 0; k < 2; ++k) dst[n][k] = *(const LAS bf16x8*)(lds + PG8_SB(b, h) + boff + n * 2048 + k * 1024); } while (0)
; #define PG8_MMA(ai, bj, At, Bt) do { __builtin_amdgcn_s_setprio(1); _Pragma("unroll") for (int m = 0; m < 4; ++m) _Pragma("unroll") for (int n = 0; n < 2; ++n) _Pragma("unroll") for (int k = 0; k < 2; ++k) \
;         acc[ai][bj][m][n] = __builtin_amdgcn_mfma_f32_16x16x32_bf16(Bt[n][k], At[m][k], acc[ai][bj][m][n], 0, 0, 0); __builtin_amdgcn_s_setprio(0); } while (0)
; #define PG8_WAIT_V(n) asm volatile("s_waitcnt vmcnt(" #n ")" ::: "memory")
; #define PG8_WAIT_L(n) asm volatile("s_waitcnt lgkmcnt(" #n ")" ::: "memory")
; #define PG8_BAR __builtin_amdgcn_s_barrier()
; #define PG8_SCHED __builtin_amdgcn_sched_barrier(0)
; template <class Epi>
; __device__ __forceinline__ void gemm_phase(ldsp lds, const Gemm g, const StaticOrder& S, const Epi& E, int wave0) {
;     ...
;             PG8_LDB(B0, 1, 0); PG8_LDB(B1, 1, 1); PG8_SCHED; PG8_LDA(At, 1, 0); PG8_STAGE(PG8_SA(0, 1), a2 + hstep, voffA);
;             PG8_WAIT_V(8); PG8_WAIT_L(0); PG8_BAR; PG8_MMA(0, 0, At, B0); PG8_MMA(0, 1, At, B1); PG8_BAR; PG8_SCHED;
;             PG8_LDA(At, 1, 1); PG8_STAGE(PG8_SB(1, 0), b3, voffB); PG8_STAGE(PG8_SB(1, 1), b3 + hstep, voffB); PG8_STAGE(PG8_SA(1, 0), a3, voffA);
;             PG8_WAIT_V(8); PG8_WAIT_L(0); PG8_BAR; PG8_MMA(1, 0, At, B0); PG8_MMA(1, 1, At, B1); PG8_BAR; PG8_SCHED;
;         }
;         if (wr == 0) PG8_BAR;
	s_add_i32 s90, 0, 0x18000
	s_add_i32 s91, 0, 0x1c000
	v_add_u32_e32 v140, s90, v170
	v_add_u32_e32 v175, s91, v170
	ds_read_b128 v[128:131], v140
	ds_read_b128 v[132:135], v140 offset:1024
	ds_read_b128 v[136:139], v140 offset:2048
	ds_read_b128 v[140:143], v140 offset:3072
	ds_read_b128 v[160:163], v175
	ds_read_b128 v[164:167], v175 offset:1024
	ds_read_b128 v[176:179], v175 offset:2048
	ds_read_b128 v[180:183], v175 offset:3072
	s_add_u32 s50, s50, 0x80000
	s_addc_u32 s51, s51, 0
	s_mov_b32 m0, s64
	ds_read_b128 v[184:187], v173 offset:32768
	ds_read_b128 v[188:191], v173 offset:33792
	ds_read_b128 v[192:195], v173 offset:34816
	ds_read_b128 v[196:199], v173 offset:35840
	ds_read_b128 v[200:203], v173 offset:36864
	ds_read_b128 v[204:207], v173 offset:37888
	ds_read_b128 v[208:211], v173 offset:38912
	ds_read_b128 v[212:215], v173 offset:39936
	global_load_lds_dwordx4 v144, s[50:51]
	s_mov_b32 m0, s65
	s_nop 0
	global_load_lds_dwordx4 v148, s[50:51]
	s_waitcnt vmcnt(8)
	s_waitcnt lgkmcnt(0)
	s_barrier
	s_setprio 1
	s_waitcnt lgkmcnt(0)
	v_mfma_f32_16x16x32_bf16 v[124:127], v[128:131], v[184:187], v[124:127]
	v_mfma_f32_16x16x32_bf16 v[120:123], v[136:139], v[184:187], v[120:123]
	v_mfma_f32_16x16x32_bf16 v[108:111], v[128:131], v[192:195], v[108:111]
	v_mfma_f32_16x16x32_bf16 v[104:107], v[136:139], v[192:195], v[104:107]
	v_mfma_f32_16x16x32_bf16 v[92:95], v[128:131], v[200:203], v[92:95]
	v_mfma_f32_16x16x32_bf16 v[88:91], v[136:139], v[200:203], v[88:91]
	v_mfma_f32_16x16x32_bf16 v[76:79], v[128:131], v[208:211], v[76:79]
	v_mfma_f32_16x16x32_bf16 v[72:75], v[136:139], v[208:211], v[72:75]
	v_mfma_f32_16x16x32_bf16 v[124:127], v[132:135], v[188:191], v[124:127]
	v_mfma_f32_16x16x32_bf16 v[120:123], v[140:143], v[188:191], v[120:123]
	v_mfma_f32_16x16x32_bf16 v[108:111], v[132:135], v[196:199], v[108:111]
	v_mfma_f32_16x16x32_bf16 v[104:107], v[140:143], v[196:199], v[104:107]
	v_mfma_f32_16x16x32_bf16 v[92:95], v[132:135], v[204:207], v[92:95]
	v_mfma_f32_16x16x32_bf16 v[88:91], v[140:143], v[204:207], v[88:91]
	v_mfma_f32_16x16x32_bf16 v[76:79], v[132:135], v[212:215], v[76:79]
	v_mfma_f32_16x16x32_bf16 v[72:75], v[140:143], v[212:215], v[72:75]
	s_setprio 0
	s_setprio 1
	v_mfma_f32_16x16x32_bf16 v[116:119], v[160:163], v[184:187], v[116:119]
	v_mfma_f32_16x16x32_bf16 v[112:115], v[176:179], v[184:187], v[112:115]
	v_mfma_f32_16x16x32_bf16 v[100:103], v[160:163], v[192:195], v[100:103]
	v_mfma_f32_16x16x32_bf16 v[96:99], v[176:179], v[192:195], v[96:99]
	v_mfma_f32_16x16x32_bf16 v[84:87], v[160:163], v[200:203], v[84:87]
	v_mfma_f32_16x16x32_bf16 v[80:83], v[176:179], v[200:203], v[80:83]
	v_mfma_f32_16x16x32_bf16 v[68:71], v[160:163], v[208:211], v[68:71]
	v_mfma_f32_16x16x32_bf16 v[64:67], v[176:179], v[208:211], v[64:67]
	v_mfma_f32_16x16x32_bf16 v[116:119], v[164:167], v[188:191], v[116:119]
	v_mfma_f32_16x16x32_bf16 v[112:115], v[180:183], v[188:191], v[112:115]
	v_mfma_f32_16x16x32_bf16 v[100:103], v[164:167], v[196:199], v[100:103]
	v_mfma_f32_16x16x32_bf16 v[96:99], v[180:183], v[196:199], v[96:99]
	v_mfma_f32_16x16x32_bf16 v[84:87], v[164:167], v[204:207], v[84:87]
	v_mfma_f32_16x16x32_bf16 v[80:83], v[180:183], v[204:207], v[80:83]
	v_mfma_f32_16x16x32_bf16 v[68:71], v[164:167], v[212:215], v[68:71]
	v_mfma_f32_16x16x32_bf16 v[64:67], v[180:183], v[212:215], v[64:67]
	s_setprio 0
	s_barrier
	s_add_i32 s50, s90, s62
	s_add_u32 s48, s48, 0x80
	s_addc_u32 s49, s49, 0
	s_mov_b32 m0, s50
	ds_read_b128 v[184:187], v173 offset:49152
	ds_read_b128 v[188:191], v173 offset:50176
	ds_read_b128 v[192:195], v173 offset:51200
	ds_read_b128 v[196:199], v173 offset:52224
	ds_read_b128 v[200:203], v173 offset:53248
	ds_read_b128 v[204:207], v173 offset:54272
	ds_read_b128 v[208:211], v173 offset:55296
	ds_read_b128 v[212:215], v173 offset:56320
	global_load_lds_dwordx4 v146, s[48:49]
	s_add_i32 m0, s50, 0x2000
	s_add_i32 s50, s91, s62
	global_load_lds_dwordx4 v150, s[48:49]
	s_add_u32 s48, s48, 0x80000
	s_addc_u32 s49, s49, 0
	s_mov_b32 m0, s50
	s_nop 0
	global_load_lds_dwordx4 v146, s[48:49]
	s_add_i32 m0, s50, 0x2000
	s_nop 0
	global_load_lds_dwordx4 v150, s[48:49]
	s_mov_b32 m0, s70
	s_nop 0
	global_load_lds_dwordx4 v144, s[100:101]
	s_mov_b32 m0, s71
	s_nop 0
	global_load_lds_dwordx4 v148, s[100:101]
	s_waitcnt vmcnt(8)
	s_waitcnt lgkmcnt(0)
	s_barrier
	s_setprio 1
	s_waitcnt lgkmcnt(0)
	v_mfma_f32_16x16x32_bf16 v[60:63], v[128:131], v[184:187], v[60:63]
	v_mfma_f32_16x16x32_bf16 v[56:59], v[136:139], v[184:187], v[56:59]
	v_mfma_f32_16x16x32_bf16 v[44:47], v[128:131], v[192:195], v[44:47]
	v_mfma_f32_16x16x32_bf16 v[40:43], v[136:139], v[192:195], v[40:43]
	v_mfma_f32_16x16x32_bf16 v[28:31], v[128:131], v[200:203], v[28:31]
	v_mfma_f32_16x16x32_bf16 v[24:27], v[136:139], v[200:203], v[24:27]
	v_mfma_f32_16x16x32_bf16 v[12:15], v[128:131], v[208:211], v[12:15]
	v_mfma_f32_16x16x32_bf16 v[8:11], v[136:139], v[208:211], v[8:11]
	v_mfma_f32_16x16x32_bf16 v[60:63], v[132:135], v[188:191], v[60:63]
	v_mfma_f32_16x16x32_bf16 v[56:59], v[140:143], v[188:191], v[56:59]
	v_mfma_f32_16x16x32_bf16 v[44:47], v[132:135], v[196:199], v[44:47]
	v_mfma_f32_16x16x32_bf16 v[40:43], v[140:143], v[196:199], v[40:43]
	v_mfma_f32_16x16x32_bf16 v[28:31], v[132:135], v[204:207], v[28:31]
	v_mfma_f32_16x16x32_bf16 v[24:27], v[140:143], v[204:207], v[24:27]
	v_mfma_f32_16x16x32_bf16 v[12:15], v[132:135], v[212:215], v[12:15]
	v_mfma_f32_16x16x32_bf16 v[8:11], v[140:143], v[212:215], v[8:11]
	s_setprio 0
	s_setprio 1
	v_mfma_f32_16x16x32_bf16 v[52:55], v[160:163], v[184:187], v[52:55]
	v_mfma_f32_16x16x32_bf16 v[48:51], v[176:179], v[184:187], v[48:51]
	v_mfma_f32_16x16x32_bf16 v[36:39], v[160:163], v[192:195], v[36:39]
	v_mfma_f32_16x16x32_bf16 v[32:35], v[176:179], v[192:195], v[32:35]
	v_mfma_f32_16x16x32_bf16 v[20:23], v[160:163], v[200:203], v[20:23]
	v_mfma_f32_16x16x32_bf16 v[16:19], v[176:179], v[200:203], v[16:19]
	v_mfma_f32_16x16x32_bf16 v[4:7], v[160:163], v[208:211], v[4:7]
	v_mfma_f32_16x16x32_bf16 v[0:3], v[176:179], v[208:211], v[0:3]
	v_mfma_f32_16x16x32_bf16 v[52:55], v[164:167], v[188:191], v[52:55]
	v_mfma_f32_16x16x32_bf16 v[48:51], v[180:183], v[188:191], v[48:51]
	v_mfma_f32_16x16x32_bf16 v[36:39], v[164:167], v[196:199], v[36:39]
	v_mfma_f32_16x16x32_bf16 v[32:35], v[180:183], v[196:199], v[32:35]
	v_mfma_f32_16x16x32_bf16 v[20:23], v[164:167], v[204:207], v[20:23]
	v_mfma_f32_16x16x32_bf16 v[16:19], v[180:183], v[204:207], v[16:19]
	v_mfma_f32_16x16x32_bf16 v[4:7], v[164:167], v[212:215], v[4:7]
	v_mfma_f32_16x16x32_bf16 v[0:3], v[180:183], v[212:215], v[0:3]
	s_setprio 0
	s_barrier
	s_add_i32 s89, s89, 2
	s_add_u32 s53, s53, 0x100
	s_addc_u32 s88, s88, 0
	s_add_u32 s46, s46, 0x100
	s_addc_u32 s47, s47, 0
	s_cmp_gt_u32 s89, 29
	s_cbranch_scc0 .LBB0_332
	s_and_b64 vcc, exec, s[18:19]
	s_cbranch_vccz .LBB0_335
	s_barrier

; #define PG8_STAGE(bufoff, gbase, voff) do { _Pragma("unroll") for (int _i = 0; _i < 2; ++_i) \
;         __builtin_amdgcn_global_load_lds((const unsigned*)((const char*)(gbase) + (voff)[_i]), (LAS unsigned*)(lds + (bufoff) + ldsw + _i * 8192), 16, 0, 0); } while (0)
; #define PG8_LDA(dst, b, h) do { _Pragma("unroll") for (int m = 0; m < 4; ++m) _Pragma("unroll") for (int k = 0; k < 2; ++k) dst[m][k] = *(const LAS bf16x8*)(lds + PG8_SA(b, h) + aoff + m * 2048 + k * 1024); } while (0)
; #define PG8_LDB(dst, b, h) do { _Pragma("unroll") for (int n = 0; n < 2; ++n) _Pragma("unroll") for (int k = 0; k < 2; ++k) dst[n][k] = *(const LAS bf16x8*)(lds + PG8_SB(b, h) + boff + n * 2048 + k * 1024); } while (0)
; #define PG8_MMA(ai, bj, At, Bt) do { __builtin_amdgcn_s_setprio(1); _Pragma("unroll") for (int m = 0; m < 4; ++m) _Pragma("unroll") for (int n = 0; n < 2; ++n) _Pragma("unroll") for (int k = 0; k < 2; ++k) \
;         acc[ai][bj][m][n] = __builtin_amdgcn_mfma_f32_16x16x32_bf16(Bt[n][k], At[m][k], acc[ai][bj][m][n], 0, 0, 0); __builtin_amdgcn_s_setprio(0); } while (0)
; #define PG8_WAIT_V(n) asm volatile("s_waitcnt vmcnt(" #n ")" ::: "memory")
; #define PG8_WAIT_L(n) asm volatile("s_waitcnt lgkmcnt(" #n ")" ::: "memory")
; #define PG8_BAR __builtin_amdgcn_s_barrier()
; #define PG8_SCHED __builtin_amdgcn_sched_barrier(0)
; template <class Epi>
; __device__ __forceinline__ void gemm_phase(ldsp lds, const Gemm g, const StaticOrder& S, const Epi& E, int wave0) {
;     ...
;             const char* a1 = cA + (size_t)(t + 1) * kstep;
;             const char* a2 = last ? nA : cA + (size_t)(t + 2) * kstep; const char* b2 = last ? nB : cB + (size_t)(t + 2) * kstep;
;             const char* a3 = a2 + kstep; const char* b3 = b2 + kstep;
;             PG8_LDB(B0, 0, 0); PG8_LDB(B1, 0, 1); PG8_SCHED; PG8_LDA(At, 0, 0); PG8_STAGE(PG8_SA(1, 1), a1 + hstep, voffA);
;             PG8_WAIT_V(8); PG8_WAIT_L(0); PG8_BAR; PG8_MMA(0, 0, At, B0); PG8_MMA(0, 1, At, B1); PG8_BAR; PG8_SCHED;
;             PG8_LDA(At, 0, 1); PG8_STAGE(PG8_SB(0, 0), b2, voffB); PG8_STAGE(PG8_SB(0, 1), b2 + hstep, voffB); PG8_STAGE(PG8_SA(0, 0), a2, voffA);
;             PG8_WAIT_V(8); PG8_WAIT_L(0); PG8_BAR; PG8_MMA(1, 0, At, B0); PG8_MMA(1, 1, At, B1); PG8_BAR; PG8_SCHED;
.LBB0_375:
	ds_read_b128 v[144:147], v151
	ds_read_b128 v[154:157], v151 offset:1024
	ds_read_b128 v[158:161], v151 offset:2048
	ds_read_b128 v[162:165], v151 offset:3072
	ds_read_b128 v[166:169], v152
	ds_read_b128 v[170:173], v152 offset:1024
	ds_read_b128 v[174:177], v152 offset:2048
	ds_read_b128 v[178:181], v152 offset:3072
	s_add_u32 s20, s18, 0xfff80080
	s_addc_u32 s21, s19, -1
	s_cmp_eq_u32 s56, 28
	s_cselect_b32 s23, s11, s21
	s_cselect_b32 s22, s17, s20
	s_cselect_b32 s21, s9, s55
	s_cselect_b32 s20, s53, s54
	s_add_i32 m0, s36, 0xc000
	ds_read_b128 v[182:185], v153
	ds_read_b128 v[186:189], v153 offset:1024
	ds_read_b128 v[190:193], v153 offset:2048
	ds_read_b128 v[194:197], v153 offset:3072
	ds_read_b128 v[198:201], v153 offset:4096
	ds_read_b128 v[202:205], v153 offset:5120
	ds_read_b128 v[206:209], v153 offset:6144
	ds_read_b128 v[210:213], v153 offset:7168
	global_load_lds_dwordx4 v138, s[18:19]
	s_add_i32 m0, s36, 0xe000
	s_nop 0
	global_load_lds_dwordx4 v136, s[18:19]
	s_waitcnt vmcnt(8)
	s_waitcnt lgkmcnt(0)
	s_barrier
	s_setprio 1
	s_waitcnt lgkmcnt(0)
	v_mfma_f32_16x16x32_bf16 v[124:127], v[144:147], v[182:185], v[124:127]
	v_mfma_f32_16x16x32_bf16 v[120:123], v[158:161], v[182:185], v[120:123]
	v_mfma_f32_16x16x32_bf16 v[112:115], v[144:147], v[190:193], v[112:115]
	v_mfma_f32_16x16x32_bf16 v[104:107], v[158:161], v[190:193], v[104:107]
	v_mfma_f32_16x16x32_bf16 v[100:103], v[144:147], v[198:201], v[100:103]
	v_mfma_f32_16x16x32_bf16 v[92:95], v[158:161], v[198:201], v[92:95]
	v_mfma_f32_16x16x32_bf16 v[84:87], v[144:147], v[206:209], v[84:87]
	v_mfma_f32_16x16x32_bf16 v[76:79], v[158:161], v[206:209], v[76:79]
	v_mfma_f32_16x16x32_bf16 v[124:127], v[154:157], v[186:189], v[124:127]
	v_mfma_f32_16x16x32_bf16 v[120:123], v[162:165], v[186:189], v[120:123]
	v_mfma_f32_16x16x32_bf16 v[112:115], v[154:157], v[194:197], v[112:115]
	v_mfma_f32_16x16x32_bf16 v[104:107], v[162:165], v[194:197], v[104:107]
	v_mfma_f32_16x16x32_bf16 v[100:103], v[154:157], v[202:205], v[100:103]
	v_mfma_f32_16x16x32_bf16 v[92:95], v[162:165], v[202:205], v[92:95]
	v_mfma_f32_16x16x32_bf16 v[84:87], v[154:157], v[210:213], v[84:87]
	v_mfma_f32_16x16x32_bf16 v[76:79], v[162:165], v[210:213], v[76:79]
	s_setprio 0
	s_setprio 1
	v_mfma_f32_16x16x32_bf16 v[116:119], v[166:169], v[182:185], v[116:119]
	v_mfma_f32_16x16x32_bf16 v[108:111], v[174:177], v[182:185], v[108:111]
	v_mfma_f32_16x16x32_bf16 v[96:99], v[166:169], v[190:193], v[96:99]
	v_mfma_f32_16x16x32_bf16 v[88:91], v[174:177], v[190:193], v[88:91]
	v_mfma_f32_16x16x32_bf16 v[80:83], v[166:169], v[198:201], v[80:83]
	v_mfma_f32_16x16x32_bf16 v[72:75], v[174:177], v[198:201], v[72:75]
	v_mfma_f32_16x16x32_bf16 v[68:71], v[166:169], v[206:209], v[68:71]
	v_mfma_f32_16x16x32_bf16 v[64:67], v[174:177], v[206:209], v[64:67]
	v_mfma_f32_16x16x32_bf16 v[116:119], v[170:173], v[186:189], v[116:119]
	v_mfma_f32_16x16x32_bf16 v[108:111], v[178:181], v[186:189], v[108:111]
	v_mfma_f32_16x16x32_bf16 v[96:99], v[170:173], v[194:197], v[96:99]
	v_mfma_f32_16x16x32_bf16 v[88:91], v[178:181], v[194:197], v[88:91]
	v_mfma_f32_16x16x32_bf16 v[80:83], v[170:173], v[202:205], v[80:83]
	v_mfma_f32_16x16x32_bf16 v[72:75], v[178:181], v[202:205], v[72:75]
	v_mfma_f32_16x16x32_bf16 v[68:71], v[170:173], v[210:213], v[68:71]
	v_mfma_f32_16x16x32_bf16 v[64:67], v[178:181], v[210:213], v[64:67]
	s_setprio 0
	s_barrier
	s_add_i32 s57, s50, s31
	s_add_u32 s100, s22, 0x80
	s_addc_u32 s101, s23, 0
	s_mov_b32 m0, s57
	ds_read_b128 v[182:185], v153 offset:16384
	ds_read_b128 v[186:189], v153 offset:17408
	ds_read_b128 v[190:193], v153 offset:18432
	ds_read_b128 v[194:197], v153 offset:19456
	ds_read_b128 v[198:201], v153 offset:20480
	ds_read_b128 v[202:205], v153 offset:21504
	ds_read_b128 v[206:209], v153 offset:22528
	ds_read_b128 v[210:213], v153 offset:23552
	global_load_lds_dwordx4 v132, s[20:21]
	s_add_i32 m0, s57, 0x2000
	s_add_u32 s60, s20, 0x80000
	s_addc_u32 s61, s21, 0
	s_add_i32 s57, s51, s31
	global_load_lds_dwordx4 v128, s[20:21]
	s_mov_b32 m0, s57
	s_nop 0
	global_load_lds_dwordx4 v132, s[60:61]
	s_add_i32 m0, s57, 0x2000
	s_nop 0
	global_load_lds_dwordx4 v128, s[60:61]
	s_mov_b32 m0, s36
	s_nop 0
	global_load_lds_dwordx4 v134, s[22:23]
	s_mov_b32 m0, s37
	s_nop 0
	global_load_lds_dwordx4 v130, s[22:23]
	s_waitcnt vmcnt(8)
	s_waitcnt lgkmcnt(0)
	s_barrier
	s_setprio 1
	s_waitcnt lgkmcnt(0)
	v_mfma_f32_16x16x32_bf16 v[60:63], v[144:147], v[182:185], v[60:63]
	v_mfma_f32_16x16x32_bf16 v[56:59], v[158:161], v[182:185], v[56:59]
	v_mfma_f32_16x16x32_bf16 v[52:55], v[144:147], v[190:193], v[52:55]
	v_mfma_f32_16x16x32_bf16 v[44:47], v[158:161], v[190:193], v[44:47]
	v_mfma_f32_16x16x32_bf16 v[36:39], v[144:147], v[198:201], v[36:39]
	v_mfma_f32_16x16x32_bf16 v[28:31], v[158:161], v[198:201], v[28:31]
	v_mfma_f32_16x16x32_bf16 v[20:23], v[144:147], v[206:209], v[20:23]
	v_mfma_f32_16x16x32_bf16 v[12:15], v[158:161], v[206:209], v[12:15]
	v_mfma_f32_16x16x32_bf16 v[60:63], v[154:157], v[186:189], v[60:63]
	v_mfma_f32_16x16x32_bf16 v[56:59], v[162:165], v[186:189], v[56:59]
	v_mfma_f32_16x16x32_bf16 v[52:55], v[154:157], v[194:197], v[52:55]
	v_mfma_f32_16x16x32_bf16 v[44:47], v[162:165], v[194:197], v[44:47]
	v_mfma_f32_16x16x32_bf16 v[36:39], v[154:157], v[202:205], v[36:39]
	v_mfma_f32_16x16x32_bf16 v[28:31], v[162:165], v[202:205], v[28:31]
	v_mfma_f32_16x16x32_bf16 v[20:23], v[154:157], v[210:213], v[20:23]
	v_mfma_f32_16x16x32_bf16 v[12:15], v[162:165], v[210:213], v[12:15]
	s_setprio 0
	s_setprio 1
	v_mfma_f32_16x16x32_bf16 v[48:51], v[166:169], v[182:185], v[48:51]
	v_mfma_f32_16x16x32_bf16 v[40:43], v[174:177], v[182:185], v[40:43]
	v_mfma_f32_16x16x32_bf16 v[32:35], v[166:169], v[190:193], v[32:35]
	v_mfma_f32_16x16x32_bf16 v[24:27], v[174:177], v[190:193], v[24:27]
	v_mfma_f32_16x16x32_bf16 v[16:19], v[166:169], v[198:201], v[16:19]
	v_mfma_f32_16x16x32_bf16 v[8:11], v[174:177], v[198:201], v[8:11]
	v_mfma_f32_16x16x32_bf16 v[4:7], v[166:169], v[206:209], v[4:7]
	v_mfma_f32_16x16x32_bf16 v[0:3], v[174:177], v[206:209], v[0:3]
	v_mfma_f32_16x16x32_bf16 v[48:51], v[170:173], v[186:189], v[48:51]
	v_mfma_f32_16x16x32_bf16 v[40:43], v[178:181], v[186:189], v[40:43]
	v_mfma_f32_16x16x32_bf16 v[32:35], v[170:173], v[194:197], v[32:35]
	v_mfma_f32_16x16x32_bf16 v[24:27], v[178:181], v[194:197], v[24:27]
	v_mfma_f32_16x16x32_bf16 v[16:19], v[170:173], v[202:205], v[16:19]
	v_mfma_f32_16x16x32_bf16 v[8:11], v[178:181], v[202:205], v[8:11]
	v_mfma_f32_16x16x32_bf16 v[4:7], v[170:173], v[210:213], v[4:7]
	v_mfma_f32_16x16x32_bf16 v[0:3], v[178:181], v[210:213], v[0:3]
	s_setprio 0
	s_barrier
; #define PG8_STAGE(bufoff, gbase, voff) do { _Pragma("unroll") for (int _i = 0; _i < 2; ++_i) \
;         __builtin_amdgcn_global_load_lds((const unsigned*)((const char*)(gbase) + (voff)[_i]), (LAS unsigned*)(lds + (bufoff) + ldsw + _i * 8192), 16, 0, 0); } while (0)
; #define PG8_LDA(dst, b, h) do { _Pragma("unroll") for (int m = 0; m < 4; ++m) _Pragma("unroll") for (int k = 0; k < 2; ++k) dst[m][k] = *(const LAS bf16x8*)(lds + PG8_SA(b, h) + aoff + m * 2048 + k * 1024); } while (0)
; #define PG8_LDB(dst, b, h) do { _Pragma("unroll") for (int n = 0; n < 2; ++n) _Pragma("unroll") for (int k = 0; k < 2; ++k) dst[n][k] = *(const LAS bf16x8*)(lds + PG8_SB(b, h) + boff + n * 2048 + k * 1024); } while (0)
; #define PG8_MMA(ai, bj, At, Bt) do { __builtin_amdgcn_s_setprio(1); _Pragma("unroll") for (int m = 0; m < 4; ++m) _Pragma("unroll") for (int n = 0; n < 2; ++n) _Pragma("unroll") for (int k = 0; k < 2; ++k) \
;         acc[ai][bj][m][n] = __builtin_amdgcn_mfma_f32_16x16x32_bf16(Bt[n][k], At[m][k], acc[ai][bj][m][n], 0, 0, 0); __builtin_amdgcn_s_setprio(0); } while (0)
; #define PG8_WAIT_V(n) asm volatile("s_waitcnt vmcnt(" #n ")" ::: "memory")
; #define PG8_WAIT_L(n) asm volatile("s_waitcnt lgkmcnt(" #n ")" ::: "memory")
; #define PG8_BAR __builtin_amdgcn_s_barrier()
; #define PG8_SCHED __builtin_amdgcn_sched_barrier(0)
; template <class Epi>
; __device__ __forceinline__ void gemm_phase(ldsp lds, const Gemm g, const StaticOrder& S, const Epi& E, int wave0) {
;     ...
;             PG8_LDB(B0, 1, 0); PG8_LDB(B1, 1, 1); PG8_SCHED; PG8_LDA(At, 1, 0); PG8_STAGE(PG8_SA(0, 1), a2 + hstep, voffA);
;             PG8_WAIT_V(8); PG8_WAIT_L(0); PG8_BAR; PG8_MMA(0, 0, At, B0); PG8_MMA(0, 1, At, B1); PG8_BAR; PG8_SCHED;
;             PG8_LDA(At, 1, 1); PG8_STAGE(PG8_SB(1, 0), b3, voffB); PG8_STAGE(PG8_SB(1, 1), b3 + hstep, voffB); PG8_STAGE(PG8_SA(1, 0), a3, voffA);
;             PG8_WAIT_V(8); PG8_WAIT_L(0); PG8_BAR; PG8_MMA(1, 0, At, B0); PG8_MMA(1, 1, At, B1); PG8_BAR; PG8_SCHED;
;         }
;         if (wr == 0) PG8_BAR;
	s_add_i32 s57, 0, 0x18000
	s_add_i32 s60, 0, 0x1c000
	v_add_u32_e32 v162, s57, v150
	v_add_u32_e32 v178, s60, v150
	ds_read_b128 v[144:147], v162
	ds_read_b128 v[154:157], v162 offset:1024
	ds_read_b128 v[158:161], v162 offset:2048
	ds_read_b128 v[162:165], v162 offset:3072
	ds_read_b128 v[166:169], v178
	ds_read_b128 v[170:173], v178 offset:1024
	ds_read_b128 v[174:177], v178 offset:2048
	ds_read_b128 v[178:181], v178 offset:3072
	s_add_u32 s22, s22, 0x80000
	s_addc_u32 s23, s23, 0
	s_mov_b32 m0, s38
	ds_read_b128 v[182:185], v153 offset:32768
	ds_read_b128 v[186:189], v153 offset:33792
	ds_read_b128 v[190:193], v153 offset:34816
	ds_read_b128 v[194:197], v153 offset:35840
	ds_read_b128 v[198:201], v153 offset:36864
	ds_read_b128 v[202:205], v153 offset:37888
	ds_read_b128 v[206:209], v153 offset:38912
	ds_read_b128 v[210:213], v153 offset:39936
	global_load_lds_dwordx4 v134, s[22:23]
	s_mov_b32 m0, s39
	s_nop 0
	global_load_lds_dwordx4 v130, s[22:23]
	s_waitcnt vmcnt(8)
	s_waitcnt lgkmcnt(0)
	s_barrier
	s_setprio 1
	s_waitcnt lgkmcnt(0)
	v_mfma_f32_16x16x32_bf16 v[124:127], v[144:147], v[182:185], v[124:127]
	v_mfma_f32_16x16x32_bf16 v[120:123], v[158:161], v[182:185], v[120:123]
	v_mfma_f32_16x16x32_bf16 v[112:115], v[144:147], v[190:193], v[112:115]
	v_mfma_f32_16x16x32_bf16 v[104:107], v[158:161], v[190:193], v[104:107]
	v_mfma_f32_16x16x32_bf16 v[100:103], v[144:147], v[198:201], v[100:103]
	v_mfma_f32_16x16x32_bf16 v[92:95], v[158:161], v[198:201], v[92:95]
	v_mfma_f32_16x16x32_bf16 v[84:87], v[144:147], v[206:209], v[84:87]
	v_mfma_f32_16x16x32_bf16 v[76:79], v[158:161], v[206:209], v[76:79]
	v_mfma_f32_16x16x32_bf16 v[124:127], v[154:157], v[186:189], v[124:127]
	v_mfma_f32_16x16x32_bf16 v[120:123], v[162:165], v[186:189], v[120:123]
	v_mfma_f32_16x16x32_bf16 v[112:115], v[154:157], v[194:197], v[112:115]
	v_mfma_f32_16x16x32_bf16 v[104:107], v[162:165], v[194:197], v[104:107]
	v_mfma_f32_16x16x32_bf16 v[100:103], v[154:157], v[202:205], v[100:103]
	v_mfma_f32_16x16x32_bf16 v[92:95], v[162:165], v[202:205], v[92:95]
	v_mfma_f32_16x16x32_bf16 v[84:87], v[154:157], v[210:213], v[84:87]
	v_mfma_f32_16x16x32_bf16 v[76:79], v[162:165], v[210:213], v[76:79]
	s_setprio 0
	s_setprio 1
	v_mfma_f32_16x16x32_bf16 v[116:119], v[166:169], v[182:185], v[116:119]
	v_mfma_f32_16x16x32_bf16 v[108:111], v[174:177], v[182:185], v[108:111]
	v_mfma_f32_16x16x32_bf16 v[96:99], v[166:169], v[190:193], v[96:99]
	v_mfma_f32_16x16x32_bf16 v[88:91], v[174:177], v[190:193], v[88:91]
	v_mfma_f32_16x16x32_bf16 v[80:83], v[166:169], v[198:201], v[80:83]
	v_mfma_f32_16x16x32_bf16 v[72:75], v[174:177], v[198:201], v[72:75]
	v_mfma_f32_16x16x32_bf16 v[68:71], v[166:169], v[206:209], v[68:71]
	v_mfma_f32_16x16x32_bf16 v[64:67], v[174:177], v[206:209], v[64:67]
	v_mfma_f32_16x16x32_bf16 v[116:119], v[170:173], v[186:189], v[116:119]
	v_mfma_f32_16x16x32_bf16 v[108:111], v[178:181], v[186:189], v[108:111]
	v_mfma_f32_16x16x32_bf16 v[96:99], v[170:173], v[194:197], v[96:99]
	v_mfma_f32_16x16x32_bf16 v[88:91], v[178:181], v[194:197], v[88:91]
	v_mfma_f32_16x16x32_bf16 v[80:83], v[170:173], v[202:205], v[80:83]
	v_mfma_f32_16x16x32_bf16 v[72:75], v[178:181], v[202:205], v[72:75]
	v_mfma_f32_16x16x32_bf16 v[68:71], v[170:173], v[210:213], v[68:71]
	v_mfma_f32_16x16x32_bf16 v[64:67], v[178:181], v[210:213], v[64:67]
	s_setprio 0
	s_barrier
	s_add_i32 s22, s57, s31
	s_add_u32 s20, s20, 0x80
	s_addc_u32 s21, s21, 0
	s_mov_b32 m0, s22
	ds_read_b128 v[182:185], v153 offset:49152
	ds_read_b128 v[186:189], v153 offset:50176
	ds_read_b128 v[190:193], v153 offset:51200
	ds_read_b128 v[194:197], v153 offset:52224
	ds_read_b128 v[198:201], v153 offset:53248
	ds_read_b128 v[202:205], v153 offset:54272
	ds_read_b128 v[206:209], v153 offset:55296
	ds_read_b128 v[210:213], v153 offset:56320
	global_load_lds_dwordx4 v132, s[20:21]
	s_add_i32 m0, s22, 0x2000
	s_add_i32 s22, s60, s31
	global_load_lds_dwordx4 v128, s[20:21]
	s_add_u32 s20, s20, 0x80000
	s_addc_u32 s21, s21, 0
	s_mov_b32 m0, s22
	s_nop 0
	global_load_lds_dwordx4 v132, s[20:21]
	s_add_i32 m0, s22, 0x2000
	s_nop 0
	global_load_lds_dwordx4 v128, s[20:21]
	s_mov_b32 m0, s46
	s_nop 0
	global_load_lds_dwordx4 v134, s[100:101]
	s_mov_b32 m0, s47
	s_nop 0
	global_load_lds_dwordx4 v130, s[100:101]
	s_waitcnt vmcnt(8)
	s_waitcnt lgkmcnt(0)
	s_barrier
	s_setprio 1
	s_waitcnt lgkmcnt(0)
	v_mfma_f32_16x16x32_bf16 v[60:63], v[144:147], v[182:185], v[60:63]
	v_mfma_f32_16x16x32_bf16 v[56:59], v[158:161], v[182:185], v[56:59]
	v_mfma_f32_16x16x32_bf16 v[52:55], v[144:147], v[190:193], v[52:55]
	v_mfma_f32_16x16x32_bf16 v[44:47], v[158:161], v[190:193], v[44:47]
	v_mfma_f32_16x16x32_bf16 v[36:39], v[144:147], v[198:201], v[36:39]
	v_mfma_f32_16x16x32_bf16 v[28:31], v[158:161], v[198:201], v[28:31]
	v_mfma_f32_16x16x32_bf16 v[20:23], v[144:147], v[206:209], v[20:23]
	v_mfma_f32_16x16x32_bf16 v[12:15], v[158:161], v[206:209], v[12:15]
	v_mfma_f32_16x16x32_bf16 v[60:63], v[154:157], v[186:189], v[60:63]
	v_mfma_f32_16x16x32_bf16 v[56:59], v[162:165], v[186:189], v[56:59]
	v_mfma_f32_16x16x32_bf16 v[52:55], v[154:157], v[194:197], v[52:55]
	v_mfma_f32_16x16x32_bf16 v[44:47], v[162:165], v[194:197], v[44:47]
	v_mfma_f32_16x16x32_bf16 v[36:39], v[154:157], v[202:205], v[36:39]
	v_mfma_f32_16x16x32_bf16 v[28:31], v[162:165], v[202:205], v[28:31]
	v_mfma_f32_16x16x32_bf16 v[20:23], v[154:157], v[210:213], v[20:23]
	v_mfma_f32_16x16x32_bf16 v[12:15], v[162:165], v[210:213], v[12:15]
	s_setprio 0
	s_setprio 1
	v_mfma_f32_16x16x32_bf16 v[48:51], v[166:169], v[182:185], v[48:51]
	v_mfma_f32_16x16x32_bf16 v[40:43], v[174:177], v[182:185], v[40:43]
	v_mfma_f32_16x16x32_bf16 v[32:35], v[166:169], v[190:193], v[32:35]
	v_mfma_f32_16x16x32_bf16 v[24:27], v[174:177], v[190:193], v[24:27]
	v_mfma_f32_16x16x32_bf16 v[16:19], v[166:169], v[198:201], v[16:19]
	v_mfma_f32_16x16x32_bf16 v[8:11], v[174:177], v[198:201], v[8:11]
	v_mfma_f32_16x16x32_bf16 v[4:7], v[166:169], v[206:209], v[4:7]
	v_mfma_f32_16x16x32_bf16 v[0:3], v[174:177], v[206:209], v[0:3]
	v_mfma_f32_16x16x32_bf16 v[48:51], v[170:173], v[186:189], v[48:51]
	v_mfma_f32_16x16x32_bf16 v[40:43], v[178:181], v[186:189], v[40:43]
	v_mfma_f32_16x16x32_bf16 v[32:35], v[170:173], v[194:197], v[32:35]
	v_mfma_f32_16x16x32_bf16 v[24:27], v[178:181], v[194:197], v[24:27]
	v_mfma_f32_16x16x32_bf16 v[16:19], v[170:173], v[202:205], v[16:19]
	v_mfma_f32_16x16x32_bf16 v[8:11], v[178:181], v[202:205], v[8:11]
	v_mfma_f32_16x16x32_bf16 v[4:7], v[170:173], v[210:213], v[4:7]
	v_mfma_f32_16x16x32_bf16 v[0:3], v[178:181], v[210:213], v[0:3]
	s_setprio 0
	s_barrier
	s_add_i32 s56, s56, 2
	s_add_u32 s54, s54, 0x100
	s_addc_u32 s55, s55, 0
	s_add_u32 s18, s18, 0x100
	s_addc_u32 s19, s19, 0
	s_cmp_gt_u32 s56, 29
	s_cbranch_scc0 .LBB0_375
	s_and_b64 vcc, exec, s[6:7]
	s_cbranch_vccz .LBB0_378
	s_barrier

; #define PG8_STAGE(bufoff, gbase, voff) do { _Pragma("unroll") for (int _i = 0; _i < 2; ++_i) \
;         __builtin_amdgcn_global_load_lds((const unsigned*)((const char*)(gbase) + (voff)[_i]), (LAS unsigned*)(lds + (bufoff) + ldsw + _i * 8192), 16, 0, 0); } while (0)
; #define PG8_LDA(dst, b, h) do { _Pragma("unroll") for (int m = 0; m < 4; ++m) _Pragma("unroll") for (int k = 0; k < 2; ++k) dst[m][k] = *(const LAS bf16x8*)(lds + PG8_SA(b, h) + aoff + m * 2048 + k * 1024); } while (0)
; #define PG8_LDB(dst, b, h) do { _Pragma("unroll") for (int n = 0; n < 2; ++n) _Pragma("unroll") for (int k = 0; k < 2; ++k) dst[n][k] = *(const LAS bf16x8*)(lds + PG8_SB(b, h) + boff + n * 2048 + k * 1024); } while (0)
; #define PG8_MMA(ai, bj, At, Bt) do { __builtin_amdgcn_s_setprio(1); _Pragma("unroll") for (int m = 0; m < 4; ++m) _Pragma("unroll") for (int n = 0; n < 2; ++n) _Pragma("unroll") for (int k = 0; k < 2; ++k) \
;         acc[ai][bj][m][n] = __builtin_amdgcn_mfma_f32_16x16x32_bf16(Bt[n][k], At[m][k], acc[ai][bj][m][n], 0, 0, 0); __builtin_amdgcn_s_setprio(0); } while (0)
; #define PG8_WAIT_V(n) asm volatile("s_waitcnt vmcnt(" #n ")" ::: "memory")
; #define PG8_WAIT_L(n) asm volatile("s_waitcnt lgkmcnt(" #n ")" ::: "memory")
; #define PG8_BAR __builtin_amdgcn_s_barrier()
; #define PG8_SCHED __builtin_amdgcn_sched_barrier(0)
; template <class Epi>
; __device__ __forceinline__ void gemm_phase(ldsp lds, const Gemm g, const StaticOrder& S, const Epi& E, int wave0) {
;     ...
;             const char* a1 = cA + (size_t)(t + 1) * kstep;
;             const char* a2 = last ? nA : cA + (size_t)(t + 2) * kstep; const char* b2 = last ? nB : cB + (size_t)(t + 2) * kstep;
;             const char* a3 = a2 + kstep; const char* b3 = b2 + kstep;
;             PG8_LDB(B0, 0, 0); PG8_LDB(B1, 0, 1); PG8_SCHED; PG8_LDA(At, 0, 0); PG8_STAGE(PG8_SA(1, 1), a1 + hstep, voffA);
;             PG8_WAIT_V(8); PG8_WAIT_L(0); PG8_BAR; PG8_MMA(0, 0, At, B0); PG8_MMA(0, 1, At, B1); PG8_BAR; PG8_SCHED;
;             PG8_LDA(At, 0, 1); PG8_STAGE(PG8_SB(0, 0), b2, voffB); PG8_STAGE(PG8_SB(0, 1), b2 + hstep, voffB); PG8_STAGE(PG8_SA(0, 0), a2, voffA);
;             PG8_WAIT_V(8); PG8_WAIT_L(0); PG8_BAR; PG8_MMA(1, 0, At, B0); PG8_MMA(1, 1, At, B1); PG8_BAR; PG8_SCHED;
.LBB0_621:
	ds_read_b128 v[152:155], v149
	ds_read_b128 v[156:159], v149 offset:1024
	ds_read_b128 v[160:163], v149 offset:2048
	ds_read_b128 v[164:167], v149 offset:3072
	ds_read_b128 v[168:171], v150
	ds_read_b128 v[172:175], v150 offset:1024
	ds_read_b128 v[176:179], v150 offset:2048
	ds_read_b128 v[180:183], v150 offset:3072
	s_add_u32 s36, s34, 0xfff80080
	s_addc_u32 s37, s35, -1
	s_cmp_eq_u32 s76, 28
	s_cselect_b32 s39, s25, s37
	s_cselect_b32 s38, s72, s36
	s_cselect_b32 s37, s23, s75
	s_cselect_b32 s36, s73, s74
	s_add_i32 m0, s31, 0xc000
	ds_read_b128 v[184:187], v151
	ds_read_b128 v[188:191], v151 offset:1024
	ds_read_b128 v[192:195], v151 offset:2048
	ds_read_b128 v[196:199], v151 offset:3072
	ds_read_b128 v[200:203], v151 offset:4096
	ds_read_b128 v[204:207], v151 offset:5120
	ds_read_b128 v[208:211], v151 offset:6144
	ds_read_b128 v[212:215], v151 offset:7168
	global_load_lds_dwordx4 v138, s[34:35]
	s_add_i32 m0, s31, 0xe000
	s_nop 0
	global_load_lds_dwordx4 v136, s[34:35]
	s_waitcnt vmcnt(8)
	s_waitcnt lgkmcnt(0)
	s_barrier
	s_setprio 1
	s_waitcnt lgkmcnt(0)
	v_mfma_f32_16x16x32_bf16 v[124:127], v[152:155], v[184:187], v[124:127]
	v_mfma_f32_16x16x32_bf16 v[120:123], v[160:163], v[184:187], v[120:123]
	v_mfma_f32_16x16x32_bf16 v[108:111], v[152:155], v[192:195], v[108:111]
	v_mfma_f32_16x16x32_bf16 v[104:107], v[160:163], v[192:195], v[104:107]
	v_mfma_f32_16x16x32_bf16 v[92:95], v[152:155], v[200:203], v[92:95]
	v_mfma_f32_16x16x32_bf16 v[88:91], v[160:163], v[200:203], v[88:91]
	v_mfma_f32_16x16x32_bf16 v[76:79], v[152:155], v[208:211], v[76:79]
	v_mfma_f32_16x16x32_bf16 v[72:75], v[160:163], v[208:211], v[72:75]
	v_mfma_f32_16x16x32_bf16 v[124:127], v[156:159], v[188:191], v[124:127]
	v_mfma_f32_16x16x32_bf16 v[120:123], v[164:167], v[188:191], v[120:123]
	v_mfma_f32_16x16x32_bf16 v[108:111], v[156:159], v[196:199], v[108:111]
	v_mfma_f32_16x16x32_bf16 v[104:107], v[164:167], v[196:199], v[104:107]
	v_mfma_f32_16x16x32_bf16 v[92:95], v[156:159], v[204:207], v[92:95]
	v_mfma_f32_16x16x32_bf16 v[88:91], v[164:167], v[204:207], v[88:91]
	v_mfma_f32_16x16x32_bf16 v[76:79], v[156:159], v[212:215], v[76:79]
	v_mfma_f32_16x16x32_bf16 v[72:75], v[164:167], v[212:215], v[72:75]
	s_setprio 0
	s_setprio 1
	v_mfma_f32_16x16x32_bf16 v[116:119], v[168:171], v[184:187], v[116:119]
	v_mfma_f32_16x16x32_bf16 v[112:115], v[176:179], v[184:187], v[112:115]
	v_mfma_f32_16x16x32_bf16 v[100:103], v[168:171], v[192:195], v[100:103]
	v_mfma_f32_16x16x32_bf16 v[96:99], v[176:179], v[192:195], v[96:99]
	v_mfma_f32_16x16x32_bf16 v[84:87], v[168:171], v[200:203], v[84:87]
	v_mfma_f32_16x16x32_bf16 v[80:83], v[176:179], v[200:203], v[80:83]
	v_mfma_f32_16x16x32_bf16 v[68:71], v[168:171], v[208:211], v[68:71]
	v_mfma_f32_16x16x32_bf16 v[64:67], v[176:179], v[208:211], v[64:67]
	v_mfma_f32_16x16x32_bf16 v[116:119], v[172:175], v[188:191], v[116:119]
	v_mfma_f32_16x16x32_bf16 v[112:115], v[180:183], v[188:191], v[112:115]
	v_mfma_f32_16x16x32_bf16 v[100:103], v[172:175], v[196:199], v[100:103]
	v_mfma_f32_16x16x32_bf16 v[96:99], v[180:183], v[196:199], v[96:99]
	v_mfma_f32_16x16x32_bf16 v[84:87], v[172:175], v[204:207], v[84:87]
	v_mfma_f32_16x16x32_bf16 v[80:83], v[180:183], v[204:207], v[80:83]
	v_mfma_f32_16x16x32_bf16 v[68:71], v[172:175], v[212:215], v[68:71]
	v_mfma_f32_16x16x32_bf16 v[64:67], v[180:183], v[212:215], v[64:67]
	s_setprio 0
	s_barrier
	s_add_i32 s77, s62, s49
	s_add_u32 s100, s38, 0x80
	s_addc_u32 s101, s39, 0
	s_mov_b32 m0, s77
	ds_read_b128 v[184:187], v151 offset:16384
	ds_read_b128 v[188:191], v151 offset:17408
	ds_read_b128 v[192:195], v151 offset:18432
	ds_read_b128 v[196:199], v151 offset:19456
	ds_read_b128 v[200:203], v151 offset:20480
	ds_read_b128 v[204:207], v151 offset:21504
	ds_read_b128 v[208:211], v151 offset:22528
	ds_read_b128 v[212:215], v151 offset:23552
	global_load_lds_dwordx4 v130, s[36:37]
	s_add_i32 m0, s77, 0x2000
	s_add_u32 s78, s36, 0x80000
	s_addc_u32 s79, s37, 0
	s_add_i32 s77, s63, s49
	global_load_lds_dwordx4 v134, s[36:37]
	s_mov_b32 m0, s77
	s_nop 0
	global_load_lds_dwordx4 v130, s[78:79]
	s_add_i32 m0, s77, 0x2000
	s_nop 0
	global_load_lds_dwordx4 v134, s[78:79]
	s_mov_b32 m0, s31
	s_nop 0
	global_load_lds_dwordx4 v128, s[38:39]
	s_mov_b32 m0, s50
	s_nop 0
	global_load_lds_dwordx4 v132, s[38:39]
	s_waitcnt vmcnt(8)
	s_waitcnt lgkmcnt(0)
	s_barrier
	s_setprio 1
	s_waitcnt lgkmcnt(0)
	v_mfma_f32_16x16x32_bf16 v[60:63], v[152:155], v[184:187], v[60:63]
	v_mfma_f32_16x16x32_bf16 v[56:59], v[160:163], v[184:187], v[56:59]
	v_mfma_f32_16x16x32_bf16 v[44:47], v[152:155], v[192:195], v[44:47]
	v_mfma_f32_16x16x32_bf16 v[40:43], v[160:163], v[192:195], v[40:43]
	v_mfma_f32_16x16x32_bf16 v[28:31], v[152:155], v[200:203], v[28:31]
	v_mfma_f32_16x16x32_bf16 v[24:27], v[160:163], v[200:203], v[24:27]
	v_mfma_f32_16x16x32_bf16 v[12:15], v[152:155], v[208:211], v[12:15]
	v_mfma_f32_16x16x32_bf16 v[8:11], v[160:163], v[208:211], v[8:11]
	v_mfma_f32_16x16x32_bf16 v[60:63], v[156:159], v[188:191], v[60:63]
	v_mfma_f32_16x16x32_bf16 v[56:59], v[164:167], v[188:191], v[56:59]
	v_mfma_f32_16x16x32_bf16 v[44:47], v[156:159], v[196:199], v[44:47]
	v_mfma_f32_16x16x32_bf16 v[40:43], v[164:167], v[196:199], v[40:43]
	v_mfma_f32_16x16x32_bf16 v[28:31], v[156:159], v[204:207], v[28:31]
	v_mfma_f32_16x16x32_bf16 v[24:27], v[164:167], v[204:207], v[24:27]
	v_mfma_f32_16x16x32_bf16 v[12:15], v[156:159], v[212:215], v[12:15]
	v_mfma_f32_16x16x32_bf16 v[8:11], v[164:167], v[212:215], v[8:11]
	s_setprio 0
	s_setprio 1
	v_mfma_f32_16x16x32_bf16 v[52:55], v[168:171], v[184:187], v[52:55]
	v_mfma_f32_16x16x32_bf16 v[48:51], v[176:179], v[184:187], v[48:51]
	v_mfma_f32_16x16x32_bf16 v[36:39], v[168:171], v[192:195], v[36:39]
	v_mfma_f32_16x16x32_bf16 v[32:35], v[176:179], v[192:195], v[32:35]
	v_mfma_f32_16x16x32_bf16 v[20:23], v[168:171], v[200:203], v[20:23]
	v_mfma_f32_16x16x32_bf16 v[16:19], v[176:179], v[200:203], v[16:19]
	v_mfma_f32_16x16x32_bf16 v[4:7], v[168:171], v[208:211], v[4:7]
	v_mfma_f32_16x16x32_bf16 v[0:3], v[176:179], v[208:211], v[0:3]
	v_mfma_f32_16x16x32_bf16 v[52:55], v[172:175], v[188:191], v[52:55]
	v_mfma_f32_16x16x32_bf16 v[48:51], v[180:183], v[188:191], v[48:51]
	v_mfma_f32_16x16x32_bf16 v[36:39], v[172:175], v[196:199], v[36:39]
	v_mfma_f32_16x16x32_bf16 v[32:35], v[180:183], v[196:199], v[32:35]
	v_mfma_f32_16x16x32_bf16 v[20:23], v[172:175], v[204:207], v[20:23]
	v_mfma_f32_16x16x32_bf16 v[16:19], v[180:183], v[204:207], v[16:19]
	v_mfma_f32_16x16x32_bf16 v[4:7], v[172:175], v[212:215], v[4:7]
	v_mfma_f32_16x16x32_bf16 v[0:3], v[180:183], v[212:215], v[0:3]
	s_setprio 0
	s_barrier
; #define PG8_STAGE(bufoff, gbase, voff) do { _Pragma("unroll") for (int _i = 0; _i < 2; ++_i) \
;         __builtin_amdgcn_global_load_lds((const unsigned*)((const char*)(gbase) + (voff)[_i]), (LAS unsigned*)(lds + (bufoff) + ldsw + _i * 8192), 16, 0, 0); } while (0)
; #define PG8_LDA(dst, b, h) do { _Pragma("unroll") for (int m = 0; m < 4; ++m) _Pragma("unroll") for (int k = 0; k < 2; ++k) dst[m][k] = *(const LAS bf16x8*)(lds + PG8_SA(b, h) + aoff + m * 2048 + k * 1024); } while (0)
; #define PG8_LDB(dst, b, h) do { _Pragma("unroll") for (int n = 0; n < 2; ++n) _Pragma("unroll") for (int k = 0; k < 2; ++k) dst[n][k] = *(const LAS bf16x8*)(lds + PG8_SB(b, h) + boff + n * 2048 + k * 1024); } while (0)
; #define PG8_MMA(ai, bj, At, Bt) do { __builtin_amdgcn_s_setprio(1); _Pragma("unroll") for (int m = 0; m < 4; ++m) _Pragma("unroll") for (int n = 0; n < 2; ++n) _Pragma("unroll") for (int k = 0; k < 2; ++k) \
;         acc[ai][bj][m][n] = __builtin_amdgcn_mfma_f32_16x16x32_bf16(Bt[n][k], At[m][k], acc[ai][bj][m][n], 0, 0, 0); __builtin_amdgcn_s_setprio(0); } while (0)
; #define PG8_WAIT_V(n) asm volatile("s_waitcnt vmcnt(" #n ")" ::: "memory")
; #define PG8_WAIT_L(n) asm volatile("s_waitcnt lgkmcnt(" #n ")" ::: "memory")
; #define PG8_BAR __builtin_amdgcn_s_barrier()
; #define PG8_SCHED __builtin_amdgcn_sched_barrier(0)
; template <class Epi>
; __device__ __forceinline__ void gemm_phase(ldsp lds, const Gemm g, const StaticOrder& S, const Epi& E, int wave0) {
;     ...
;             PG8_LDB(B0, 1, 0); PG8_LDB(B1, 1, 1); PG8_SCHED; PG8_LDA(At, 1, 0); PG8_STAGE(PG8_SA(0, 1), a2 + hstep, voffA);
;             PG8_WAIT_V(8); PG8_WAIT_L(0); PG8_BAR; PG8_MMA(0, 0, At, B0); PG8_MMA(0, 1, At, B1); PG8_BAR; PG8_SCHED;
;             PG8_LDA(At, 1, 1); PG8_STAGE(PG8_SB(1, 0), b3, voffB); PG8_STAGE(PG8_SB(1, 1), b3 + hstep, voffB); PG8_STAGE(PG8_SA(1, 0), a3, voffA);
;             PG8_WAIT_V(8); PG8_WAIT_L(0); PG8_BAR; PG8_MMA(1, 0, At, B0); PG8_MMA(1, 1, At, B1); PG8_BAR; PG8_SCHED;
;         }
;         if (wr == 0) PG8_BAR;
	s_add_i32 s77, 0, 0x18000
	s_add_i32 s78, 0, 0x1c000
	v_add_u32_e32 v164, s77, v148
	v_add_u32_e32 v180, s78, v148
	ds_read_b128 v[152:155], v164
	ds_read_b128 v[156:159], v164 offset:1024
	ds_read_b128 v[160:163], v164 offset:2048
	ds_read_b128 v[164:167], v164 offset:3072
	ds_read_b128 v[168:171], v180
	ds_read_b128 v[172:175], v180 offset:1024
	ds_read_b128 v[176:179], v180 offset:2048
	ds_read_b128 v[180:183], v180 offset:3072
	s_add_u32 s38, s38, 0x80000
	s_addc_u32 s39, s39, 0
	s_mov_b32 m0, s51
	ds_read_b128 v[184:187], v151 offset:32768
	ds_read_b128 v[188:191], v151 offset:33792
	ds_read_b128 v[192:195], v151 offset:34816
	ds_read_b128 v[196:199], v151 offset:35840
	ds_read_b128 v[200:203], v151 offset:36864
	ds_read_b128 v[204:207], v151 offset:37888
	ds_read_b128 v[208:211], v151 offset:38912
	ds_read_b128 v[212:215], v151 offset:39936
	global_load_lds_dwordx4 v128, s[38:39]
	s_mov_b32 m0, s52
	s_nop 0
	global_load_lds_dwordx4 v132, s[38:39]
	s_waitcnt vmcnt(8)
	s_waitcnt lgkmcnt(0)
	s_barrier
	s_setprio 1
	s_waitcnt lgkmcnt(0)
	v_mfma_f32_16x16x32_bf16 v[124:127], v[152:155], v[184:187], v[124:127]
	v_mfma_f32_16x16x32_bf16 v[120:123], v[160:163], v[184:187], v[120:123]
	v_mfma_f32_16x16x32_bf16 v[108:111], v[152:155], v[192:195], v[108:111]
	v_mfma_f32_16x16x32_bf16 v[104:107], v[160:163], v[192:195], v[104:107]
	v_mfma_f32_16x16x32_bf16 v[92:95], v[152:155], v[200:203], v[92:95]
	v_mfma_f32_16x16x32_bf16 v[88:91], v[160:163], v[200:203], v[88:91]
	v_mfma_f32_16x16x32_bf16 v[76:79], v[152:155], v[208:211], v[76:79]
	v_mfma_f32_16x16x32_bf16 v[72:75], v[160:163], v[208:211], v[72:75]
	v_mfma_f32_16x16x32_bf16 v[124:127], v[156:159], v[188:191], v[124:127]
	v_mfma_f32_16x16x32_bf16 v[120:123], v[164:167], v[188:191], v[120:123]
	v_mfma_f32_16x16x32_bf16 v[108:111], v[156:159], v[196:199], v[108:111]
	v_mfma_f32_16x16x32_bf16 v[104:107], v[164:167], v[196:199], v[104:107]
	v_mfma_f32_16x16x32_bf16 v[92:95], v[156:159], v[204:207], v[92:95]
	v_mfma_f32_16x16x32_bf16 v[88:91], v[164:167], v[204:207], v[88:91]
	v_mfma_f32_16x16x32_bf16 v[76:79], v[156:159], v[212:215], v[76:79]
	v_mfma_f32_16x16x32_bf16 v[72:75], v[164:167], v[212:215], v[72:75]
	s_setprio 0
	s_setprio 1
	v_mfma_f32_16x16x32_bf16 v[116:119], v[168:171], v[184:187], v[116:119]
	v_mfma_f32_16x16x32_bf16 v[112:115], v[176:179], v[184:187], v[112:115]
	v_mfma_f32_16x16x32_bf16 v[100:103], v[168:171], v[192:195], v[100:103]
	v_mfma_f32_16x16x32_bf16 v[96:99], v[176:179], v[192:195], v[96:99]
	v_mfma_f32_16x16x32_bf16 v[84:87], v[168:171], v[200:203], v[84:87]
	v_mfma_f32_16x16x32_bf16 v[80:83], v[176:179], v[200:203], v[80:83]
	v_mfma_f32_16x16x32_bf16 v[68:71], v[168:171], v[208:211], v[68:71]
	v_mfma_f32_16x16x32_bf16 v[64:67], v[176:179], v[208:211], v[64:67]
	v_mfma_f32_16x16x32_bf16 v[116:119], v[172:175], v[188:191], v[116:119]
	v_mfma_f32_16x16x32_bf16 v[112:115], v[180:183], v[188:191], v[112:115]
	v_mfma_f32_16x16x32_bf16 v[100:103], v[172:175], v[196:199], v[100:103]
	v_mfma_f32_16x16x32_bf16 v[96:99], v[180:183], v[196:199], v[96:99]
	v_mfma_f32_16x16x32_bf16 v[84:87], v[172:175], v[204:207], v[84:87]
	v_mfma_f32_16x16x32_bf16 v[80:83], v[180:183], v[204:207], v[80:83]
	v_mfma_f32_16x16x32_bf16 v[68:71], v[172:175], v[212:215], v[68:71]
	v_mfma_f32_16x16x32_bf16 v[64:67], v[180:183], v[212:215], v[64:67]
	s_setprio 0
	s_barrier
	s_add_i32 s38, s77, s49
	s_add_u32 s36, s36, 0x80
	s_addc_u32 s37, s37, 0
	s_mov_b32 m0, s38
	ds_read_b128 v[184:187], v151 offset:49152
	ds_read_b128 v[188:191], v151 offset:50176
	ds_read_b128 v[192:195], v151 offset:51200
	ds_read_b128 v[196:199], v151 offset:52224
	ds_read_b128 v[200:203], v151 offset:53248
	ds_read_b128 v[204:207], v151 offset:54272
	ds_read_b128 v[208:211], v151 offset:55296
	ds_read_b128 v[212:215], v151 offset:56320
	global_load_lds_dwordx4 v130, s[36:37]
	s_add_i32 m0, s38, 0x2000
	s_add_i32 s38, s78, s49
	global_load_lds_dwordx4 v134, s[36:37]
	s_add_u32 s36, s36, 0x80000
	s_addc_u32 s37, s37, 0
	s_mov_b32 m0, s38
	s_nop 0
	global_load_lds_dwordx4 v130, s[36:37]
	s_add_i32 m0, s38, 0x2000
	s_nop 0
	global_load_lds_dwordx4 v134, s[36:37]
	s_mov_b32 m0, s59
	s_nop 0
	global_load_lds_dwordx4 v128, s[100:101]
	s_mov_b32 m0, s60
	s_nop 0
	global_load_lds_dwordx4 v132, s[100:101]
	s_waitcnt vmcnt(8)
	s_waitcnt lgkmcnt(0)
	s_barrier
	s_setprio 1
	s_waitcnt lgkmcnt(0)
	v_mfma_f32_16x16x32_bf16 v[60:63], v[152:155], v[184:187], v[60:63]
	v_mfma_f32_16x16x32_bf16 v[56:59], v[160:163], v[184:187], v[56:59]
	v_mfma_f32_16x16x32_bf16 v[44:47], v[152:155], v[192:195], v[44:47]
	v_mfma_f32_16x16x32_bf16 v[40:43], v[160:163], v[192:195], v[40:43]
	v_mfma_f32_16x16x32_bf16 v[28:31], v[152:155], v[200:203], v[28:31]
	v_mfma_f32_16x16x32_bf16 v[24:27], v[160:163], v[200:203], v[24:27]
	v_mfma_f32_16x16x32_bf16 v[12:15], v[152:155], v[208:211], v[12:15]
	v_mfma_f32_16x16x32_bf16 v[8:11], v[160:163], v[208:211], v[8:11]
	v_mfma_f32_16x16x32_bf16 v[60:63], v[156:159], v[188:191], v[60:63]
	v_mfma_f32_16x16x32_bf16 v[56:59], v[164:167], v[188:191], v[56:59]
	v_mfma_f32_16x16x32_bf16 v[44:47], v[156:159], v[196:199], v[44:47]
	v_mfma_f32_16x16x32_bf16 v[40:43], v[164:167], v[196:199], v[40:43]
	v_mfma_f32_16x16x32_bf16 v[28:31], v[156:159], v[204:207], v[28:31]
	v_mfma_f32_16x16x32_bf16 v[24:27], v[164:167], v[204:207], v[24:27]
	v_mfma_f32_16x16x32_bf16 v[12:15], v[156:159], v[212:215], v[12:15]
	v_mfma_f32_16x16x32_bf16 v[8:11], v[164:167], v[212:215], v[8:11]
	s_setprio 0
	s_setprio 1
	v_mfma_f32_16x16x32_bf16 v[52:55], v[168:171], v[184:187], v[52:55]
	v_mfma_f32_16x16x32_bf16 v[48:51], v[176:179], v[184:187], v[48:51]
	v_mfma_f32_16x16x32_bf16 v[36:39], v[168:171], v[192:195], v[36:39]
	v_mfma_f32_16x16x32_bf16 v[32:35], v[176:179], v[192:195], v[32:35]
	v_mfma_f32_16x16x32_bf16 v[20:23], v[168:171], v[200:203], v[20:23]
	v_mfma_f32_16x16x32_bf16 v[16:19], v[176:179], v[200:203], v[16:19]
	v_mfma_f32_16x16x32_bf16 v[4:7], v[168:171], v[208:211], v[4:7]
	v_mfma_f32_16x16x32_bf16 v[0:3], v[176:179], v[208:211], v[0:3]
	v_mfma_f32_16x16x32_bf16 v[52:55], v[172:175], v[188:191], v[52:55]
	v_mfma_f32_16x16x32_bf16 v[48:51], v[180:183], v[188:191], v[48:51]
	v_mfma_f32_16x16x32_bf16 v[36:39], v[172:175], v[196:199], v[36:39]
	v_mfma_f32_16x16x32_bf16 v[32:35], v[180:183], v[196:199], v[32:35]
	v_mfma_f32_16x16x32_bf16 v[20:23], v[172:175], v[204:207], v[20:23]
	v_mfma_f32_16x16x32_bf16 v[16:19], v[180:183], v[204:207], v[16:19]
	v_mfma_f32_16x16x32_bf16 v[4:7], v[172:175], v[212:215], v[4:7]
	v_mfma_f32_16x16x32_bf16 v[0:3], v[180:183], v[212:215], v[0:3]
	s_setprio 0
	s_barrier
	s_add_i32 s76, s76, 2
	s_add_u32 s74, s74, 0x100
	s_addc_u32 s75, s75, 0
	s_add_u32 s34, s34, 0x100
	s_addc_u32 s35, s35, 0
	s_cmp_gt_u32 s76, 29
	s_cbranch_scc0 .LBB0_621
	s_and_b64 vcc, exec, s[8:9]
	s_cbranch_vccz .LBB0_624
	s_barrier

; #define PG8_STAGE(bufoff, gbase, voff) do { _Pragma("unroll") for (int _i = 0; _i < 2; ++_i) \
;         __builtin_amdgcn_global_load_lds((const unsigned*)((const char*)(gbase) + (voff)[_i]), (LAS unsigned*)(lds + (bufoff) + ldsw + _i * 8192), 16, 0, 0); } while (0)
; #define PG8_LDA(dst, b, h) do { _Pragma("unroll") for (int m = 0; m < 4; ++m) _Pragma("unroll") for (int k = 0; k < 2; ++k) dst[m][k] = *(const LAS bf16x8*)(lds + PG8_SA(b, h) + aoff + m * 2048 + k * 1024); } while (0)
; #define PG8_LDB(dst, b, h) do { _Pragma("unroll") for (int n = 0; n < 2; ++n) _Pragma("unroll") for (int k = 0; k < 2; ++k) dst[n][k] = *(const LAS bf16x8*)(lds + PG8_SB(b, h) + boff + n * 2048 + k * 1024); } while (0)
; #define PG8_MMA(ai, bj, At, Bt) do { __builtin_amdgcn_s_setprio(1); _Pragma("unroll") for (int m = 0; m < 4; ++m) _Pragma("unroll") for (int n = 0; n < 2; ++n) _Pragma("unroll") for (int k = 0; k < 2; ++k) \
;         acc[ai][bj][m][n] = __builtin_amdgcn_mfma_f32_16x16x32_bf16(Bt[n][k], At[m][k], acc[ai][bj][m][n], 0, 0, 0); __builtin_amdgcn_s_setprio(0); } while (0)
; #define PG8_WAIT_V(n) asm volatile("s_waitcnt vmcnt(" #n ")" ::: "memory")
; #define PG8_WAIT_L(n) asm volatile("s_waitcnt lgkmcnt(" #n ")" ::: "memory")
; #define PG8_BAR __builtin_amdgcn_s_barrier()
; #define PG8_SCHED __builtin_amdgcn_sched_barrier(0)
; template <class Epi>
; __device__ __forceinline__ void gemm_phase(ldsp lds, const Gemm g, const StaticOrder& S, const Epi& E, int wave0) {
;     ...
;             const char* a1 = cA + (size_t)(t + 1) * kstep;
;             const char* a2 = last ? nA : cA + (size_t)(t + 2) * kstep; const char* b2 = last ? nB : cB + (size_t)(t + 2) * kstep;
;             const char* a3 = a2 + kstep; const char* b3 = b2 + kstep;
;             PG8_LDB(B0, 0, 0); PG8_LDB(B1, 0, 1); PG8_SCHED; PG8_LDA(At, 0, 0); PG8_STAGE(PG8_SA(1, 1), a1 + hstep, voffA);
;             PG8_WAIT_V(8); PG8_WAIT_L(0); PG8_BAR; PG8_MMA(0, 0, At, B0); PG8_MMA(0, 1, At, B1); PG8_BAR; PG8_SCHED;
;             PG8_LDA(At, 0, 1); PG8_STAGE(PG8_SB(0, 0), b2, voffB); PG8_STAGE(PG8_SB(0, 1), b2 + hstep, voffB); PG8_STAGE(PG8_SA(0, 0), a2, voffA);
;             PG8_WAIT_V(8); PG8_WAIT_L(0); PG8_BAR; PG8_MMA(1, 0, At, B0); PG8_MMA(1, 1, At, B1); PG8_BAR; PG8_SCHED;
.LBB0_689:
	ds_read_b128 v[152:155], v149
	ds_read_b128 v[156:159], v149 offset:1024
	ds_read_b128 v[160:163], v149 offset:2048
	ds_read_b128 v[164:167], v149 offset:3072
	ds_read_b128 v[168:171], v150
	ds_read_b128 v[172:175], v150 offset:1024
	ds_read_b128 v[176:179], v150 offset:2048
	ds_read_b128 v[180:183], v150 offset:3072
	s_add_u32 s38, s36, 0xfff80080
	s_addc_u32 s39, s37, -1
	s_cmp_eq_u32 s73, 28
	s_cselect_b32 s41, s27, s39
	s_cselect_b32 s40, s69, s38
	s_cselect_b32 s39, s25, s72
	s_cselect_b32 s38, s70, s71
	s_add_i32 m0, s35, 0xc000
	ds_read_b128 v[184:187], v151
	ds_read_b128 v[188:191], v151 offset:1024
	ds_read_b128 v[192:195], v151 offset:2048
	ds_read_b128 v[196:199], v151 offset:3072
	ds_read_b128 v[200:203], v151 offset:4096
	ds_read_b128 v[204:207], v151 offset:5120
	ds_read_b128 v[208:211], v151 offset:6144
	ds_read_b128 v[212:215], v151 offset:7168
	global_load_lds_dwordx4 v138, s[36:37]
	s_add_i32 m0, s35, 0xe000
	s_nop 0
	global_load_lds_dwordx4 v136, s[36:37]
	s_waitcnt vmcnt(8)
	s_waitcnt lgkmcnt(0)
	s_barrier
	s_setprio 1
	s_waitcnt lgkmcnt(0)
	v_mfma_f32_16x16x32_bf16 v[124:127], v[152:155], v[184:187], v[124:127]
	v_mfma_f32_16x16x32_bf16 v[120:123], v[160:163], v[184:187], v[120:123]
	v_mfma_f32_16x16x32_bf16 v[112:115], v[152:155], v[192:195], v[112:115]
	v_mfma_f32_16x16x32_bf16 v[104:107], v[160:163], v[192:195], v[104:107]
	v_mfma_f32_16x16x32_bf16 v[96:99], v[152:155], v[200:203], v[96:99]
	v_mfma_f32_16x16x32_bf16 v[88:91], v[160:163], v[200:203], v[88:91]
	v_mfma_f32_16x16x32_bf16 v[80:83], v[152:155], v[208:211], v[80:83]
	v_mfma_f32_16x16x32_bf16 v[72:75], v[160:163], v[208:211], v[72:75]
	v_mfma_f32_16x16x32_bf16 v[124:127], v[156:159], v[188:191], v[124:127]
	v_mfma_f32_16x16x32_bf16 v[120:123], v[164:167], v[188:191], v[120:123]
	v_mfma_f32_16x16x32_bf16 v[112:115], v[156:159], v[196:199], v[112:115]
	v_mfma_f32_16x16x32_bf16 v[104:107], v[164:167], v[196:199], v[104:107]
	v_mfma_f32_16x16x32_bf16 v[96:99], v[156:159], v[204:207], v[96:99]
	v_mfma_f32_16x16x32_bf16 v[88:91], v[164:167], v[204:207], v[88:91]
	v_mfma_f32_16x16x32_bf16 v[80:83], v[156:159], v[212:215], v[80:83]
	v_mfma_f32_16x16x32_bf16 v[72:75], v[164:167], v[212:215], v[72:75]
	s_setprio 0
	s_setprio 1
	v_mfma_f32_16x16x32_bf16 v[116:119], v[168:171], v[184:187], v[116:119]
	v_mfma_f32_16x16x32_bf16 v[108:111], v[176:179], v[184:187], v[108:111]
	v_mfma_f32_16x16x32_bf16 v[100:103], v[168:171], v[192:195], v[100:103]
	v_mfma_f32_16x16x32_bf16 v[92:95], v[176:179], v[192:195], v[92:95]
	v_mfma_f32_16x16x32_bf16 v[84:87], v[168:171], v[200:203], v[84:87]
	v_mfma_f32_16x16x32_bf16 v[76:79], v[176:179], v[200:203], v[76:79]
	v_mfma_f32_16x16x32_bf16 v[68:71], v[168:171], v[208:211], v[68:71]
	v_mfma_f32_16x16x32_bf16 v[64:67], v[176:179], v[208:211], v[64:67]
	v_mfma_f32_16x16x32_bf16 v[116:119], v[172:175], v[188:191], v[116:119]
	v_mfma_f32_16x16x32_bf16 v[108:111], v[180:183], v[188:191], v[108:111]
	v_mfma_f32_16x16x32_bf16 v[100:103], v[172:175], v[196:199], v[100:103]
	v_mfma_f32_16x16x32_bf16 v[92:95], v[180:183], v[196:199], v[92:95]
	v_mfma_f32_16x16x32_bf16 v[84:87], v[172:175], v[204:207], v[84:87]
	v_mfma_f32_16x16x32_bf16 v[76:79], v[180:183], v[204:207], v[76:79]
	v_mfma_f32_16x16x32_bf16 v[68:71], v[172:175], v[212:215], v[68:71]
	v_mfma_f32_16x16x32_bf16 v[64:67], v[180:183], v[212:215], v[64:67]
	s_setprio 0
	s_barrier
	s_add_i32 s74, s60, s49
	s_add_u32 s100, s40, 0x80
	s_addc_u32 s101, s41, 0
	s_mov_b32 m0, s74
	ds_read_b128 v[184:187], v151 offset:16384
	ds_read_b128 v[188:191], v151 offset:17408
	ds_read_b128 v[192:195], v151 offset:18432
	ds_read_b128 v[196:199], v151 offset:19456
	ds_read_b128 v[200:203], v151 offset:20480
	ds_read_b128 v[204:207], v151 offset:21504
	ds_read_b128 v[208:211], v151 offset:22528
	ds_read_b128 v[212:215], v151 offset:23552
	global_load_lds_dwordx4 v130, s[38:39]
	s_add_i32 m0, s74, 0x2000
	s_add_u32 s74, s38, 0x80000
	s_addc_u32 s75, s39, 0
	s_add_i32 s76, s61, s49
	global_load_lds_dwordx4 v134, s[38:39]
	s_mov_b32 m0, s76
	s_nop 0
	global_load_lds_dwordx4 v130, s[74:75]
	s_add_i32 m0, s76, 0x2000
	s_nop 0
	global_load_lds_dwordx4 v134, s[74:75]
	s_mov_b32 m0, s35
	s_nop 0
	global_load_lds_dwordx4 v128, s[40:41]
	s_mov_b32 m0, s50
	s_nop 0
	global_load_lds_dwordx4 v132, s[40:41]
	s_waitcnt vmcnt(8)
	s_waitcnt lgkmcnt(0)
	s_barrier
	s_setprio 1
	s_waitcnt lgkmcnt(0)
	v_mfma_f32_16x16x32_bf16 v[60:63], v[152:155], v[184:187], v[60:63]
	v_mfma_f32_16x16x32_bf16 v[56:59], v[160:163], v[184:187], v[56:59]
	v_mfma_f32_16x16x32_bf16 v[48:51], v[152:155], v[192:195], v[48:51]
	v_mfma_f32_16x16x32_bf16 v[40:43], v[160:163], v[192:195], v[40:43]
	v_mfma_f32_16x16x32_bf16 v[32:35], v[152:155], v[200:203], v[32:35]
	v_mfma_f32_16x16x32_bf16 v[24:27], v[160:163], v[200:203], v[24:27]
	v_mfma_f32_16x16x32_bf16 v[16:19], v[152:155], v[208:211], v[16:19]
	v_mfma_f32_16x16x32_bf16 v[8:11], v[160:163], v[208:211], v[8:11]
	v_mfma_f32_16x16x32_bf16 v[60:63], v[156:159], v[188:191], v[60:63]
	v_mfma_f32_16x16x32_bf16 v[56:59], v[164:167], v[188:191], v[56:59]
	v_mfma_f32_16x16x32_bf16 v[48:51], v[156:159], v[196:199], v[48:51]
	v_mfma_f32_16x16x32_bf16 v[40:43], v[164:167], v[196:199], v[40:43]
	v_mfma_f32_16x16x32_bf16 v[32:35], v[156:159], v[204:207], v[32:35]
	v_mfma_f32_16x16x32_bf16 v[24:27], v[164:167], v[204:207], v[24:27]
	v_mfma_f32_16x16x32_bf16 v[16:19], v[156:159], v[212:215], v[16:19]
	v_mfma_f32_16x16x32_bf16 v[8:11], v[164:167], v[212:215], v[8:11]
	s_setprio 0
	s_setprio 1
	v_mfma_f32_16x16x32_bf16 v[52:55], v[168:171], v[184:187], v[52:55]
	v_mfma_f32_16x16x32_bf16 v[44:47], v[176:179], v[184:187], v[44:47]
	v_mfma_f32_16x16x32_bf16 v[36:39], v[168:171], v[192:195], v[36:39]
	v_mfma_f32_16x16x32_bf16 v[28:31], v[176:179], v[192:195], v[28:31]
	v_mfma_f32_16x16x32_bf16 v[20:23], v[168:171], v[200:203], v[20:23]
	v_mfma_f32_16x16x32_bf16 v[12:15], v[176:179], v[200:203], v[12:15]
	v_mfma_f32_16x16x32_bf16 v[4:7], v[168:171], v[208:211], v[4:7]
	v_mfma_f32_16x16x32_bf16 v[0:3], v[176:179], v[208:211], v[0:3]
	v_mfma_f32_16x16x32_bf16 v[52:55], v[172:175], v[188:191], v[52:55]
	v_mfma_f32_16x16x32_bf16 v[44:47], v[180:183], v[188:191], v[44:47]
	v_mfma_f32_16x16x32_bf16 v[36:39], v[172:175], v[196:199], v[36:39]
	v_mfma_f32_16x16x32_bf16 v[28:31], v[180:183], v[196:199], v[28:31]
	v_mfma_f32_16x16x32_bf16 v[20:23], v[172:175], v[204:207], v[20:23]
	v_mfma_f32_16x16x32_bf16 v[12:15], v[180:183], v[204:207], v[12:15]
	v_mfma_f32_16x16x32_bf16 v[4:7], v[172:175], v[212:215], v[4:7]
	v_mfma_f32_16x16x32_bf16 v[0:3], v[180:183], v[212:215], v[0:3]
	s_setprio 0
	s_barrier
; #define PG8_STAGE(bufoff, gbase, voff) do { _Pragma("unroll") for (int _i = 0; _i < 2; ++_i) \
;         __builtin_amdgcn_global_load_lds((const unsigned*)((const char*)(gbase) + (voff)[_i]), (LAS unsigned*)(lds + (bufoff) + ldsw + _i * 8192), 16, 0, 0); } while (0)
; #define PG8_LDA(dst, b, h) do { _Pragma("unroll") for (int m = 0; m < 4; ++m) _Pragma("unroll") for (int k = 0; k < 2; ++k) dst[m][k] = *(const LAS bf16x8*)(lds + PG8_SA(b, h) + aoff + m * 2048 + k * 1024); } while (0)
; #define PG8_LDB(dst, b, h) do { _Pragma("unroll") for (int n = 0; n < 2; ++n) _Pragma("unroll") for (int k = 0; k < 2; ++k) dst[n][k] = *(const LAS bf16x8*)(lds + PG8_SB(b, h) + boff + n * 2048 + k * 1024); } while (0)
; #define PG8_MMA(ai, bj, At, Bt) do { __builtin_amdgcn_s_setprio(1); _Pragma("unroll") for (int m = 0; m < 4; ++m) _Pragma("unroll") for (int n = 0; n < 2; ++n) _Pragma("unroll") for (int k = 0; k < 2; ++k) \
;         acc[ai][bj][m][n] = __builtin_amdgcn_mfma_f32_16x16x32_bf16(Bt[n][k], At[m][k], acc[ai][bj][m][n], 0, 0, 0); __builtin_amdgcn_s_setprio(0); } while (0)
; #define PG8_WAIT_V(n) asm volatile("s_waitcnt vmcnt(" #n ")" ::: "memory")
; #define PG8_WAIT_L(n) asm volatile("s_waitcnt lgkmcnt(" #n ")" ::: "memory")
; #define PG8_BAR __builtin_amdgcn_s_barrier()
; #define PG8_SCHED __builtin_amdgcn_sched_barrier(0)
; template <class Epi>
; __device__ __forceinline__ void gemm_phase(ldsp lds, const Gemm g, const StaticOrder& S, const Epi& E, int wave0) {
;     ...
;             PG8_LDB(B0, 1, 0); PG8_LDB(B1, 1, 1); PG8_SCHED; PG8_LDA(At, 1, 0); PG8_STAGE(PG8_SA(0, 1), a2 + hstep, voffA);
;             PG8_WAIT_V(8); PG8_WAIT_L(0); PG8_BAR; PG8_MMA(0, 0, At, B0); PG8_MMA(0, 1, At, B1); PG8_BAR; PG8_SCHED;
;             PG8_LDA(At, 1, 1); PG8_STAGE(PG8_SB(1, 0), b3, voffB); PG8_STAGE(PG8_SB(1, 1), b3 + hstep, voffB); PG8_STAGE(PG8_SA(1, 0), a3, voffA);
;             PG8_WAIT_V(8); PG8_WAIT_L(0); PG8_BAR; PG8_MMA(1, 0, At, B0); PG8_MMA(1, 1, At, B1); PG8_BAR; PG8_SCHED;
;         }
;         if (wr == 0) PG8_BAR;
	s_add_i32 s74, 0, 0x18000
	s_add_i32 s75, 0, 0x1c000
	v_add_u32_e32 v164, s74, v148
	v_add_u32_e32 v180, s75, v148
	ds_read_b128 v[152:155], v164
	ds_read_b128 v[156:159], v164 offset:1024
	ds_read_b128 v[160:163], v164 offset:2048
	ds_read_b128 v[164:167], v164 offset:3072
	ds_read_b128 v[168:171], v180
	ds_read_b128 v[172:175], v180 offset:1024
	ds_read_b128 v[176:179], v180 offset:2048
	ds_read_b128 v[180:183], v180 offset:3072
	s_add_u32 s40, s40, 0x80000
	s_addc_u32 s41, s41, 0
	s_mov_b32 m0, s51
	ds_read_b128 v[184:187], v151 offset:32768
	ds_read_b128 v[188:191], v151 offset:33792
	ds_read_b128 v[192:195], v151 offset:34816
	ds_read_b128 v[196:199], v151 offset:35840
	ds_read_b128 v[200:203], v151 offset:36864
	ds_read_b128 v[204:207], v151 offset:37888
	ds_read_b128 v[208:211], v151 offset:38912
	ds_read_b128 v[212:215], v151 offset:39936
	global_load_lds_dwordx4 v128, s[40:41]
	s_mov_b32 m0, s52
	s_nop 0
	global_load_lds_dwordx4 v132, s[40:41]
	s_waitcnt vmcnt(8)
	s_waitcnt lgkmcnt(0)
	s_barrier
	s_setprio 1
	s_waitcnt lgkmcnt(0)
	v_mfma_f32_16x16x32_bf16 v[124:127], v[152:155], v[184:187], v[124:127]
	v_mfma_f32_16x16x32_bf16 v[120:123], v[160:163], v[184:187], v[120:123]
	v_mfma_f32_16x16x32_bf16 v[112:115], v[152:155], v[192:195], v[112:115]
	v_mfma_f32_16x16x32_bf16 v[104:107], v[160:163], v[192:195], v[104:107]
	v_mfma_f32_16x16x32_bf16 v[96:99], v[152:155], v[200:203], v[96:99]
	v_mfma_f32_16x16x32_bf16 v[88:91], v[160:163], v[200:203], v[88:91]
	v_mfma_f32_16x16x32_bf16 v[80:83], v[152:155], v[208:211], v[80:83]
	v_mfma_f32_16x16x32_bf16 v[72:75], v[160:163], v[208:211], v[72:75]
	v_mfma_f32_16x16x32_bf16 v[124:127], v[156:159], v[188:191], v[124:127]
	v_mfma_f32_16x16x32_bf16 v[120:123], v[164:167], v[188:191], v[120:123]
	v_mfma_f32_16x16x32_bf16 v[112:115], v[156:159], v[196:199], v[112:115]
	v_mfma_f32_16x16x32_bf16 v[104:107], v[164:167], v[196:199], v[104:107]
	v_mfma_f32_16x16x32_bf16 v[96:99], v[156:159], v[204:207], v[96:99]
	v_mfma_f32_16x16x32_bf16 v[88:91], v[164:167], v[204:207], v[88:91]
	v_mfma_f32_16x16x32_bf16 v[80:83], v[156:159], v[212:215], v[80:83]
	v_mfma_f32_16x16x32_bf16 v[72:75], v[164:167], v[212:215], v[72:75]
	s_setprio 0
	s_setprio 1
	v_mfma_f32_16x16x32_bf16 v[116:119], v[168:171], v[184:187], v[116:119]
	v_mfma_f32_16x16x32_bf16 v[108:111], v[176:179], v[184:187], v[108:111]
	v_mfma_f32_16x16x32_bf16 v[100:103], v[168:171], v[192:195], v[100:103]
	v_mfma_f32_16x16x32_bf16 v[92:95], v[176:179], v[192:195], v[92:95]
	v_mfma_f32_16x16x32_bf16 v[84:87], v[168:171], v[200:203], v[84:87]
	v_mfma_f32_16x16x32_bf16 v[76:79], v[176:179], v[200:203], v[76:79]
	v_mfma_f32_16x16x32_bf16 v[68:71], v[168:171], v[208:211], v[68:71]
	v_mfma_f32_16x16x32_bf16 v[64:67], v[176:179], v[208:211], v[64:67]
	v_mfma_f32_16x16x32_bf16 v[116:119], v[172:175], v[188:191], v[116:119]
	v_mfma_f32_16x16x32_bf16 v[108:111], v[180:183], v[188:191], v[108:111]
	v_mfma_f32_16x16x32_bf16 v[100:103], v[172:175], v[196:199], v[100:103]
	v_mfma_f32_16x16x32_bf16 v[92:95], v[180:183], v[196:199], v[92:95]
	v_mfma_f32_16x16x32_bf16 v[84:87], v[172:175], v[204:207], v[84:87]
	v_mfma_f32_16x16x32_bf16 v[76:79], v[180:183], v[204:207], v[76:79]
	v_mfma_f32_16x16x32_bf16 v[68:71], v[172:175], v[212:215], v[68:71]
	v_mfma_f32_16x16x32_bf16 v[64:67], v[180:183], v[212:215], v[64:67]
	s_setprio 0
	s_barrier
	s_add_i32 s40, s74, s49
	s_add_u32 s38, s38, 0x80
	s_addc_u32 s39, s39, 0
	s_mov_b32 m0, s40
	ds_read_b128 v[184:187], v151 offset:49152
	ds_read_b128 v[188:191], v151 offset:50176
	ds_read_b128 v[192:195], v151 offset:51200
	ds_read_b128 v[196:199], v151 offset:52224
	ds_read_b128 v[200:203], v151 offset:53248
	ds_read_b128 v[204:207], v151 offset:54272
	ds_read_b128 v[208:211], v151 offset:55296
	ds_read_b128 v[212:215], v151 offset:56320
	global_load_lds_dwordx4 v130, s[38:39]
	s_add_i32 m0, s40, 0x2000
	s_add_i32 s40, s75, s49
	global_load_lds_dwordx4 v134, s[38:39]
	s_add_u32 s38, s38, 0x80000
	s_addc_u32 s39, s39, 0
	s_mov_b32 m0, s40
	s_nop 0
	global_load_lds_dwordx4 v130, s[38:39]
	s_add_i32 m0, s40, 0x2000
	s_nop 0
	global_load_lds_dwordx4 v134, s[38:39]
	s_mov_b32 m0, s57
	s_nop 0
	global_load_lds_dwordx4 v128, s[100:101]
	s_mov_b32 m0, s58
	s_nop 0
	global_load_lds_dwordx4 v132, s[100:101]
	s_waitcnt vmcnt(8)
	s_waitcnt lgkmcnt(0)
	s_barrier
	s_setprio 1
	s_waitcnt lgkmcnt(0)
	v_mfma_f32_16x16x32_bf16 v[60:63], v[152:155], v[184:187], v[60:63]
	v_mfma_f32_16x16x32_bf16 v[56:59], v[160:163], v[184:187], v[56:59]
	v_mfma_f32_16x16x32_bf16 v[48:51], v[152:155], v[192:195], v[48:51]
	v_mfma_f32_16x16x32_bf16 v[40:43], v[160:163], v[192:195], v[40:43]
	v_mfma_f32_16x16x32_bf16 v[32:35], v[152:155], v[200:203], v[32:35]
	v_mfma_f32_16x16x32_bf16 v[24:27], v[160:163], v[200:203], v[24:27]
	v_mfma_f32_16x16x32_bf16 v[16:19], v[152:155], v[208:211], v[16:19]
	v_mfma_f32_16x16x32_bf16 v[8:11], v[160:163], v[208:211], v[8:11]
	v_mfma_f32_16x16x32_bf16 v[60:63], v[156:159], v[188:191], v[60:63]
	v_mfma_f32_16x16x32_bf16 v[56:59], v[164:167], v[188:191], v[56:59]
	v_mfma_f32_16x16x32_bf16 v[48:51], v[156:159], v[196:199], v[48:51]
	v_mfma_f32_16x16x32_bf16 v[40:43], v[164:167], v[196:199], v[40:43]
	v_mfma_f32_16x16x32_bf16 v[32:35], v[156:159], v[204:207], v[32:35]
	v_mfma_f32_16x16x32_bf16 v[24:27], v[164:167], v[204:207], v[24:27]
	v_mfma_f32_16x16x32_bf16 v[16:19], v[156:159], v[212:215], v[16:19]
	v_mfma_f32_16x16x32_bf16 v[8:11], v[164:167], v[212:215], v[8:11]
	s_setprio 0
	s_setprio 1
	v_mfma_f32_16x16x32_bf16 v[52:55], v[168:171], v[184:187], v[52:55]
	v_mfma_f32_16x16x32_bf16 v[44:47], v[176:179], v[184:187], v[44:47]
	v_mfma_f32_16x16x32_bf16 v[36:39], v[168:171], v[192:195], v[36:39]
	v_mfma_f32_16x16x32_bf16 v[28:31], v[176:179], v[192:195], v[28:31]
	v_mfma_f32_16x16x32_bf16 v[20:23], v[168:171], v[200:203], v[20:23]
	v_mfma_f32_16x16x32_bf16 v[12:15], v[176:179], v[200:203], v[12:15]
	v_mfma_f32_16x16x32_bf16 v[4:7], v[168:171], v[208:211], v[4:7]
	v_mfma_f32_16x16x32_bf16 v[0:3], v[176:179], v[208:211], v[0:3]
	v_mfma_f32_16x16x32_bf16 v[52:55], v[172:175], v[188:191], v[52:55]
	v_mfma_f32_16x16x32_bf16 v[44:47], v[180:183], v[188:191], v[44:47]
	v_mfma_f32_16x16x32_bf16 v[36:39], v[172:175], v[196:199], v[36:39]
	v_mfma_f32_16x16x32_bf16 v[28:31], v[180:183], v[196:199], v[28:31]
	v_mfma_f32_16x16x32_bf16 v[20:23], v[172:175], v[204:207], v[20:23]
	v_mfma_f32_16x16x32_bf16 v[12:15], v[180:183], v[204:207], v[12:15]
	v_mfma_f32_16x16x32_bf16 v[4:7], v[172:175], v[212:215], v[4:7]
	v_mfma_f32_16x16x32_bf16 v[0:3], v[180:183], v[212:215], v[0:3]
	s_setprio 0
	s_barrier
	s_add_i32 s73, s73, 2
	s_add_u32 s71, s71, 0x100
	s_addc_u32 s72, s72, 0
	s_add_u32 s36, s36, 0x100
	s_addc_u32 s37, s37, 0
	s_cmp_gt_u32 s73, 29
	s_cbranch_scc0 .LBB0_689
	s_and_b64 vcc, exec, s[10:11]
	s_cbranch_vccz .LBB0_692
	s_barrier

; #define PG8_STAGE(bufoff, gbase, voff) do { _Pragma("unroll") for (int _i = 0; _i < 2; ++_i) \
;         __builtin_amdgcn_global_load_lds((const unsigned*)((const char*)(gbase) + (voff)[_i]), (LAS unsigned*)(lds + (bufoff) + ldsw + _i * 8192), 16, 0, 0); } while (0)
; #define PG8_LDA(dst, b, h) do { _Pragma("unroll") for (int m = 0; m < 4; ++m) _Pragma("unroll") for (int k = 0; k < 2; ++k) dst[m][k] = *(const LAS bf16x8*)(lds + PG8_SA(b, h) + aoff + m * 2048 + k * 1024); } while (0)
; #define PG8_LDB(dst, b, h) do { _Pragma("unroll") for (int n = 0; n < 2; ++n) _Pragma("unroll") for (int k = 0; k < 2; ++k) dst[n][k] = *(const LAS bf16x8*)(lds + PG8_SB(b, h) + boff + n * 2048 + k * 1024); } while (0)
; #define PG8_MMA(ai, bj, At, Bt) do { __builtin_amdgcn_s_setprio(1); _Pragma("unroll") for (int m = 0; m < 4; ++m) _Pragma("unroll") for (int n = 0; n < 2; ++n) _Pragma("unroll") for (int k = 0; k < 2; ++k) \
;         acc[ai][bj][m][n] = __builtin_amdgcn_mfma_f32_16x16x32_bf16(Bt[n][k], At[m][k], acc[ai][bj][m][n], 0, 0, 0); __builtin_amdgcn_s_setprio(0); } while (0)
; #define PG8_WAIT_V(n) asm volatile("s_waitcnt vmcnt(" #n ")" ::: "memory")
; #define PG8_WAIT_L(n) asm volatile("s_waitcnt lgkmcnt(" #n ")" ::: "memory")
; #define PG8_BAR __builtin_amdgcn_s_barrier()
; #define PG8_SCHED __builtin_amdgcn_sched_barrier(0)
; template <class Epi>
; __device__ __forceinline__ void gemm_phase(ldsp lds, const Gemm g, const StaticOrder& S, const Epi& E, int wave0) {
;     ...
;             const char* a1 = cA + (size_t)(t + 1) * kstep;
;             const char* a2 = last ? nA : cA + (size_t)(t + 2) * kstep; const char* b2 = last ? nB : cB + (size_t)(t + 2) * kstep;
;             const char* a3 = a2 + kstep; const char* b3 = b2 + kstep;
;             PG8_LDB(B0, 0, 0); PG8_LDB(B1, 0, 1); PG8_SCHED; PG8_LDA(At, 0, 0); PG8_STAGE(PG8_SA(1, 1), a1 + hstep, voffA);
;             PG8_WAIT_V(8); PG8_WAIT_L(0); PG8_BAR; PG8_MMA(0, 0, At, B0); PG8_MMA(0, 1, At, B1); PG8_BAR; PG8_SCHED;
;             PG8_LDA(At, 0, 1); PG8_STAGE(PG8_SB(0, 0), b2, voffB); PG8_STAGE(PG8_SB(0, 1), b2 + hstep, voffB); PG8_STAGE(PG8_SA(0, 0), a2, voffA);
;             PG8_WAIT_V(8); PG8_WAIT_L(0); PG8_BAR; PG8_MMA(1, 0, At, B0); PG8_MMA(1, 1, At, B1); PG8_BAR; PG8_SCHED;
.LBB0_713:
	ds_read_b128 v[152:155], v149
	ds_read_b128 v[156:159], v149 offset:1024
	ds_read_b128 v[160:163], v149 offset:2048
	ds_read_b128 v[164:167], v149 offset:3072
	ds_read_b128 v[168:171], v150
	ds_read_b128 v[172:175], v150 offset:1024
	ds_read_b128 v[176:179], v150 offset:2048
	ds_read_b128 v[180:183], v150 offset:3072
	s_add_u32 s40, s38, 0xfffc0080
	s_addc_u32 s41, s39, -1
	s_cmp_eq_u32 s66, 12
	s_cselect_b32 s43, s29, s41
	s_cselect_b32 s42, s62, s40
	s_cselect_b32 s41, s27, s65
	s_cselect_b32 s40, s63, s64
	s_add_i32 m0, s37, 0xc000
	ds_read_b128 v[184:187], v151
	ds_read_b128 v[188:191], v151 offset:1024
	ds_read_b128 v[192:195], v151 offset:2048
	ds_read_b128 v[196:199], v151 offset:3072
	ds_read_b128 v[200:203], v151 offset:4096
	ds_read_b128 v[204:207], v151 offset:5120
	ds_read_b128 v[208:211], v151 offset:6144
	ds_read_b128 v[212:215], v151 offset:7168
	global_load_lds_dwordx4 v138, s[38:39]
	s_add_i32 m0, s37, 0xe000
	s_nop 0
	global_load_lds_dwordx4 v136, s[38:39]
	s_waitcnt vmcnt(8)
	s_waitcnt lgkmcnt(0)
	s_barrier
	s_setprio 1
	s_waitcnt lgkmcnt(0)
	v_mfma_f32_16x16x32_bf16 v[124:127], v[152:155], v[184:187], v[124:127]
	v_mfma_f32_16x16x32_bf16 v[120:123], v[160:163], v[184:187], v[120:123]
	v_mfma_f32_16x16x32_bf16 v[108:111], v[152:155], v[192:195], v[108:111]
	v_mfma_f32_16x16x32_bf16 v[104:107], v[160:163], v[192:195], v[104:107]
	v_mfma_f32_16x16x32_bf16 v[92:95], v[152:155], v[200:203], v[92:95]
	v_mfma_f32_16x16x32_bf16 v[88:91], v[160:163], v[200:203], v[88:91]
	v_mfma_f32_16x16x32_bf16 v[76:79], v[152:155], v[208:211], v[76:79]
	v_mfma_f32_16x16x32_bf16 v[72:75], v[160:163], v[208:211], v[72:75]
	v_mfma_f32_16x16x32_bf16 v[124:127], v[156:159], v[188:191], v[124:127]
	v_mfma_f32_16x16x32_bf16 v[120:123], v[164:167], v[188:191], v[120:123]
	v_mfma_f32_16x16x32_bf16 v[108:111], v[156:159], v[196:199], v[108:111]
	v_mfma_f32_16x16x32_bf16 v[104:107], v[164:167], v[196:199], v[104:107]
	v_mfma_f32_16x16x32_bf16 v[92:95], v[156:159], v[204:207], v[92:95]
	v_mfma_f32_16x16x32_bf16 v[88:91], v[164:167], v[204:207], v[88:91]
	v_mfma_f32_16x16x32_bf16 v[76:79], v[156:159], v[212:215], v[76:79]
	v_mfma_f32_16x16x32_bf16 v[72:75], v[164:167], v[212:215], v[72:75]
	s_setprio 0
	s_setprio 1
	v_mfma_f32_16x16x32_bf16 v[116:119], v[168:171], v[184:187], v[116:119]
	v_mfma_f32_16x16x32_bf16 v[112:115], v[176:179], v[184:187], v[112:115]
	v_mfma_f32_16x16x32_bf16 v[100:103], v[168:171], v[192:195], v[100:103]
	v_mfma_f32_16x16x32_bf16 v[96:99], v[176:179], v[192:195], v[96:99]
	v_mfma_f32_16x16x32_bf16 v[84:87], v[168:171], v[200:203], v[84:87]
	v_mfma_f32_16x16x32_bf16 v[80:83], v[176:179], v[200:203], v[80:83]
	v_mfma_f32_16x16x32_bf16 v[68:71], v[168:171], v[208:211], v[68:71]
	v_mfma_f32_16x16x32_bf16 v[64:67], v[176:179], v[208:211], v[64:67]
	v_mfma_f32_16x16x32_bf16 v[116:119], v[172:175], v[188:191], v[116:119]
	v_mfma_f32_16x16x32_bf16 v[112:115], v[180:183], v[188:191], v[112:115]
	v_mfma_f32_16x16x32_bf16 v[100:103], v[172:175], v[196:199], v[100:103]
	v_mfma_f32_16x16x32_bf16 v[96:99], v[180:183], v[196:199], v[96:99]
	v_mfma_f32_16x16x32_bf16 v[84:87], v[172:175], v[204:207], v[84:87]
	v_mfma_f32_16x16x32_bf16 v[80:83], v[180:183], v[204:207], v[80:83]
	v_mfma_f32_16x16x32_bf16 v[68:71], v[172:175], v[212:215], v[68:71]
	v_mfma_f32_16x16x32_bf16 v[64:67], v[180:183], v[212:215], v[64:67]
	s_setprio 0
	s_barrier
	s_add_i32 s67, s59, s49
	s_add_u32 s100, s42, 0x80
	s_addc_u32 s101, s43, 0
	s_mov_b32 m0, s67
	ds_read_b128 v[184:187], v151 offset:16384
	ds_read_b128 v[188:191], v151 offset:17408
	ds_read_b128 v[192:195], v151 offset:18432
	ds_read_b128 v[196:199], v151 offset:19456
	ds_read_b128 v[200:203], v151 offset:20480
	ds_read_b128 v[204:207], v151 offset:21504
	ds_read_b128 v[208:211], v151 offset:22528
	ds_read_b128 v[212:215], v151 offset:23552
	global_load_lds_dwordx4 v130, s[40:41]
	s_add_i32 m0, s67, 0x2000
	s_add_u32 s68, s40, 0x40000
	s_addc_u32 s69, s41, 0
	s_add_i32 s67, s60, s49
	global_load_lds_dwordx4 v134, s[40:41]
	s_mov_b32 m0, s67
	s_nop 0
	global_load_lds_dwordx4 v130, s[68:69]
	s_add_i32 m0, s67, 0x2000
	s_nop 0
	global_load_lds_dwordx4 v134, s[68:69]
	s_mov_b32 m0, s37
	s_nop 0
	global_load_lds_dwordx4 v128, s[42:43]
	s_mov_b32 m0, s50
	s_nop 0
	global_load_lds_dwordx4 v132, s[42:43]
	s_waitcnt vmcnt(8)
	s_waitcnt lgkmcnt(0)
	s_barrier
	s_setprio 1
	s_waitcnt lgkmcnt(0)
	v_mfma_f32_16x16x32_bf16 v[60:63], v[152:155], v[184:187], v[60:63]
	v_mfma_f32_16x16x32_bf16 v[56:59], v[160:163], v[184:187], v[56:59]
	v_mfma_f32_16x16x32_bf16 v[44:47], v[152:155], v[192:195], v[44:47]
	v_mfma_f32_16x16x32_bf16 v[40:43], v[160:163], v[192:195], v[40:43]
	v_mfma_f32_16x16x32_bf16 v[28:31], v[152:155], v[200:203], v[28:31]
	v_mfma_f32_16x16x32_bf16 v[24:27], v[160:163], v[200:203], v[24:27]
	v_mfma_f32_16x16x32_bf16 v[12:15], v[152:155], v[208:211], v[12:15]
	v_mfma_f32_16x16x32_bf16 v[8:11], v[160:163], v[208:211], v[8:11]
	v_mfma_f32_16x16x32_bf16 v[60:63], v[156:159], v[188:191], v[60:63]
	v_mfma_f32_16x16x32_bf16 v[56:59], v[164:167], v[188:191], v[56:59]
	v_mfma_f32_16x16x32_bf16 v[44:47], v[156:159], v[196:199], v[44:47]
	v_mfma_f32_16x16x32_bf16 v[40:43], v[164:167], v[196:199], v[40:43]
	v_mfma_f32_16x16x32_bf16 v[28:31], v[156:159], v[204:207], v[28:31]
	v_mfma_f32_16x16x32_bf16 v[24:27], v[164:167], v[204:207], v[24:27]
	v_mfma_f32_16x16x32_bf16 v[12:15], v[156:159], v[212:215], v[12:15]
	v_mfma_f32_16x16x32_bf16 v[8:11], v[164:167], v[212:215], v[8:11]
	s_setprio 0
	s_setprio 1
	v_mfma_f32_16x16x32_bf16 v[52:55], v[168:171], v[184:187], v[52:55]
	v_mfma_f32_16x16x32_bf16 v[48:51], v[176:179], v[184:187], v[48:51]
	v_mfma_f32_16x16x32_bf16 v[36:39], v[168:171], v[192:195], v[36:39]
	v_mfma_f32_16x16x32_bf16 v[32:35], v[176:179], v[192:195], v[32:35]
	v_mfma_f32_16x16x32_bf16 v[20:23], v[168:171], v[200:203], v[20:23]
	v_mfma_f32_16x16x32_bf16 v[16:19], v[176:179], v[200:203], v[16:19]
	v_mfma_f32_16x16x32_bf16 v[4:7], v[168:171], v[208:211], v[4:7]
	v_mfma_f32_16x16x32_bf16 v[0:3], v[176:179], v[208:211], v[0:3]
	v_mfma_f32_16x16x32_bf16 v[52:55], v[172:175], v[188:191], v[52:55]
	v_mfma_f32_16x16x32_bf16 v[48:51], v[180:183], v[188:191], v[48:51]
	v_mfma_f32_16x16x32_bf16 v[36:39], v[172:175], v[196:199], v[36:39]
	v_mfma_f32_16x16x32_bf16 v[32:35], v[180:183], v[196:199], v[32:35]
	v_mfma_f32_16x16x32_bf16 v[20:23], v[172:175], v[204:207], v[20:23]
	v_mfma_f32_16x16x32_bf16 v[16:19], v[180:183], v[204:207], v[16:19]
	v_mfma_f32_16x16x32_bf16 v[4:7], v[172:175], v[212:215], v[4:7]
	v_mfma_f32_16x16x32_bf16 v[0:3], v[180:183], v[212:215], v[0:3]
	s_setprio 0
	s_barrier
; #define PG8_STAGE(bufoff, gbase, voff) do { _Pragma("unroll") for (int _i = 0; _i < 2; ++_i) \
;         __builtin_amdgcn_global_load_lds((const unsigned*)((const char*)(gbase) + (voff)[_i]), (LAS unsigned*)(lds + (bufoff) + ldsw + _i * 8192), 16, 0, 0); } while (0)
; #define PG8_LDA(dst, b, h) do { _Pragma("unroll") for (int m = 0; m < 4; ++m) _Pragma("unroll") for (int k = 0; k < 2; ++k) dst[m][k] = *(const LAS bf16x8*)(lds + PG8_SA(b, h) + aoff + m * 2048 + k * 1024); } while (0)
; #define PG8_LDB(dst, b, h) do { _Pragma("unroll") for (int n = 0; n < 2; ++n) _Pragma("unroll") for (int k = 0; k < 2; ++k) dst[n][k] = *(const LAS bf16x8*)(lds + PG8_SB(b, h) + boff + n * 2048 + k * 1024); } while (0)
; #define PG8_MMA(ai, bj, At, Bt) do { __builtin_amdgcn_s_setprio(1); _Pragma("unroll") for (int m = 0; m < 4; ++m) _Pragma("unroll") for (int n = 0; n < 2; ++n) _Pragma("unroll") for (int k = 0; k < 2; ++k) \
;         acc[ai][bj][m][n] = __builtin_amdgcn_mfma_f32_16x16x32_bf16(Bt[n][k], At[m][k], acc[ai][bj][m][n], 0, 0, 0); __builtin_amdgcn_s_setprio(0); } while (0)
; #define PG8_WAIT_V(n) asm volatile("s_waitcnt vmcnt(" #n ")" ::: "memory")
; #define PG8_WAIT_L(n) asm volatile("s_waitcnt lgkmcnt(" #n ")" ::: "memory")
; #define PG8_BAR __builtin_amdgcn_s_barrier()
; #define PG8_SCHED __builtin_amdgcn_sched_barrier(0)
; template <class Epi>
; __device__ __forceinline__ void gemm_phase(ldsp lds, const Gemm g, const StaticOrder& S, const Epi& E, int wave0) {
;     ...
;             PG8_LDB(B0, 1, 0); PG8_LDB(B1, 1, 1); PG8_SCHED; PG8_LDA(At, 1, 0); PG8_STAGE(PG8_SA(0, 1), a2 + hstep, voffA);
;             PG8_WAIT_V(8); PG8_WAIT_L(0); PG8_BAR; PG8_MMA(0, 0, At, B0); PG8_MMA(0, 1, At, B1); PG8_BAR; PG8_SCHED;
;             PG8_LDA(At, 1, 1); PG8_STAGE(PG8_SB(1, 0), b3, voffB); PG8_STAGE(PG8_SB(1, 1), b3 + hstep, voffB); PG8_STAGE(PG8_SA(1, 0), a3, voffA);
;             PG8_WAIT_V(8); PG8_WAIT_L(0); PG8_BAR; PG8_MMA(1, 0, At, B0); PG8_MMA(1, 1, At, B1); PG8_BAR; PG8_SCHED;
;         }
;         if (wr == 0) PG8_BAR;
	s_add_i32 s67, 0, 0x18000
	s_add_i32 s68, 0, 0x1c000
	v_add_u32_e32 v164, s67, v148
	v_add_u32_e32 v180, s68, v148
	ds_read_b128 v[152:155], v164
	ds_read_b128 v[156:159], v164 offset:1024
	ds_read_b128 v[160:163], v164 offset:2048
	ds_read_b128 v[164:167], v164 offset:3072
	ds_read_b128 v[168:171], v180
	ds_read_b128 v[172:175], v180 offset:1024
	ds_read_b128 v[176:179], v180 offset:2048
	ds_read_b128 v[180:183], v180 offset:3072
	s_add_u32 s42, s42, 0x40000
	s_addc_u32 s43, s43, 0
	s_mov_b32 m0, s51
	ds_read_b128 v[184:187], v151 offset:32768
	ds_read_b128 v[188:191], v151 offset:33792
	ds_read_b128 v[192:195], v151 offset:34816
	ds_read_b128 v[196:199], v151 offset:35840
	ds_read_b128 v[200:203], v151 offset:36864
	ds_read_b128 v[204:207], v151 offset:37888
	ds_read_b128 v[208:211], v151 offset:38912
	ds_read_b128 v[212:215], v151 offset:39936
	global_load_lds_dwordx4 v128, s[42:43]
	s_mov_b32 m0, s52
	s_nop 0
	global_load_lds_dwordx4 v132, s[42:43]
	s_waitcnt vmcnt(8)
	s_waitcnt lgkmcnt(0)
	s_barrier
	s_setprio 1
	s_waitcnt lgkmcnt(0)
	v_mfma_f32_16x16x32_bf16 v[124:127], v[152:155], v[184:187], v[124:127]
	v_mfma_f32_16x16x32_bf16 v[120:123], v[160:163], v[184:187], v[120:123]
	v_mfma_f32_16x16x32_bf16 v[108:111], v[152:155], v[192:195], v[108:111]
	v_mfma_f32_16x16x32_bf16 v[104:107], v[160:163], v[192:195], v[104:107]
	v_mfma_f32_16x16x32_bf16 v[92:95], v[152:155], v[200:203], v[92:95]
	v_mfma_f32_16x16x32_bf16 v[88:91], v[160:163], v[200:203], v[88:91]
	v_mfma_f32_16x16x32_bf16 v[76:79], v[152:155], v[208:211], v[76:79]
	v_mfma_f32_16x16x32_bf16 v[72:75], v[160:163], v[208:211], v[72:75]
	v_mfma_f32_16x16x32_bf16 v[124:127], v[156:159], v[188:191], v[124:127]
	v_mfma_f32_16x16x32_bf16 v[120:123], v[164:167], v[188:191], v[120:123]
	v_mfma_f32_16x16x32_bf16 v[108:111], v[156:159], v[196:199], v[108:111]
	v_mfma_f32_16x16x32_bf16 v[104:107], v[164:167], v[196:199], v[104:107]
	v_mfma_f32_16x16x32_bf16 v[92:95], v[156:159], v[204:207], v[92:95]
	v_mfma_f32_16x16x32_bf16 v[88:91], v[164:167], v[204:207], v[88:91]
	v_mfma_f32_16x16x32_bf16 v[76:79], v[156:159], v[212:215], v[76:79]
	v_mfma_f32_16x16x32_bf16 v[72:75], v[164:167], v[212:215], v[72:75]
	s_setprio 0
	s_setprio 1
	v_mfma_f32_16x16x32_bf16 v[116:119], v[168:171], v[184:187], v[116:119]
	v_mfma_f32_16x16x32_bf16 v[112:115], v[176:179], v[184:187], v[112:115]
	v_mfma_f32_16x16x32_bf16 v[100:103], v[168:171], v[192:195], v[100:103]
	v_mfma_f32_16x16x32_bf16 v[96:99], v[176:179], v[192:195], v[96:99]
	v_mfma_f32_16x16x32_bf16 v[84:87], v[168:171], v[200:203], v[84:87]
	v_mfma_f32_16x16x32_bf16 v[80:83], v[176:179], v[200:203], v[80:83]
	v_mfma_f32_16x16x32_bf16 v[68:71], v[168:171], v[208:211], v[68:71]
	v_mfma_f32_16x16x32_bf16 v[64:67], v[176:179], v[208:211], v[64:67]
	v_mfma_f32_16x16x32_bf16 v[116:119], v[172:175], v[188:191], v[116:119]
	v_mfma_f32_16x16x32_bf16 v[112:115], v[180:183], v[188:191], v[112:115]
	v_mfma_f32_16x16x32_bf16 v[100:103], v[172:175], v[196:199], v[100:103]
	v_mfma_f32_16x16x32_bf16 v[96:99], v[180:183], v[196:199], v[96:99]
	v_mfma_f32_16x16x32_bf16 v[84:87], v[172:175], v[204:207], v[84:87]
	v_mfma_f32_16x16x32_bf16 v[80:83], v[180:183], v[204:207], v[80:83]
	v_mfma_f32_16x16x32_bf16 v[68:71], v[172:175], v[212:215], v[68:71]
	v_mfma_f32_16x16x32_bf16 v[64:67], v[180:183], v[212:215], v[64:67]
	s_setprio 0
	s_barrier
	s_add_i32 s42, s67, s49
	s_add_u32 s40, s40, 0x80
	s_addc_u32 s41, s41, 0
	s_mov_b32 m0, s42
	ds_read_b128 v[184:187], v151 offset:49152
	ds_read_b128 v[188:191], v151 offset:50176
	ds_read_b128 v[192:195], v151 offset:51200
	ds_read_b128 v[196:199], v151 offset:52224
	ds_read_b128 v[200:203], v151 offset:53248
	ds_read_b128 v[204:207], v151 offset:54272
	ds_read_b128 v[208:211], v151 offset:55296
	ds_read_b128 v[212:215], v151 offset:56320
	global_load_lds_dwordx4 v130, s[40:41]
	s_add_i32 m0, s42, 0x2000
	s_add_i32 s42, s68, s49
	global_load_lds_dwordx4 v134, s[40:41]
	s_add_u32 s40, s40, 0x40000
	s_addc_u32 s41, s41, 0
	s_mov_b32 m0, s42
	s_nop 0
	global_load_lds_dwordx4 v130, s[40:41]
	s_add_i32 m0, s42, 0x2000
	s_nop 0
	global_load_lds_dwordx4 v134, s[40:41]
	s_mov_b32 m0, s56
	s_nop 0
	global_load_lds_dwordx4 v128, s[100:101]
	s_mov_b32 m0, s57
	s_nop 0
	global_load_lds_dwordx4 v132, s[100:101]
	s_waitcnt vmcnt(8)
	s_waitcnt lgkmcnt(0)
	s_barrier
	s_setprio 1
	s_waitcnt lgkmcnt(0)
	v_mfma_f32_16x16x32_bf16 v[60:63], v[152:155], v[184:187], v[60:63]
	v_mfma_f32_16x16x32_bf16 v[56:59], v[160:163], v[184:187], v[56:59]
	v_mfma_f32_16x16x32_bf16 v[44:47], v[152:155], v[192:195], v[44:47]
	v_mfma_f32_16x16x32_bf16 v[40:43], v[160:163], v[192:195], v[40:43]
	v_mfma_f32_16x16x32_bf16 v[28:31], v[152:155], v[200:203], v[28:31]
	v_mfma_f32_16x16x32_bf16 v[24:27], v[160:163], v[200:203], v[24:27]
	v_mfma_f32_16x16x32_bf16 v[12:15], v[152:155], v[208:211], v[12:15]
	v_mfma_f32_16x16x32_bf16 v[8:11], v[160:163], v[208:211], v[8:11]
	v_mfma_f32_16x16x32_bf16 v[60:63], v[156:159], v[188:191], v[60:63]
	v_mfma_f32_16x16x32_bf16 v[56:59], v[164:167], v[188:191], v[56:59]
	v_mfma_f32_16x16x32_bf16 v[44:47], v[156:159], v[196:199], v[44:47]
	v_mfma_f32_16x16x32_bf16 v[40:43], v[164:167], v[196:199], v[40:43]
	v_mfma_f32_16x16x32_bf16 v[28:31], v[156:159], v[204:207], v[28:31]
	v_mfma_f32_16x16x32_bf16 v[24:27], v[164:167], v[204:207], v[24:27]
	v_mfma_f32_16x16x32_bf16 v[12:15], v[156:159], v[212:215], v[12:15]
	v_mfma_f32_16x16x32_bf16 v[8:11], v[164:167], v[212:215], v[8:11]
	s_setprio 0
	s_setprio 1
	v_mfma_f32_16x16x32_bf16 v[52:55], v[168:171], v[184:187], v[52:55]
	v_mfma_f32_16x16x32_bf16 v[48:51], v[176:179], v[184:187], v[48:51]
	v_mfma_f32_16x16x32_bf16 v[36:39], v[168:171], v[192:195], v[36:39]
	v_mfma_f32_16x16x32_bf16 v[32:35], v[176:179], v[192:195], v[32:35]
	v_mfma_f32_16x16x32_bf16 v[20:23], v[168:171], v[200:203], v[20:23]
	v_mfma_f32_16x16x32_bf16 v[16:19], v[176:179], v[200:203], v[16:19]
	v_mfma_f32_16x16x32_bf16 v[4:7], v[168:171], v[208:211], v[4:7]
	v_mfma_f32_16x16x32_bf16 v[0:3], v[176:179], v[208:211], v[0:3]
	v_mfma_f32_16x16x32_bf16 v[52:55], v[172:175], v[188:191], v[52:55]
	v_mfma_f32_16x16x32_bf16 v[48:51], v[180:183], v[188:191], v[48:51]
	v_mfma_f32_16x16x32_bf16 v[36:39], v[172:175], v[196:199], v[36:39]
	v_mfma_f32_16x16x32_bf16 v[32:35], v[180:183], v[196:199], v[32:35]
	v_mfma_f32_16x16x32_bf16 v[20:23], v[172:175], v[204:207], v[20:23]
	v_mfma_f32_16x16x32_bf16 v[16:19], v[180:183], v[204:207], v[16:19]
	v_mfma_f32_16x16x32_bf16 v[4:7], v[172:175], v[212:215], v[4:7]
	v_mfma_f32_16x16x32_bf16 v[0:3], v[180:183], v[212:215], v[0:3]
	s_setprio 0
	s_barrier
	s_add_i32 s66, s66, 2
	s_add_u32 s64, s64, 0x100
	s_addc_u32 s65, s65, 0
	s_add_u32 s38, s38, 0x100
	s_addc_u32 s39, s39, 0
	s_cmp_gt_u32 s66, 13
	s_cbranch_scc0 .LBB0_713
	s_and_b64 vcc, exec, s[10:11]
	s_cbranch_vccz .LBB0_716
	s_barrier

; #define PG8_STAGE(bufoff, gbase, voff) do { _Pragma("unroll") for (int _i = 0; _i < 2; ++_i) \
;         __builtin_amdgcn_global_load_lds((const unsigned*)((const char*)(gbase) + (voff)[_i]), (LAS unsigned*)(lds + (bufoff) + ldsw + _i * 8192), 16, 0, 0); } while (0)
; #define PG8_LDA(dst, b, h) do { _Pragma("unroll") for (int m = 0; m < 4; ++m) _Pragma("unroll") for (int k = 0; k < 2; ++k) dst[m][k] = *(const LAS bf16x8*)(lds + PG8_SA(b, h) + aoff + m * 2048 + k * 1024); } while (0)
; #define PG8_LDB(dst, b, h) do { _Pragma("unroll") for (int n = 0; n < 2; ++n) _Pragma("unroll") for (int k = 0; k < 2; ++k) dst[n][k] = *(const LAS bf16x8*)(lds + PG8_SB(b, h) + boff + n * 2048 + k * 1024); } while (0)
; #define PG8_MMA(ai, bj, At, Bt) do { __builtin_amdgcn_s_setprio(1); _Pragma("unroll") for (int m = 0; m < 4; ++m) _Pragma("unroll") for (int n = 0; n < 2; ++n) _Pragma("unroll") for (int k = 0; k < 2; ++k) \
;         acc[ai][bj][m][n] = __builtin_amdgcn_mfma_f32_16x16x32_bf16(Bt[n][k], At[m][k], acc[ai][bj][m][n], 0, 0, 0); __builtin_amdgcn_s_setprio(0); } while (0)
; #define PG8_WAIT_V(n) asm volatile("s_waitcnt vmcnt(" #n ")" ::: "memory")
; #define PG8_WAIT_L(n) asm volatile("s_waitcnt lgkmcnt(" #n ")" ::: "memory")
; #define PG8_BAR __builtin_amdgcn_s_barrier()
; #define PG8_SCHED __builtin_amdgcn_sched_barrier(0)
; template <class Epi>
; __device__ __forceinline__ void gemm_phase(ldsp lds, const Gemm g, const StaticOrder& S, const Epi& E, int wave0) {
;     ...
;             const char* a1 = cA + (size_t)(t + 1) * kstep;
;             const char* a2 = last ? nA : cA + (size_t)(t + 2) * kstep; const char* b2 = last ? nB : cB + (size_t)(t + 2) * kstep;
;             const char* a3 = a2 + kstep; const char* b3 = b2 + kstep;
;             PG8_LDB(B0, 0, 0); PG8_LDB(B1, 0, 1); PG8_SCHED; PG8_LDA(At, 0, 0); PG8_STAGE(PG8_SA(1, 1), a1 + hstep, voffA);
;             PG8_WAIT_V(8); PG8_WAIT_L(0); PG8_BAR; PG8_MMA(0, 0, At, B0); PG8_MMA(0, 1, At, B1); PG8_BAR; PG8_SCHED;
;             PG8_LDA(At, 0, 1); PG8_STAGE(PG8_SB(0, 0), b2, voffB); PG8_STAGE(PG8_SB(0, 1), b2 + hstep, voffB); PG8_STAGE(PG8_SA(0, 0), a2, voffA);
;             PG8_WAIT_V(8); PG8_WAIT_L(0); PG8_BAR; PG8_MMA(1, 0, At, B0); PG8_MMA(1, 1, At, B1); PG8_BAR; PG8_SCHED;
.LBB0_781:
	ds_read_b128 v[152:155], v149
	ds_read_b128 v[156:159], v149 offset:1024
	ds_read_b128 v[160:163], v149 offset:2048
	ds_read_b128 v[164:167], v149 offset:3072
	ds_read_b128 v[168:171], v150
	ds_read_b128 v[172:175], v150 offset:1024
	ds_read_b128 v[176:179], v150 offset:2048
	ds_read_b128 v[180:183], v150 offset:3072
	s_add_u32 s42, s40, 0xfff80080
	s_addc_u32 s43, s41, -1
	s_cmp_eq_u32 s69, 28
	s_cselect_b32 s45, s31, s43
	s_cselect_b32 s44, s65, s42
	s_cselect_b32 s43, s29, s68
	s_cselect_b32 s42, s66, s67
	s_add_i32 m0, s39, 0xc000
	ds_read_b128 v[184:187], v151
	ds_read_b128 v[188:191], v151 offset:1024
	ds_read_b128 v[192:195], v151 offset:2048
	ds_read_b128 v[196:199], v151 offset:3072
	ds_read_b128 v[200:203], v151 offset:4096
	ds_read_b128 v[204:207], v151 offset:5120
	ds_read_b128 v[208:211], v151 offset:6144
	ds_read_b128 v[212:215], v151 offset:7168
	global_load_lds_dwordx4 v138, s[40:41]
	s_add_i32 m0, s39, 0xe000
	s_nop 0
	global_load_lds_dwordx4 v136, s[40:41]
	s_waitcnt vmcnt(8)
	s_waitcnt lgkmcnt(0)
	s_barrier
	s_setprio 1
	s_waitcnt lgkmcnt(0)
	v_mfma_f32_16x16x32_bf16 v[124:127], v[152:155], v[184:187], v[124:127]
	v_mfma_f32_16x16x32_bf16 v[120:123], v[160:163], v[184:187], v[120:123]
	v_mfma_f32_16x16x32_bf16 v[108:111], v[152:155], v[192:195], v[108:111]
	v_mfma_f32_16x16x32_bf16 v[104:107], v[160:163], v[192:195], v[104:107]
	v_mfma_f32_16x16x32_bf16 v[92:95], v[152:155], v[200:203], v[92:95]
	v_mfma_f32_16x16x32_bf16 v[88:91], v[160:163], v[200:203], v[88:91]
	v_mfma_f32_16x16x32_bf16 v[76:79], v[152:155], v[208:211], v[76:79]
	v_mfma_f32_16x16x32_bf16 v[72:75], v[160:163], v[208:211], v[72:75]
	v_mfma_f32_16x16x32_bf16 v[124:127], v[156:159], v[188:191], v[124:127]
	v_mfma_f32_16x16x32_bf16 v[120:123], v[164:167], v[188:191], v[120:123]
	v_mfma_f32_16x16x32_bf16 v[108:111], v[156:159], v[196:199], v[108:111]
	v_mfma_f32_16x16x32_bf16 v[104:107], v[164:167], v[196:199], v[104:107]
	v_mfma_f32_16x16x32_bf16 v[92:95], v[156:159], v[204:207], v[92:95]
	v_mfma_f32_16x16x32_bf16 v[88:91], v[164:167], v[204:207], v[88:91]
	v_mfma_f32_16x16x32_bf16 v[76:79], v[156:159], v[212:215], v[76:79]
	v_mfma_f32_16x16x32_bf16 v[72:75], v[164:167], v[212:215], v[72:75]
	s_setprio 0
	s_setprio 1
	v_mfma_f32_16x16x32_bf16 v[116:119], v[168:171], v[184:187], v[116:119]
	v_mfma_f32_16x16x32_bf16 v[112:115], v[176:179], v[184:187], v[112:115]
	v_mfma_f32_16x16x32_bf16 v[100:103], v[168:171], v[192:195], v[100:103]
	v_mfma_f32_16x16x32_bf16 v[96:99], v[176:179], v[192:195], v[96:99]
	v_mfma_f32_16x16x32_bf16 v[84:87], v[168:171], v[200:203], v[84:87]
	v_mfma_f32_16x16x32_bf16 v[80:83], v[176:179], v[200:203], v[80:83]
	v_mfma_f32_16x16x32_bf16 v[68:71], v[168:171], v[208:211], v[68:71]
	v_mfma_f32_16x16x32_bf16 v[64:67], v[176:179], v[208:211], v[64:67]
	v_mfma_f32_16x16x32_bf16 v[116:119], v[172:175], v[188:191], v[116:119]
	v_mfma_f32_16x16x32_bf16 v[112:115], v[180:183], v[188:191], v[112:115]
	v_mfma_f32_16x16x32_bf16 v[100:103], v[172:175], v[196:199], v[100:103]
	v_mfma_f32_16x16x32_bf16 v[96:99], v[180:183], v[196:199], v[96:99]
	v_mfma_f32_16x16x32_bf16 v[84:87], v[172:175], v[204:207], v[84:87]
	v_mfma_f32_16x16x32_bf16 v[80:83], v[180:183], v[204:207], v[80:83]
	v_mfma_f32_16x16x32_bf16 v[68:71], v[172:175], v[212:215], v[68:71]
	v_mfma_f32_16x16x32_bf16 v[64:67], v[180:183], v[212:215], v[64:67]
	s_setprio 0
	s_barrier
	s_add_i32 s70, s62, s52
	s_add_u32 s100, s44, 0x80
	s_addc_u32 s101, s45, 0
	s_mov_b32 m0, s70
	ds_read_b128 v[184:187], v151 offset:16384
	ds_read_b128 v[188:191], v151 offset:17408
	ds_read_b128 v[192:195], v151 offset:18432
	ds_read_b128 v[196:199], v151 offset:19456
	ds_read_b128 v[200:203], v151 offset:20480
	ds_read_b128 v[204:207], v151 offset:21504
	ds_read_b128 v[208:211], v151 offset:22528
	ds_read_b128 v[212:215], v151 offset:23552
	global_load_lds_dwordx4 v130, s[42:43]
	s_add_i32 m0, s70, 0x2000
	s_add_u32 s70, s42, 0x80000
	s_addc_u32 s71, s43, 0
	s_add_i32 s72, s63, s52
	global_load_lds_dwordx4 v134, s[42:43]
	s_mov_b32 m0, s72
	s_nop 0
	global_load_lds_dwordx4 v130, s[70:71]
	s_add_i32 m0, s72, 0x2000
	s_nop 0
	global_load_lds_dwordx4 v134, s[70:71]
	s_mov_b32 m0, s39
	s_nop 0
	global_load_lds_dwordx4 v128, s[44:45]
	s_mov_b32 m0, s53
	s_nop 0
	global_load_lds_dwordx4 v132, s[44:45]
	s_waitcnt vmcnt(8)
	s_waitcnt lgkmcnt(0)
	s_barrier
	s_setprio 1
	s_waitcnt lgkmcnt(0)
	v_mfma_f32_16x16x32_bf16 v[60:63], v[152:155], v[184:187], v[60:63]
	v_mfma_f32_16x16x32_bf16 v[56:59], v[160:163], v[184:187], v[56:59]
	v_mfma_f32_16x16x32_bf16 v[44:47], v[152:155], v[192:195], v[44:47]
	v_mfma_f32_16x16x32_bf16 v[40:43], v[160:163], v[192:195], v[40:43]
	v_mfma_f32_16x16x32_bf16 v[28:31], v[152:155], v[200:203], v[28:31]
	v_mfma_f32_16x16x32_bf16 v[24:27], v[160:163], v[200:203], v[24:27]
	v_mfma_f32_16x16x32_bf16 v[12:15], v[152:155], v[208:211], v[12:15]
	v_mfma_f32_16x16x32_bf16 v[8:11], v[160:163], v[208:211], v[8:11]
	v_mfma_f32_16x16x32_bf16 v[60:63], v[156:159], v[188:191], v[60:63]
	v_mfma_f32_16x16x32_bf16 v[56:59], v[164:167], v[188:191], v[56:59]
	v_mfma_f32_16x16x32_bf16 v[44:47], v[156:159], v[196:199], v[44:47]
	v_mfma_f32_16x16x32_bf16 v[40:43], v[164:167], v[196:199], v[40:43]
	v_mfma_f32_16x16x32_bf16 v[28:31], v[156:159], v[204:207], v[28:31]
	v_mfma_f32_16x16x32_bf16 v[24:27], v[164:167], v[204:207], v[24:27]
	v_mfma_f32_16x16x32_bf16 v[12:15], v[156:159], v[212:215], v[12:15]
	v_mfma_f32_16x16x32_bf16 v[8:11], v[164:167], v[212:215], v[8:11]
	s_setprio 0
	s_setprio 1
	v_mfma_f32_16x16x32_bf16 v[52:55], v[168:171], v[184:187], v[52:55]
	v_mfma_f32_16x16x32_bf16 v[48:51], v[176:179], v[184:187], v[48:51]
	v_mfma_f32_16x16x32_bf16 v[36:39], v[168:171], v[192:195], v[36:39]
	v_mfma_f32_16x16x32_bf16 v[32:35], v[176:179], v[192:195], v[32:35]
	v_mfma_f32_16x16x32_bf16 v[20:23], v[168:171], v[200:203], v[20:23]
	v_mfma_f32_16x16x32_bf16 v[16:19], v[176:179], v[200:203], v[16:19]
	v_mfma_f32_16x16x32_bf16 v[4:7], v[168:171], v[208:211], v[4:7]
	v_mfma_f32_16x16x32_bf16 v[0:3], v[176:179], v[208:211], v[0:3]
	v_mfma_f32_16x16x32_bf16 v[52:55], v[172:175], v[188:191], v[52:55]
	v_mfma_f32_16x16x32_bf16 v[48:51], v[180:183], v[188:191], v[48:51]
	v_mfma_f32_16x16x32_bf16 v[36:39], v[172:175], v[196:199], v[36:39]
	v_mfma_f32_16x16x32_bf16 v[32:35], v[180:183], v[196:199], v[32:35]
	v_mfma_f32_16x16x32_bf16 v[20:23], v[172:175], v[204:207], v[20:23]
	v_mfma_f32_16x16x32_bf16 v[16:19], v[180:183], v[204:207], v[16:19]
	v_mfma_f32_16x16x32_bf16 v[4:7], v[172:175], v[212:215], v[4:7]
	v_mfma_f32_16x16x32_bf16 v[0:3], v[180:183], v[212:215], v[0:3]
	s_setprio 0
	s_barrier
; #define PG8_STAGE(bufoff, gbase, voff) do { _Pragma("unroll") for (int _i = 0; _i < 2; ++_i) \
;         __builtin_amdgcn_global_load_lds((const unsigned*)((const char*)(gbase) + (voff)[_i]), (LAS unsigned*)(lds + (bufoff) + ldsw + _i * 8192), 16, 0, 0); } while (0)
; #define PG8_LDA(dst, b, h) do { _Pragma("unroll") for (int m = 0; m < 4; ++m) _Pragma("unroll") for (int k = 0; k < 2; ++k) dst[m][k] = *(const LAS bf16x8*)(lds + PG8_SA(b, h) + aoff + m * 2048 + k * 1024); } while (0)
; #define PG8_LDB(dst, b, h) do { _Pragma("unroll") for (int n = 0; n < 2; ++n) _Pragma("unroll") for (int k = 0; k < 2; ++k) dst[n][k] = *(const LAS bf16x8*)(lds + PG8_SB(b, h) + boff + n * 2048 + k * 1024); } while (0)
; #define PG8_MMA(ai, bj, At, Bt) do { __builtin_amdgcn_s_setprio(1); _Pragma("unroll") for (int m = 0; m < 4; ++m) _Pragma("unroll") for (int n = 0; n < 2; ++n) _Pragma("unroll") for (int k = 0; k < 2; ++k) \
;         acc[ai][bj][m][n] = __builtin_amdgcn_mfma_f32_16x16x32_bf16(Bt[n][k], At[m][k], acc[ai][bj][m][n], 0, 0, 0); __builtin_amdgcn_s_setprio(0); } while (0)
; #define PG8_WAIT_V(n) asm volatile("s_waitcnt vmcnt(" #n ")" ::: "memory")
; #define PG8_WAIT_L(n) asm volatile("s_waitcnt lgkmcnt(" #n ")" ::: "memory")
; #define PG8_BAR __builtin_amdgcn_s_barrier()
; #define PG8_SCHED __builtin_amdgcn_sched_barrier(0)
; template <class Epi>
; __device__ __forceinline__ void gemm_phase(ldsp lds, const Gemm g, const StaticOrder& S, const Epi& E, int wave0) {
;     ...
;             PG8_LDB(B0, 1, 0); PG8_LDB(B1, 1, 1); PG8_SCHED; PG8_LDA(At, 1, 0); PG8_STAGE(PG8_SA(0, 1), a2 + hstep, voffA);
;             PG8_WAIT_V(8); PG8_WAIT_L(0); PG8_BAR; PG8_MMA(0, 0, At, B0); PG8_MMA(0, 1, At, B1); PG8_BAR; PG8_SCHED;
;             PG8_LDA(At, 1, 1); PG8_STAGE(PG8_SB(1, 0), b3, voffB); PG8_STAGE(PG8_SB(1, 1), b3 + hstep, voffB); PG8_STAGE(PG8_SA(1, 0), a3, voffA);
;             PG8_WAIT_V(8); PG8_WAIT_L(0); PG8_BAR; PG8_MMA(1, 0, At, B0); PG8_MMA(1, 1, At, B1); PG8_BAR; PG8_SCHED;
;         }
;         if (wr == 0) PG8_BAR;
	s_add_i32 s70, 0, 0x18000
	s_add_i32 s71, 0, 0x1c000
	v_add_u32_e32 v164, s70, v148
	v_add_u32_e32 v180, s71, v148
	ds_read_b128 v[152:155], v164
	ds_read_b128 v[156:159], v164 offset:1024
	ds_read_b128 v[160:163], v164 offset:2048
	ds_read_b128 v[164:167], v164 offset:3072
	ds_read_b128 v[168:171], v180
	ds_read_b128 v[172:175], v180 offset:1024
	ds_read_b128 v[176:179], v180 offset:2048
	ds_read_b128 v[180:183], v180 offset:3072
	s_add_u32 s44, s44, 0x80000
	s_addc_u32 s45, s45, 0
	s_mov_b32 m0, s54
	ds_read_b128 v[184:187], v151 offset:32768
	ds_read_b128 v[188:191], v151 offset:33792
	ds_read_b128 v[192:195], v151 offset:34816
	ds_read_b128 v[196:199], v151 offset:35840
	ds_read_b128 v[200:203], v151 offset:36864
	ds_read_b128 v[204:207], v151 offset:37888
	ds_read_b128 v[208:211], v151 offset:38912
	ds_read_b128 v[212:215], v151 offset:39936
	global_load_lds_dwordx4 v128, s[44:45]
	s_mov_b32 m0, s55
	s_nop 0
	global_load_lds_dwordx4 v132, s[44:45]
	s_waitcnt vmcnt(8)
	s_waitcnt lgkmcnt(0)
	s_barrier
	s_setprio 1
	s_waitcnt lgkmcnt(0)
	v_mfma_f32_16x16x32_bf16 v[124:127], v[152:155], v[184:187], v[124:127]
	v_mfma_f32_16x16x32_bf16 v[120:123], v[160:163], v[184:187], v[120:123]
	v_mfma_f32_16x16x32_bf16 v[108:111], v[152:155], v[192:195], v[108:111]
	v_mfma_f32_16x16x32_bf16 v[104:107], v[160:163], v[192:195], v[104:107]
	v_mfma_f32_16x16x32_bf16 v[92:95], v[152:155], v[200:203], v[92:95]
	v_mfma_f32_16x16x32_bf16 v[88:91], v[160:163], v[200:203], v[88:91]
	v_mfma_f32_16x16x32_bf16 v[76:79], v[152:155], v[208:211], v[76:79]
	v_mfma_f32_16x16x32_bf16 v[72:75], v[160:163], v[208:211], v[72:75]
	v_mfma_f32_16x16x32_bf16 v[124:127], v[156:159], v[188:191], v[124:127]
	v_mfma_f32_16x16x32_bf16 v[120:123], v[164:167], v[188:191], v[120:123]
	v_mfma_f32_16x16x32_bf16 v[108:111], v[156:159], v[196:199], v[108:111]
	v_mfma_f32_16x16x32_bf16 v[104:107], v[164:167], v[196:199], v[104:107]
	v_mfma_f32_16x16x32_bf16 v[92:95], v[156:159], v[204:207], v[92:95]
	v_mfma_f32_16x16x32_bf16 v[88:91], v[164:167], v[204:207], v[88:91]
	v_mfma_f32_16x16x32_bf16 v[76:79], v[156:159], v[212:215], v[76:79]
	v_mfma_f32_16x16x32_bf16 v[72:75], v[164:167], v[212:215], v[72:75]
	s_setprio 0
	s_setprio 1
	v_mfma_f32_16x16x32_bf16 v[116:119], v[168:171], v[184:187], v[116:119]
	v_mfma_f32_16x16x32_bf16 v[112:115], v[176:179], v[184:187], v[112:115]
	v_mfma_f32_16x16x32_bf16 v[100:103], v[168:171], v[192:195], v[100:103]
	v_mfma_f32_16x16x32_bf16 v[96:99], v[176:179], v[192:195], v[96:99]
	v_mfma_f32_16x16x32_bf16 v[84:87], v[168:171], v[200:203], v[84:87]
	v_mfma_f32_16x16x32_bf16 v[80:83], v[176:179], v[200:203], v[80:83]
	v_mfma_f32_16x16x32_bf16 v[68:71], v[168:171], v[208:211], v[68:71]
	v_mfma_f32_16x16x32_bf16 v[64:67], v[176:179], v[208:211], v[64:67]
	v_mfma_f32_16x16x32_bf16 v[116:119], v[172:175], v[188:191], v[116:119]
	v_mfma_f32_16x16x32_bf16 v[112:115], v[180:183], v[188:191], v[112:115]
	v_mfma_f32_16x16x32_bf16 v[100:103], v[172:175], v[196:199], v[100:103]
	v_mfma_f32_16x16x32_bf16 v[96:99], v[180:183], v[196:199], v[96:99]
	v_mfma_f32_16x16x32_bf16 v[84:87], v[172:175], v[204:207], v[84:87]
	v_mfma_f32_16x16x32_bf16 v[80:83], v[180:183], v[204:207], v[80:83]
	v_mfma_f32_16x16x32_bf16 v[68:71], v[172:175], v[212:215], v[68:71]
	v_mfma_f32_16x16x32_bf16 v[64:67], v[180:183], v[212:215], v[64:67]
	s_setprio 0
	s_barrier
	s_add_i32 s44, s70, s52
	s_add_u32 s42, s42, 0x80
	s_addc_u32 s43, s43, 0
	s_mov_b32 m0, s44
	ds_read_b128 v[184:187], v151 offset:49152
	ds_read_b128 v[188:191], v151 offset:50176
	ds_read_b128 v[192:195], v151 offset:51200
	ds_read_b128 v[196:199], v151 offset:52224
	ds_read_b128 v[200:203], v151 offset:53248
	ds_read_b128 v[204:207], v151 offset:54272
	ds_read_b128 v[208:211], v151 offset:55296
	ds_read_b128 v[212:215], v151 offset:56320
	global_load_lds_dwordx4 v130, s[42:43]
	s_add_i32 m0, s44, 0x2000
	s_add_i32 s44, s71, s52
	global_load_lds_dwordx4 v134, s[42:43]
	s_add_u32 s42, s42, 0x80000
	s_addc_u32 s43, s43, 0
	s_mov_b32 m0, s44
	s_nop 0
	global_load_lds_dwordx4 v130, s[42:43]
	s_add_i32 m0, s44, 0x2000
	s_nop 0
	global_load_lds_dwordx4 v134, s[42:43]
	s_mov_b32 m0, s59
	s_nop 0
	global_load_lds_dwordx4 v128, s[100:101]
	s_mov_b32 m0, s60
	s_nop 0
	global_load_lds_dwordx4 v132, s[100:101]
	s_waitcnt vmcnt(8)
	s_waitcnt lgkmcnt(0)
	s_barrier
	s_setprio 1
	s_waitcnt lgkmcnt(0)
	v_mfma_f32_16x16x32_bf16 v[60:63], v[152:155], v[184:187], v[60:63]
	v_mfma_f32_16x16x32_bf16 v[56:59], v[160:163], v[184:187], v[56:59]
	v_mfma_f32_16x16x32_bf16 v[44:47], v[152:155], v[192:195], v[44:47]
	v_mfma_f32_16x16x32_bf16 v[40:43], v[160:163], v[192:195], v[40:43]
	v_mfma_f32_16x16x32_bf16 v[28:31], v[152:155], v[200:203], v[28:31]
	v_mfma_f32_16x16x32_bf16 v[24:27], v[160:163], v[200:203], v[24:27]
	v_mfma_f32_16x16x32_bf16 v[12:15], v[152:155], v[208:211], v[12:15]
	v_mfma_f32_16x16x32_bf16 v[8:11], v[160:163], v[208:211], v[8:11]
	v_mfma_f32_16x16x32_bf16 v[60:63], v[156:159], v[188:191], v[60:63]
	v_mfma_f32_16x16x32_bf16 v[56:59], v[164:167], v[188:191], v[56:59]
	v_mfma_f32_16x16x32_bf16 v[44:47], v[156:159], v[196:199], v[44:47]
	v_mfma_f32_16x16x32_bf16 v[40:43], v[164:167], v[196:199], v[40:43]
	v_mfma_f32_16x16x32_bf16 v[28:31], v[156:159], v[204:207], v[28:31]
	v_mfma_f32_16x16x32_bf16 v[24:27], v[164:167], v[204:207], v[24:27]
	v_mfma_f32_16x16x32_bf16 v[12:15], v[156:159], v[212:215], v[12:15]
	v_mfma_f32_16x16x32_bf16 v[8:11], v[164:167], v[212:215], v[8:11]
	s_setprio 0
	s_setprio 1
	v_mfma_f32_16x16x32_bf16 v[52:55], v[168:171], v[184:187], v[52:55]
	v_mfma_f32_16x16x32_bf16 v[48:51], v[176:179], v[184:187], v[48:51]
	v_mfma_f32_16x16x32_bf16 v[36:39], v[168:171], v[192:195], v[36:39]
	v_mfma_f32_16x16x32_bf16 v[32:35], v[176:179], v[192:195], v[32:35]
	v_mfma_f32_16x16x32_bf16 v[20:23], v[168:171], v[200:203], v[20:23]
	v_mfma_f32_16x16x32_bf16 v[16:19], v[176:179], v[200:203], v[16:19]
	v_mfma_f32_16x16x32_bf16 v[4:7], v[168:171], v[208:211], v[4:7]
	v_mfma_f32_16x16x32_bf16 v[0:3], v[176:179], v[208:211], v[0:3]
	v_mfma_f32_16x16x32_bf16 v[52:55], v[172:175], v[188:191], v[52:55]
	v_mfma_f32_16x16x32_bf16 v[48:51], v[180:183], v[188:191], v[48:51]
	v_mfma_f32_16x16x32_bf16 v[36:39], v[172:175], v[196:199], v[36:39]
	v_mfma_f32_16x16x32_bf16 v[32:35], v[180:183], v[196:199], v[32:35]
	v_mfma_f32_16x16x32_bf16 v[20:23], v[172:175], v[204:207], v[20:23]
	v_mfma_f32_16x16x32_bf16 v[16:19], v[180:183], v[204:207], v[16:19]
	v_mfma_f32_16x16x32_bf16 v[4:7], v[172:175], v[212:215], v[4:7]
	v_mfma_f32_16x16x32_bf16 v[0:3], v[180:183], v[212:215], v[0:3]
	s_setprio 0
	s_barrier
	s_add_i32 s69, s69, 2
	s_add_u32 s67, s67, 0x100
	s_addc_u32 s68, s68, 0
	s_add_u32 s40, s40, 0x100
	s_addc_u32 s41, s41, 0
	s_cmp_gt_u32 s69, 29
	s_cbranch_scc0 .LBB0_781
	s_and_b64 vcc, exec, s[10:11]
	s_cbranch_vccz .LBB0_784
	s_barrier

; #define PG8_STAGE(bufoff, gbase, voff) do { _Pragma("unroll") for (int _i = 0; _i < 2; ++_i) \
;         __builtin_amdgcn_global_load_lds((const unsigned*)((const char*)(gbase) + (voff)[_i]), (LAS unsigned*)(lds + (bufoff) + ldsw + _i * 8192), 16, 0, 0); } while (0)
; #define PG8_LDA(dst, b, h) do { _Pragma("unroll") for (int m = 0; m < 4; ++m) _Pragma("unroll") for (int k = 0; k < 2; ++k) dst[m][k] = *(const LAS bf16x8*)(lds + PG8_SA(b, h) + aoff + m * 2048 + k * 1024); } while (0)
; #define PG8_LDB(dst, b, h) do { _Pragma("unroll") for (int n = 0; n < 2; ++n) _Pragma("unroll") for (int k = 0; k < 2; ++k) dst[n][k] = *(const LAS bf16x8*)(lds + PG8_SB(b, h) + boff + n * 2048 + k * 1024); } while (0)
; #define PG8_MMA(ai, bj, At, Bt) do { __builtin_amdgcn_s_setprio(1); _Pragma("unroll") for (int m = 0; m < 4; ++m) _Pragma("unroll") for (int n = 0; n < 2; ++n) _Pragma("unroll") for (int k = 0; k < 2; ++k) \
;         acc[ai][bj][m][n] = __builtin_amdgcn_mfma_f32_16x16x32_bf16(Bt[n][k], At[m][k], acc[ai][bj][m][n], 0, 0, 0); __builtin_amdgcn_s_setprio(0); } while (0)
; #define PG8_WAIT_V(n) asm volatile("s_waitcnt vmcnt(" #n ")" ::: "memory")
; #define PG8_WAIT_L(n) asm volatile("s_waitcnt lgkmcnt(" #n ")" ::: "memory")
; #define PG8_BAR __builtin_amdgcn_s_barrier()
; #define PG8_SCHED __builtin_amdgcn_sched_barrier(0)
; template <class Epi>
; __device__ __forceinline__ void gemm_phase(ldsp lds, const Gemm g, const StaticOrder& S, const Epi& E, int wave0) {
;     ...
;             const bool last = (t == nt - 2);
;             const char* a1 = cA + (size_t)(t + 1) * kstep;
;             const char* a2 = last ? nA : cA + (size_t)(t + 2) * kstep; const char* b2 = last ? nB : cB + (size_t)(t + 2) * kstep;
;             const char* a3 = a2 + kstep; const char* b3 = b2 + kstep;
;             PG8_LDB(B0, 0, 0); PG8_LDB(B1, 0, 1); PG8_SCHED; PG8_LDA(At, 0, 0); PG8_STAGE(PG8_SA(1, 1), a1 + hstep, voffA);
;             PG8_WAIT_V(8); PG8_WAIT_L(0); PG8_BAR; PG8_MMA(0, 0, At, B0); PG8_MMA(0, 1, At, B1); PG8_BAR; PG8_SCHED;
;             PG8_LDA(At, 0, 1); PG8_STAGE(PG8_SB(0, 0), b2, voffB); PG8_STAGE(PG8_SB(0, 1), b2 + hstep, voffB); PG8_STAGE(PG8_SA(0, 0), a2, voffA);
;             PG8_WAIT_V(8); PG8_WAIT_L(0); PG8_BAR; PG8_MMA(1, 0, At, B0); PG8_MMA(1, 1, At, B1); PG8_BAR; PG8_SCHED;
.LBB0_961:
	ds_read_b128 v[152:155], v149
	ds_read_b128 v[156:159], v149 offset:1024
	ds_read_b128 v[160:163], v149 offset:2048
	ds_read_b128 v[164:167], v149 offset:3072
	ds_read_b128 v[168:171], v150
	ds_read_b128 v[172:175], v150 offset:1024
	ds_read_b128 v[176:179], v150 offset:2048
	ds_read_b128 v[180:183], v150 offset:3072
	s_add_u32 s36, s34, 0x100
	s_addc_u32 s37, s35, 0
	s_cmpk_eq_i32 s67, 0x54
	s_cselect_b32 s41, s5, s37
	s_cselect_b32 s40, s4, s36
	s_cselect_b32 s39, s31, s66
	s_cselect_b32 s38, s30, s65
	s_add_i32 m0, s49, 0xc000
	ds_read_b128 v[184:187], v151
	ds_read_b128 v[188:191], v151 offset:1024
	ds_read_b128 v[192:195], v151 offset:2048
	ds_read_b128 v[196:199], v151 offset:3072
	ds_read_b128 v[200:203], v151 offset:4096
	ds_read_b128 v[204:207], v151 offset:5120
	ds_read_b128 v[208:211], v151 offset:6144
	ds_read_b128 v[212:215], v151 offset:7168
	global_load_lds_dwordx4 v138, s[34:35]
	s_add_i32 m0, s49, 0xe000
	s_nop 0
	global_load_lds_dwordx4 v136, s[34:35]
	s_waitcnt vmcnt(8)
	s_waitcnt lgkmcnt(0)
	s_barrier
	s_setprio 1
	s_waitcnt lgkmcnt(0)
	v_mfma_f32_16x16x32_bf16 v[124:127], v[152:155], v[184:187], v[124:127]
	v_mfma_f32_16x16x32_bf16 v[120:123], v[160:163], v[184:187], v[120:123]
	v_mfma_f32_16x16x32_bf16 v[108:111], v[152:155], v[192:195], v[108:111]
	v_mfma_f32_16x16x32_bf16 v[104:107], v[160:163], v[192:195], v[104:107]
	v_mfma_f32_16x16x32_bf16 v[92:95], v[152:155], v[200:203], v[92:95]
	v_mfma_f32_16x16x32_bf16 v[88:91], v[160:163], v[200:203], v[88:91]
	v_mfma_f32_16x16x32_bf16 v[76:79], v[152:155], v[208:211], v[76:79]
	v_mfma_f32_16x16x32_bf16 v[72:75], v[160:163], v[208:211], v[72:75]
	v_mfma_f32_16x16x32_bf16 v[124:127], v[156:159], v[188:191], v[124:127]
	v_mfma_f32_16x16x32_bf16 v[120:123], v[164:167], v[188:191], v[120:123]
	v_mfma_f32_16x16x32_bf16 v[108:111], v[156:159], v[196:199], v[108:111]
	v_mfma_f32_16x16x32_bf16 v[104:107], v[164:167], v[196:199], v[104:107]
	v_mfma_f32_16x16x32_bf16 v[92:95], v[156:159], v[204:207], v[92:95]
	v_mfma_f32_16x16x32_bf16 v[88:91], v[164:167], v[204:207], v[88:91]
	v_mfma_f32_16x16x32_bf16 v[76:79], v[156:159], v[212:215], v[76:79]
	v_mfma_f32_16x16x32_bf16 v[72:75], v[164:167], v[212:215], v[72:75]
	s_setprio 0
	s_setprio 1
	v_mfma_f32_16x16x32_bf16 v[116:119], v[168:171], v[184:187], v[116:119]
	v_mfma_f32_16x16x32_bf16 v[112:115], v[176:179], v[184:187], v[112:115]
	v_mfma_f32_16x16x32_bf16 v[100:103], v[168:171], v[192:195], v[100:103]
	v_mfma_f32_16x16x32_bf16 v[96:99], v[176:179], v[192:195], v[96:99]
	v_mfma_f32_16x16x32_bf16 v[84:87], v[168:171], v[200:203], v[84:87]
	v_mfma_f32_16x16x32_bf16 v[80:83], v[176:179], v[200:203], v[80:83]
	v_mfma_f32_16x16x32_bf16 v[68:71], v[168:171], v[208:211], v[68:71]
	v_mfma_f32_16x16x32_bf16 v[64:67], v[176:179], v[208:211], v[64:67]
	v_mfma_f32_16x16x32_bf16 v[116:119], v[172:175], v[188:191], v[116:119]
	v_mfma_f32_16x16x32_bf16 v[112:115], v[180:183], v[188:191], v[112:115]
	v_mfma_f32_16x16x32_bf16 v[100:103], v[172:175], v[196:199], v[100:103]
	v_mfma_f32_16x16x32_bf16 v[96:99], v[180:183], v[196:199], v[96:99]
	v_mfma_f32_16x16x32_bf16 v[84:87], v[172:175], v[204:207], v[84:87]
	v_mfma_f32_16x16x32_bf16 v[80:83], v[180:183], v[204:207], v[80:83]
	v_mfma_f32_16x16x32_bf16 v[68:71], v[172:175], v[212:215], v[68:71]
	v_mfma_f32_16x16x32_bf16 v[64:67], v[180:183], v[212:215], v[64:67]
	s_setprio 0
	s_barrier
	s_add_i32 s34, s59, s48
	s_mov_b32 m0, s34
	ds_read_b128 v[184:187], v151 offset:16384
	ds_read_b128 v[188:191], v151 offset:17408
	ds_read_b128 v[192:195], v151 offset:18432
	ds_read_b128 v[196:199], v151 offset:19456
	ds_read_b128 v[200:203], v151 offset:20480
	ds_read_b128 v[204:207], v151 offset:21504
	ds_read_b128 v[208:211], v151 offset:22528
	ds_read_b128 v[212:215], v151 offset:23552
	global_load_lds_dwordx4 v130, s[38:39]
	s_add_i32 m0, s34, 0x2000
	s_add_u32 s34, s38, 0x160000
	s_addc_u32 s35, s39, 0
	s_add_i32 s68, s60, s48
	global_load_lds_dwordx4 v134, s[38:39]
	s_mov_b32 m0, s68
	s_nop 0
	global_load_lds_dwordx4 v130, s[34:35]
	s_add_i32 m0, s68, 0x2000
	s_nop 0
	global_load_lds_dwordx4 v134, s[34:35]
	s_mov_b32 m0, s49
	s_nop 0
	global_load_lds_dwordx4 v128, s[40:41]
	s_mov_b32 m0, s50
	s_nop 0
	global_load_lds_dwordx4 v132, s[40:41]
	s_waitcnt vmcnt(8)
	s_waitcnt lgkmcnt(0)
	s_barrier
	s_setprio 1
	s_waitcnt lgkmcnt(0)
	v_mfma_f32_16x16x32_bf16 v[60:63], v[152:155], v[184:187], v[60:63]
	v_mfma_f32_16x16x32_bf16 v[56:59], v[160:163], v[184:187], v[56:59]
	v_mfma_f32_16x16x32_bf16 v[44:47], v[152:155], v[192:195], v[44:47]
	v_mfma_f32_16x16x32_bf16 v[40:43], v[160:163], v[192:195], v[40:43]
	v_mfma_f32_16x16x32_bf16 v[28:31], v[152:155], v[200:203], v[28:31]
	v_mfma_f32_16x16x32_bf16 v[24:27], v[160:163], v[200:203], v[24:27]
	v_mfma_f32_16x16x32_bf16 v[12:15], v[152:155], v[208:211], v[12:15]
	v_mfma_f32_16x16x32_bf16 v[8:11], v[160:163], v[208:211], v[8:11]
	v_mfma_f32_16x16x32_bf16 v[60:63], v[156:159], v[188:191], v[60:63]
	v_mfma_f32_16x16x32_bf16 v[56:59], v[164:167], v[188:191], v[56:59]
	v_mfma_f32_16x16x32_bf16 v[44:47], v[156:159], v[196:199], v[44:47]
	v_mfma_f32_16x16x32_bf16 v[40:43], v[164:167], v[196:199], v[40:43]
	v_mfma_f32_16x16x32_bf16 v[28:31], v[156:159], v[204:207], v[28:31]
	v_mfma_f32_16x16x32_bf16 v[24:27], v[164:167], v[204:207], v[24:27]
	v_mfma_f32_16x16x32_bf16 v[12:15], v[156:159], v[212:215], v[12:15]
	v_mfma_f32_16x16x32_bf16 v[8:11], v[164:167], v[212:215], v[8:11]
	s_setprio 0
	s_setprio 1
	v_mfma_f32_16x16x32_bf16 v[52:55], v[168:171], v[184:187], v[52:55]
	v_mfma_f32_16x16x32_bf16 v[48:51], v[176:179], v[184:187], v[48:51]
	v_mfma_f32_16x16x32_bf16 v[36:39], v[168:171], v[192:195], v[36:39]
	v_mfma_f32_16x16x32_bf16 v[32:35], v[176:179], v[192:195], v[32:35]
	v_mfma_f32_16x16x32_bf16 v[20:23], v[168:171], v[200:203], v[20:23]
	v_mfma_f32_16x16x32_bf16 v[16:19], v[176:179], v[200:203], v[16:19]
	v_mfma_f32_16x16x32_bf16 v[4:7], v[168:171], v[208:211], v[4:7]
	v_mfma_f32_16x16x32_bf16 v[0:3], v[176:179], v[208:211], v[0:3]
	v_mfma_f32_16x16x32_bf16 v[52:55], v[172:175], v[188:191], v[52:55]
	v_mfma_f32_16x16x32_bf16 v[48:51], v[180:183], v[188:191], v[48:51]
	v_mfma_f32_16x16x32_bf16 v[36:39], v[172:175], v[196:199], v[36:39]
	v_mfma_f32_16x16x32_bf16 v[32:35], v[180:183], v[196:199], v[32:35]
	v_mfma_f32_16x16x32_bf16 v[20:23], v[172:175], v[204:207], v[20:23]
	v_mfma_f32_16x16x32_bf16 v[16:19], v[180:183], v[204:207], v[16:19]
	v_mfma_f32_16x16x32_bf16 v[4:7], v[172:175], v[212:215], v[4:7]
	v_mfma_f32_16x16x32_bf16 v[0:3], v[180:183], v[212:215], v[0:3]
	s_setprio 0
	s_barrier
; #define PG8_STAGE(bufoff, gbase, voff) do { _Pragma("unroll") for (int _i = 0; _i < 2; ++_i) \
;         __builtin_amdgcn_global_load_lds((const unsigned*)((const char*)(gbase) + (voff)[_i]), (LAS unsigned*)(lds + (bufoff) + ldsw + _i * 8192), 16, 0, 0); } while (0)
; #define PG8_LDA(dst, b, h) do { _Pragma("unroll") for (int m = 0; m < 4; ++m) _Pragma("unroll") for (int k = 0; k < 2; ++k) dst[m][k] = *(const LAS bf16x8*)(lds + PG8_SA(b, h) + aoff + m * 2048 + k * 1024); } while (0)
; #define PG8_LDB(dst, b, h) do { _Pragma("unroll") for (int n = 0; n < 2; ++n) _Pragma("unroll") for (int k = 0; k < 2; ++k) dst[n][k] = *(const LAS bf16x8*)(lds + PG8_SB(b, h) + boff + n * 2048 + k * 1024); } while (0)
; #define PG8_MMA(ai, bj, At, Bt) do { __builtin_amdgcn_s_setprio(1); _Pragma("unroll") for (int m = 0; m < 4; ++m) _Pragma("unroll") for (int n = 0; n < 2; ++n) _Pragma("unroll") for (int k = 0; k < 2; ++k) \
;         acc[ai][bj][m][n] = __builtin_amdgcn_mfma_f32_16x16x32_bf16(Bt[n][k], At[m][k], acc[ai][bj][m][n], 0, 0, 0); __builtin_amdgcn_s_setprio(0); } while (0)
; #define PG8_WAIT_V(n) asm volatile("s_waitcnt vmcnt(" #n ")" ::: "memory")
; #define PG8_WAIT_L(n) asm volatile("s_waitcnt lgkmcnt(" #n ")" ::: "memory")
; #define PG8_BAR __builtin_amdgcn_s_barrier()
; #define PG8_SCHED __builtin_amdgcn_sched_barrier(0)
; template <class Epi>
; __device__ __forceinline__ void gemm_phase(ldsp lds, const Gemm g, const StaticOrder& S, const Epi& E, int wave0) {
;     ...
;             PG8_LDB(B0, 1, 0); PG8_LDB(B1, 1, 1); PG8_SCHED; PG8_LDA(At, 1, 0); PG8_STAGE(PG8_SA(0, 1), a2 + hstep, voffA);
;             PG8_WAIT_V(8); PG8_WAIT_L(0); PG8_BAR; PG8_MMA(0, 0, At, B0); PG8_MMA(0, 1, At, B1); PG8_BAR; PG8_SCHED;
;             PG8_LDA(At, 1, 1); PG8_STAGE(PG8_SB(1, 0), b3, voffB); PG8_STAGE(PG8_SB(1, 1), b3 + hstep, voffB); PG8_STAGE(PG8_SA(1, 0), a3, voffA);
;             PG8_WAIT_V(8); PG8_WAIT_L(0); PG8_BAR; PG8_MMA(1, 0, At, B0); PG8_MMA(1, 1, At, B1); PG8_BAR; PG8_SCHED;
;         }
	s_add_i32 s68, 0, 0x18000
	s_add_i32 s69, 0, 0x1c000
	v_add_u32_e32 v164, s68, v148
	v_add_u32_e32 v180, s69, v148
	ds_read_b128 v[152:155], v164
	ds_read_b128 v[156:159], v164 offset:1024
	ds_read_b128 v[160:163], v164 offset:2048
	ds_read_b128 v[164:167], v164 offset:3072
	ds_read_b128 v[168:171], v180
	ds_read_b128 v[172:175], v180 offset:1024
	ds_read_b128 v[176:179], v180 offset:2048
	ds_read_b128 v[180:183], v180 offset:3072
	s_add_u32 s34, s40, 0x160000
	s_addc_u32 s35, s41, 0
	s_mov_b32 m0, s51
	ds_read_b128 v[184:187], v151 offset:32768
	ds_read_b128 v[188:191], v151 offset:33792
	ds_read_b128 v[192:195], v151 offset:34816
	ds_read_b128 v[196:199], v151 offset:35840
	ds_read_b128 v[200:203], v151 offset:36864
	ds_read_b128 v[204:207], v151 offset:37888
	ds_read_b128 v[208:211], v151 offset:38912
	ds_read_b128 v[212:215], v151 offset:39936
	global_load_lds_dwordx4 v128, s[34:35]
	s_mov_b32 m0, s52
	s_nop 0
	global_load_lds_dwordx4 v132, s[34:35]
	s_waitcnt vmcnt(8)
	s_waitcnt lgkmcnt(0)
	s_barrier
	s_setprio 1
	s_waitcnt lgkmcnt(0)
	v_mfma_f32_16x16x32_bf16 v[124:127], v[152:155], v[184:187], v[124:127]
	v_mfma_f32_16x16x32_bf16 v[120:123], v[160:163], v[184:187], v[120:123]
	v_mfma_f32_16x16x32_bf16 v[108:111], v[152:155], v[192:195], v[108:111]
	v_mfma_f32_16x16x32_bf16 v[104:107], v[160:163], v[192:195], v[104:107]
	v_mfma_f32_16x16x32_bf16 v[92:95], v[152:155], v[200:203], v[92:95]
	v_mfma_f32_16x16x32_bf16 v[88:91], v[160:163], v[200:203], v[88:91]
	v_mfma_f32_16x16x32_bf16 v[76:79], v[152:155], v[208:211], v[76:79]
	v_mfma_f32_16x16x32_bf16 v[72:75], v[160:163], v[208:211], v[72:75]
	v_mfma_f32_16x16x32_bf16 v[124:127], v[156:159], v[188:191], v[124:127]
	v_mfma_f32_16x16x32_bf16 v[120:123], v[164:167], v[188:191], v[120:123]
	v_mfma_f32_16x16x32_bf16 v[108:111], v[156:159], v[196:199], v[108:111]
	v_mfma_f32_16x16x32_bf16 v[104:107], v[164:167], v[196:199], v[104:107]
	v_mfma_f32_16x16x32_bf16 v[92:95], v[156:159], v[204:207], v[92:95]
	v_mfma_f32_16x16x32_bf16 v[88:91], v[164:167], v[204:207], v[88:91]
	v_mfma_f32_16x16x32_bf16 v[76:79], v[156:159], v[212:215], v[76:79]
	v_mfma_f32_16x16x32_bf16 v[72:75], v[164:167], v[212:215], v[72:75]
	s_setprio 0
	s_setprio 1
	v_mfma_f32_16x16x32_bf16 v[116:119], v[168:171], v[184:187], v[116:119]
	v_mfma_f32_16x16x32_bf16 v[112:115], v[176:179], v[184:187], v[112:115]
	v_mfma_f32_16x16x32_bf16 v[100:103], v[168:171], v[192:195], v[100:103]
	v_mfma_f32_16x16x32_bf16 v[96:99], v[176:179], v[192:195], v[96:99]
	v_mfma_f32_16x16x32_bf16 v[84:87], v[168:171], v[200:203], v[84:87]
	v_mfma_f32_16x16x32_bf16 v[80:83], v[176:179], v[200:203], v[80:83]
	v_mfma_f32_16x16x32_bf16 v[68:71], v[168:171], v[208:211], v[68:71]
	v_mfma_f32_16x16x32_bf16 v[64:67], v[176:179], v[208:211], v[64:67]
	v_mfma_f32_16x16x32_bf16 v[116:119], v[172:175], v[188:191], v[116:119]
	v_mfma_f32_16x16x32_bf16 v[112:115], v[180:183], v[188:191], v[112:115]
	v_mfma_f32_16x16x32_bf16 v[100:103], v[172:175], v[196:199], v[100:103]
	v_mfma_f32_16x16x32_bf16 v[96:99], v[180:183], v[196:199], v[96:99]
	v_mfma_f32_16x16x32_bf16 v[84:87], v[172:175], v[204:207], v[84:87]
	v_mfma_f32_16x16x32_bf16 v[80:83], v[180:183], v[204:207], v[80:83]
	v_mfma_f32_16x16x32_bf16 v[68:71], v[172:175], v[212:215], v[68:71]
	v_mfma_f32_16x16x32_bf16 v[64:67], v[180:183], v[212:215], v[64:67]
	s_setprio 0
	s_barrier
	s_add_i32 s34, s68, s48
	s_add_u32 s100, s38, 0x80
	s_addc_u32 s101, s39, 0
	s_add_u32 s98, s40, 0x80
	s_addc_u32 s99, s41, 0
	s_mov_b32 m0, s34
	ds_read_b128 v[184:187], v151 offset:49152
	ds_read_b128 v[188:191], v151 offset:50176
	ds_read_b128 v[192:195], v151 offset:51200
	ds_read_b128 v[196:199], v151 offset:52224
	ds_read_b128 v[200:203], v151 offset:53248
	ds_read_b128 v[204:207], v151 offset:54272
	ds_read_b128 v[208:211], v151 offset:55296
	ds_read_b128 v[212:215], v151 offset:56320
	global_load_lds_dwordx4 v130, s[100:101]
	s_add_i32 m0, s34, 0x2000
	s_add_u32 s34, s38, 0x160080
	s_addc_u32 s35, s39, 0
	s_add_i32 s38, s69, s48
	global_load_lds_dwordx4 v134, s[100:101]
	s_mov_b32 m0, s38
	s_nop 0
	global_load_lds_dwordx4 v130, s[34:35]
	s_add_i32 m0, s38, 0x2000
	s_nop 0
	global_load_lds_dwordx4 v134, s[34:35]
	s_mov_b32 m0, s56
	s_nop 0
	global_load_lds_dwordx4 v128, s[98:99]
	s_mov_b32 m0, s57
	s_nop 0
	global_load_lds_dwordx4 v132, s[98:99]
	s_waitcnt vmcnt(8)
	s_waitcnt lgkmcnt(0)
	s_barrier
	s_setprio 1
	s_waitcnt lgkmcnt(0)
	v_mfma_f32_16x16x32_bf16 v[60:63], v[152:155], v[184:187], v[60:63]
	v_mfma_f32_16x16x32_bf16 v[56:59], v[160:163], v[184:187], v[56:59]
	v_mfma_f32_16x16x32_bf16 v[44:47], v[152:155], v[192:195], v[44:47]
	v_mfma_f32_16x16x32_bf16 v[40:43], v[160:163], v[192:195], v[40:43]
	v_mfma_f32_16x16x32_bf16 v[28:31], v[152:155], v[200:203], v[28:31]
	v_mfma_f32_16x16x32_bf16 v[24:27], v[160:163], v[200:203], v[24:27]
	v_mfma_f32_16x16x32_bf16 v[12:15], v[152:155], v[208:211], v[12:15]
	v_mfma_f32_16x16x32_bf16 v[8:11], v[160:163], v[208:211], v[8:11]
	v_mfma_f32_16x16x32_bf16 v[60:63], v[156:159], v[188:191], v[60:63]
	v_mfma_f32_16x16x32_bf16 v[56:59], v[164:167], v[188:191], v[56:59]
	v_mfma_f32_16x16x32_bf16 v[44:47], v[156:159], v[196:199], v[44:47]
	v_mfma_f32_16x16x32_bf16 v[40:43], v[164:167], v[196:199], v[40:43]
	v_mfma_f32_16x16x32_bf16 v[28:31], v[156:159], v[204:207], v[28:31]
	v_mfma_f32_16x16x32_bf16 v[24:27], v[164:167], v[204:207], v[24:27]
	v_mfma_f32_16x16x32_bf16 v[12:15], v[156:159], v[212:215], v[12:15]
	v_mfma_f32_16x16x32_bf16 v[8:11], v[164:167], v[212:215], v[8:11]
	s_setprio 0
	s_setprio 1
	v_mfma_f32_16x16x32_bf16 v[52:55], v[168:171], v[184:187], v[52:55]
	v_mfma_f32_16x16x32_bf16 v[48:51], v[176:179], v[184:187], v[48:51]
	v_mfma_f32_16x16x32_bf16 v[36:39], v[168:171], v[192:195], v[36:39]
	v_mfma_f32_16x16x32_bf16 v[32:35], v[176:179], v[192:195], v[32:35]
	v_mfma_f32_16x16x32_bf16 v[20:23], v[168:171], v[200:203], v[20:23]
	v_mfma_f32_16x16x32_bf16 v[16:19], v[176:179], v[200:203], v[16:19]
	v_mfma_f32_16x16x32_bf16 v[4:7], v[168:171], v[208:211], v[4:7]
	v_mfma_f32_16x16x32_bf16 v[0:3], v[176:179], v[208:211], v[0:3]
	v_mfma_f32_16x16x32_bf16 v[52:55], v[172:175], v[188:191], v[52:55]
	v_mfma_f32_16x16x32_bf16 v[48:51], v[180:183], v[188:191], v[48:51]
	v_mfma_f32_16x16x32_bf16 v[36:39], v[172:175], v[196:199], v[36:39]
	v_mfma_f32_16x16x32_bf16 v[32:35], v[180:183], v[196:199], v[32:35]
	v_mfma_f32_16x16x32_bf16 v[20:23], v[172:175], v[204:207], v[20:23]
	v_mfma_f32_16x16x32_bf16 v[16:19], v[180:183], v[204:207], v[16:19]
	v_mfma_f32_16x16x32_bf16 v[4:7], v[172:175], v[212:215], v[4:7]
	v_mfma_f32_16x16x32_bf16 v[0:3], v[180:183], v[212:215], v[0:3]
	s_setprio 0
	s_barrier
	s_add_i32 s67, s67, 2
	s_add_u32 s65, s65, 0x100
	s_addc_u32 s66, s66, 0
	s_cmpk_gt_u32 s67, 0x55
	s_mov_b64 s[34:35], s[36:37]
	s_cbranch_scc0 .LBB0_961
	s_and_b64 vcc, exec, s[12:13]
	s_cbranch_vccz .LBB0_964
	s_barrier

; #define PG8_STAGE(bufoff, gbase, voff) do { _Pragma("unroll") for (int _i = 0; _i < 2; ++_i) \
;         __builtin_amdgcn_global_load_lds((const unsigned*)((const char*)(gbase) + (voff)[_i]), (LAS unsigned*)(lds + (bufoff) + ldsw + _i * 8192), 16, 0, 0); } while (0)
; #define PG8_LDA(dst, b, h) do { _Pragma("unroll") for (int m = 0; m < 4; ++m) _Pragma("unroll") for (int k = 0; k < 2; ++k) dst[m][k] = *(const LAS bf16x8*)(lds + PG8_SA(b, h) + aoff + m * 2048 + k * 1024); } while (0)
; #define PG8_LDB(dst, b, h) do { _Pragma("unroll") for (int n = 0; n < 2; ++n) _Pragma("unroll") for (int k = 0; k < 2; ++k) dst[n][k] = *(const LAS bf16x8*)(lds + PG8_SB(b, h) + boff + n * 2048 + k * 1024); } while (0)
; #define PG8_MMA(ai, bj, At, Bt) do { __builtin_amdgcn_s_setprio(1); _Pragma("unroll") for (int m = 0; m < 4; ++m) _Pragma("unroll") for (int n = 0; n < 2; ++n) _Pragma("unroll") for (int k = 0; k < 2; ++k) \
;         acc[ai][bj][m][n] = __builtin_amdgcn_mfma_f32_16x16x32_bf16(Bt[n][k], At[m][k], acc[ai][bj][m][n], 0, 0, 0); __builtin_amdgcn_s_setprio(0); } while (0)
; #define PG8_WAIT_V(n) asm volatile("s_waitcnt vmcnt(" #n ")" ::: "memory")
; #define PG8_WAIT_L(n) asm volatile("s_waitcnt lgkmcnt(" #n ")" ::: "memory")
; #define PG8_BAR __builtin_amdgcn_s_barrier()
; #define PG8_SCHED __builtin_amdgcn_sched_barrier(0)
; template <class Epi>
; __device__ __forceinline__ void gemm_phase(ldsp lds, const Gemm g, const StaticOrder& S, const Epi& E, int wave0) {
;     ...
;             const bool last = (t == nt - 2);
;             const char* a1 = cA + (size_t)(t + 1) * kstep;
;             const char* a2 = last ? nA : cA + (size_t)(t + 2) * kstep; const char* b2 = last ? nB : cB + (size_t)(t + 2) * kstep;
;             const char* a3 = a2 + kstep; const char* b3 = b2 + kstep;
;             PG8_LDB(B0, 0, 0); PG8_LDB(B1, 0, 1); PG8_SCHED; PG8_LDA(At, 0, 0); PG8_STAGE(PG8_SA(1, 1), a1 + hstep, voffA);
;             PG8_WAIT_V(8); PG8_WAIT_L(0); PG8_BAR; PG8_MMA(0, 0, At, B0); PG8_MMA(0, 1, At, B1); PG8_BAR; PG8_SCHED;
;             PG8_LDA(At, 0, 1); PG8_STAGE(PG8_SB(0, 0), b2, voffB); PG8_STAGE(PG8_SB(0, 1), b2 + hstep, voffB); PG8_STAGE(PG8_SA(0, 0), a2, voffA);
;             PG8_WAIT_V(8); PG8_WAIT_L(0); PG8_BAR; PG8_MMA(1, 0, At, B0); PG8_MMA(1, 1, At, B1); PG8_BAR; PG8_SCHED;
.LBB0_1099:
	ds_read_b128 v[152:155], v149
	ds_read_b128 v[156:159], v149 offset:1024
	ds_read_b128 v[160:163], v149 offset:2048
	ds_read_b128 v[164:167], v149 offset:3072
	ds_read_b128 v[168:171], v150
	ds_read_b128 v[172:175], v150 offset:1024
	ds_read_b128 v[176:179], v150 offset:2048
	ds_read_b128 v[180:183], v150 offset:3072
	s_add_u32 s44, s42, 0xfff80080
	s_addc_u32 s45, s43, -1
	s_cmp_eq_u32 s69, 28
	s_cselect_b32 s47, s35, s45
	s_cselect_b32 s46, s65, s44
	s_cselect_b32 s45, s31, s68
	s_cselect_b32 s44, s66, s67
	s_add_i32 m0, s41, 0xc000
	ds_read_b128 v[184:187], v151
	ds_read_b128 v[188:191], v151 offset:1024
	ds_read_b128 v[192:195], v151 offset:2048
	ds_read_b128 v[196:199], v151 offset:3072
	ds_read_b128 v[200:203], v151 offset:4096
	ds_read_b128 v[204:207], v151 offset:5120
	ds_read_b128 v[208:211], v151 offset:6144
	ds_read_b128 v[212:215], v151 offset:7168
	global_load_lds_dwordx4 v138, s[42:43]
	s_add_i32 m0, s41, 0xe000
	s_nop 0
	global_load_lds_dwordx4 v136, s[42:43]
	s_waitcnt vmcnt(8)
	s_waitcnt lgkmcnt(0)
	s_barrier
	s_setprio 1
	s_waitcnt lgkmcnt(0)
	v_mfma_f32_16x16x32_bf16 v[124:127], v[152:155], v[184:187], v[124:127]
	v_mfma_f32_16x16x32_bf16 v[120:123], v[160:163], v[184:187], v[120:123]
	v_mfma_f32_16x16x32_bf16 v[108:111], v[152:155], v[192:195], v[108:111]
	v_mfma_f32_16x16x32_bf16 v[104:107], v[160:163], v[192:195], v[104:107]
	v_mfma_f32_16x16x32_bf16 v[92:95], v[152:155], v[200:203], v[92:95]
	v_mfma_f32_16x16x32_bf16 v[88:91], v[160:163], v[200:203], v[88:91]
	v_mfma_f32_16x16x32_bf16 v[76:79], v[152:155], v[208:211], v[76:79]
	v_mfma_f32_16x16x32_bf16 v[72:75], v[160:163], v[208:211], v[72:75]
	v_mfma_f32_16x16x32_bf16 v[124:127], v[156:159], v[188:191], v[124:127]
	v_mfma_f32_16x16x32_bf16 v[120:123], v[164:167], v[188:191], v[120:123]
	v_mfma_f32_16x16x32_bf16 v[108:111], v[156:159], v[196:199], v[108:111]
	v_mfma_f32_16x16x32_bf16 v[104:107], v[164:167], v[196:199], v[104:107]
	v_mfma_f32_16x16x32_bf16 v[92:95], v[156:159], v[204:207], v[92:95]
	v_mfma_f32_16x16x32_bf16 v[88:91], v[164:167], v[204:207], v[88:91]
	v_mfma_f32_16x16x32_bf16 v[76:79], v[156:159], v[212:215], v[76:79]
	v_mfma_f32_16x16x32_bf16 v[72:75], v[164:167], v[212:215], v[72:75]
	s_setprio 0
	s_setprio 1
	v_mfma_f32_16x16x32_bf16 v[116:119], v[168:171], v[184:187], v[116:119]
	v_mfma_f32_16x16x32_bf16 v[112:115], v[176:179], v[184:187], v[112:115]
	v_mfma_f32_16x16x32_bf16 v[100:103], v[168:171], v[192:195], v[100:103]
	v_mfma_f32_16x16x32_bf16 v[96:99], v[176:179], v[192:195], v[96:99]
	v_mfma_f32_16x16x32_bf16 v[84:87], v[168:171], v[200:203], v[84:87]
	v_mfma_f32_16x16x32_bf16 v[80:83], v[176:179], v[200:203], v[80:83]
	v_mfma_f32_16x16x32_bf16 v[68:71], v[168:171], v[208:211], v[68:71]
	v_mfma_f32_16x16x32_bf16 v[64:67], v[176:179], v[208:211], v[64:67]
	v_mfma_f32_16x16x32_bf16 v[116:119], v[172:175], v[188:191], v[116:119]
	v_mfma_f32_16x16x32_bf16 v[112:115], v[180:183], v[188:191], v[112:115]
	v_mfma_f32_16x16x32_bf16 v[100:103], v[172:175], v[196:199], v[100:103]
	v_mfma_f32_16x16x32_bf16 v[96:99], v[180:183], v[196:199], v[96:99]
	v_mfma_f32_16x16x32_bf16 v[84:87], v[172:175], v[204:207], v[84:87]
	v_mfma_f32_16x16x32_bf16 v[80:83], v[180:183], v[204:207], v[80:83]
	v_mfma_f32_16x16x32_bf16 v[68:71], v[172:175], v[212:215], v[68:71]
	v_mfma_f32_16x16x32_bf16 v[64:67], v[180:183], v[212:215], v[64:67]
	s_setprio 0
	s_barrier
	s_add_i32 s70, s62, s52
	s_add_u32 s100, s46, 0x80
	s_addc_u32 s101, s47, 0
	s_mov_b32 m0, s70
	ds_read_b128 v[184:187], v151 offset:16384
	ds_read_b128 v[188:191], v151 offset:17408
	ds_read_b128 v[192:195], v151 offset:18432
	ds_read_b128 v[196:199], v151 offset:19456
	ds_read_b128 v[200:203], v151 offset:20480
	ds_read_b128 v[204:207], v151 offset:21504
	ds_read_b128 v[208:211], v151 offset:22528
	ds_read_b128 v[212:215], v151 offset:23552
	global_load_lds_dwordx4 v130, s[44:45]
	s_add_i32 m0, s70, 0x2000
	s_add_u32 s70, s44, 0x80000
	s_addc_u32 s71, s45, 0
	s_add_i32 s72, s63, s52
	global_load_lds_dwordx4 v134, s[44:45]
	s_mov_b32 m0, s72
	s_nop 0
	global_load_lds_dwordx4 v130, s[70:71]
	s_add_i32 m0, s72, 0x2000
	s_nop 0
	global_load_lds_dwordx4 v134, s[70:71]
	s_mov_b32 m0, s41
	s_nop 0
	global_load_lds_dwordx4 v128, s[46:47]
	s_mov_b32 m0, s53
	s_nop 0
	global_load_lds_dwordx4 v132, s[46:47]
	s_waitcnt vmcnt(8)
	s_waitcnt lgkmcnt(0)
	s_barrier
	s_setprio 1
	s_waitcnt lgkmcnt(0)
	v_mfma_f32_16x16x32_bf16 v[60:63], v[152:155], v[184:187], v[60:63]
	v_mfma_f32_16x16x32_bf16 v[56:59], v[160:163], v[184:187], v[56:59]
	v_mfma_f32_16x16x32_bf16 v[44:47], v[152:155], v[192:195], v[44:47]
	v_mfma_f32_16x16x32_bf16 v[40:43], v[160:163], v[192:195], v[40:43]
	v_mfma_f32_16x16x32_bf16 v[28:31], v[152:155], v[200:203], v[28:31]
	v_mfma_f32_16x16x32_bf16 v[24:27], v[160:163], v[200:203], v[24:27]
	v_mfma_f32_16x16x32_bf16 v[12:15], v[152:155], v[208:211], v[12:15]
	v_mfma_f32_16x16x32_bf16 v[8:11], v[160:163], v[208:211], v[8:11]
	v_mfma_f32_16x16x32_bf16 v[60:63], v[156:159], v[188:191], v[60:63]
	v_mfma_f32_16x16x32_bf16 v[56:59], v[164:167], v[188:191], v[56:59]
	v_mfma_f32_16x16x32_bf16 v[44:47], v[156:159], v[196:199], v[44:47]
	v_mfma_f32_16x16x32_bf16 v[40:43], v[164:167], v[196:199], v[40:43]
	v_mfma_f32_16x16x32_bf16 v[28:31], v[156:159], v[204:207], v[28:31]
	v_mfma_f32_16x16x32_bf16 v[24:27], v[164:167], v[204:207], v[24:27]
	v_mfma_f32_16x16x32_bf16 v[12:15], v[156:159], v[212:215], v[12:15]
	v_mfma_f32_16x16x32_bf16 v[8:11], v[164:167], v[212:215], v[8:11]
	s_setprio 0
	s_setprio 1
	v_mfma_f32_16x16x32_bf16 v[52:55], v[168:171], v[184:187], v[52:55]
	v_mfma_f32_16x16x32_bf16 v[48:51], v[176:179], v[184:187], v[48:51]
	v_mfma_f32_16x16x32_bf16 v[36:39], v[168:171], v[192:195], v[36:39]
	v_mfma_f32_16x16x32_bf16 v[32:35], v[176:179], v[192:195], v[32:35]
	v_mfma_f32_16x16x32_bf16 v[20:23], v[168:171], v[200:203], v[20:23]
	v_mfma_f32_16x16x32_bf16 v[16:19], v[176:179], v[200:203], v[16:19]
	v_mfma_f32_16x16x32_bf16 v[4:7], v[168:171], v[208:211], v[4:7]
	v_mfma_f32_16x16x32_bf16 v[0:3], v[176:179], v[208:211], v[0:3]
	v_mfma_f32_16x16x32_bf16 v[52:55], v[172:175], v[188:191], v[52:55]
	v_mfma_f32_16x16x32_bf16 v[48:51], v[180:183], v[188:191], v[48:51]
	v_mfma_f32_16x16x32_bf16 v[36:39], v[172:175], v[196:199], v[36:39]
	v_mfma_f32_16x16x32_bf16 v[32:35], v[180:183], v[196:199], v[32:35]
	v_mfma_f32_16x16x32_bf16 v[20:23], v[172:175], v[204:207], v[20:23]
	v_mfma_f32_16x16x32_bf16 v[16:19], v[180:183], v[204:207], v[16:19]
	v_mfma_f32_16x16x32_bf16 v[4:7], v[172:175], v[212:215], v[4:7]
	v_mfma_f32_16x16x32_bf16 v[0:3], v[180:183], v[212:215], v[0:3]
	s_setprio 0
	s_barrier
; #define PG8_STAGE(bufoff, gbase, voff) do { _Pragma("unroll") for (int _i = 0; _i < 2; ++_i) \
;         __builtin_amdgcn_global_load_lds((const unsigned*)((const char*)(gbase) + (voff)[_i]), (LAS unsigned*)(lds + (bufoff) + ldsw + _i * 8192), 16, 0, 0); } while (0)
; #define PG8_LDA(dst, b, h) do { _Pragma("unroll") for (int m = 0; m < 4; ++m) _Pragma("unroll") for (int k = 0; k < 2; ++k) dst[m][k] = *(const LAS bf16x8*)(lds + PG8_SA(b, h) + aoff + m * 2048 + k * 1024); } while (0)
; #define PG8_LDB(dst, b, h) do { _Pragma("unroll") for (int n = 0; n < 2; ++n) _Pragma("unroll") for (int k = 0; k < 2; ++k) dst[n][k] = *(const LAS bf16x8*)(lds + PG8_SB(b, h) + boff + n * 2048 + k * 1024); } while (0)
; #define PG8_MMA(ai, bj, At, Bt) do { __builtin_amdgcn_s_setprio(1); _Pragma("unroll") for (int m = 0; m < 4; ++m) _Pragma("unroll") for (int n = 0; n < 2; ++n) _Pragma("unroll") for (int k = 0; k < 2; ++k) \
;         acc[ai][bj][m][n] = __builtin_amdgcn_mfma_f32_16x16x32_bf16(Bt[n][k], At[m][k], acc[ai][bj][m][n], 0, 0, 0); __builtin_amdgcn_s_setprio(0); } while (0)
; #define PG8_WAIT_V(n) asm volatile("s_waitcnt vmcnt(" #n ")" ::: "memory")
; #define PG8_WAIT_L(n) asm volatile("s_waitcnt lgkmcnt(" #n ")" ::: "memory")
; #define PG8_BAR __builtin_amdgcn_s_barrier()
; #define PG8_SCHED __builtin_amdgcn_sched_barrier(0)
; template <class Epi>
; __device__ __forceinline__ void gemm_phase(ldsp lds, const Gemm g, const StaticOrder& S, const Epi& E, int wave0) {
;     ...
;             PG8_LDB(B0, 1, 0); PG8_LDB(B1, 1, 1); PG8_SCHED; PG8_LDA(At, 1, 0); PG8_STAGE(PG8_SA(0, 1), a2 + hstep, voffA);
;             PG8_WAIT_V(8); PG8_WAIT_L(0); PG8_BAR; PG8_MMA(0, 0, At, B0); PG8_MMA(0, 1, At, B1); PG8_BAR; PG8_SCHED;
;             PG8_LDA(At, 1, 1); PG8_STAGE(PG8_SB(1, 0), b3, voffB); PG8_STAGE(PG8_SB(1, 1), b3 + hstep, voffB); PG8_STAGE(PG8_SA(1, 0), a3, voffA);
;             PG8_WAIT_V(8); PG8_WAIT_L(0); PG8_BAR; PG8_MMA(1, 0, At, B0); PG8_MMA(1, 1, At, B1); PG8_BAR; PG8_SCHED;
;         }
	s_add_i32 s70, 0, 0x18000
	s_add_i32 s71, 0, 0x1c000
	v_add_u32_e32 v164, s70, v148
	v_add_u32_e32 v180, s71, v148
	ds_read_b128 v[152:155], v164
	ds_read_b128 v[156:159], v164 offset:1024
	ds_read_b128 v[160:163], v164 offset:2048
	ds_read_b128 v[164:167], v164 offset:3072
	ds_read_b128 v[168:171], v180
	ds_read_b128 v[172:175], v180 offset:1024
	ds_read_b128 v[176:179], v180 offset:2048
	ds_read_b128 v[180:183], v180 offset:3072
	s_add_u32 s46, s46, 0x80000
	s_addc_u32 s47, s47, 0
	s_mov_b32 m0, s54
	ds_read_b128 v[184:187], v151 offset:32768
	ds_read_b128 v[188:191], v151 offset:33792
	ds_read_b128 v[192:195], v151 offset:34816
	ds_read_b128 v[196:199], v151 offset:35840
	ds_read_b128 v[200:203], v151 offset:36864
	ds_read_b128 v[204:207], v151 offset:37888
	ds_read_b128 v[208:211], v151 offset:38912
	ds_read_b128 v[212:215], v151 offset:39936
	global_load_lds_dwordx4 v128, s[46:47]
	s_mov_b32 m0, s55
	s_nop 0
	global_load_lds_dwordx4 v132, s[46:47]
	s_waitcnt vmcnt(8)
	s_waitcnt lgkmcnt(0)
	s_barrier
	s_setprio 1
	s_waitcnt lgkmcnt(0)
	v_mfma_f32_16x16x32_bf16 v[124:127], v[152:155], v[184:187], v[124:127]
	v_mfma_f32_16x16x32_bf16 v[120:123], v[160:163], v[184:187], v[120:123]
	v_mfma_f32_16x16x32_bf16 v[108:111], v[152:155], v[192:195], v[108:111]
	v_mfma_f32_16x16x32_bf16 v[104:107], v[160:163], v[192:195], v[104:107]
	v_mfma_f32_16x16x32_bf16 v[92:95], v[152:155], v[200:203], v[92:95]
	v_mfma_f32_16x16x32_bf16 v[88:91], v[160:163], v[200:203], v[88:91]
	v_mfma_f32_16x16x32_bf16 v[76:79], v[152:155], v[208:211], v[76:79]
	v_mfma_f32_16x16x32_bf16 v[72:75], v[160:163], v[208:211], v[72:75]
	v_mfma_f32_16x16x32_bf16 v[124:127], v[156:159], v[188:191], v[124:127]
	v_mfma_f32_16x16x32_bf16 v[120:123], v[164:167], v[188:191], v[120:123]
	v_mfma_f32_16x16x32_bf16 v[108:111], v[156:159], v[196:199], v[108:111]
	v_mfma_f32_16x16x32_bf16 v[104:107], v[164:167], v[196:199], v[104:107]
	v_mfma_f32_16x16x32_bf16 v[92:95], v[156:159], v[204:207], v[92:95]
	v_mfma_f32_16x16x32_bf16 v[88:91], v[164:167], v[204:207], v[88:91]
	v_mfma_f32_16x16x32_bf16 v[76:79], v[156:159], v[212:215], v[76:79]
	v_mfma_f32_16x16x32_bf16 v[72:75], v[164:167], v[212:215], v[72:75]
	s_setprio 0
	s_setprio 1
	v_mfma_f32_16x16x32_bf16 v[116:119], v[168:171], v[184:187], v[116:119]
	v_mfma_f32_16x16x32_bf16 v[112:115], v[176:179], v[184:187], v[112:115]
	v_mfma_f32_16x16x32_bf16 v[100:103], v[168:171], v[192:195], v[100:103]
	v_mfma_f32_16x16x32_bf16 v[96:99], v[176:179], v[192:195], v[96:99]
	v_mfma_f32_16x16x32_bf16 v[84:87], v[168:171], v[200:203], v[84:87]
	v_mfma_f32_16x16x32_bf16 v[80:83], v[176:179], v[200:203], v[80:83]
	v_mfma_f32_16x16x32_bf16 v[68:71], v[168:171], v[208:211], v[68:71]
	v_mfma_f32_16x16x32_bf16 v[64:67], v[176:179], v[208:211], v[64:67]
	v_mfma_f32_16x16x32_bf16 v[116:119], v[172:175], v[188:191], v[116:119]
	v_mfma_f32_16x16x32_bf16 v[112:115], v[180:183], v[188:191], v[112:115]
	v_mfma_f32_16x16x32_bf16 v[100:103], v[172:175], v[196:199], v[100:103]
	v_mfma_f32_16x16x32_bf16 v[96:99], v[180:183], v[196:199], v[96:99]
	v_mfma_f32_16x16x32_bf16 v[84:87], v[172:175], v[204:207], v[84:87]
	v_mfma_f32_16x16x32_bf16 v[80:83], v[180:183], v[204:207], v[80:83]
	v_mfma_f32_16x16x32_bf16 v[68:71], v[172:175], v[212:215], v[68:71]
	v_mfma_f32_16x16x32_bf16 v[64:67], v[180:183], v[212:215], v[64:67]
	s_setprio 0
	s_barrier
	s_add_i32 s46, s70, s52
	s_add_u32 s44, s44, 0x80
	s_addc_u32 s45, s45, 0
	s_mov_b32 m0, s46
	ds_read_b128 v[184:187], v151 offset:49152
	ds_read_b128 v[188:191], v151 offset:50176
	ds_read_b128 v[192:195], v151 offset:51200
	ds_read_b128 v[196:199], v151 offset:52224
	ds_read_b128 v[200:203], v151 offset:53248
	ds_read_b128 v[204:207], v151 offset:54272
	ds_read_b128 v[208:211], v151 offset:55296
	ds_read_b128 v[212:215], v151 offset:56320
	global_load_lds_dwordx4 v130, s[44:45]
	s_add_i32 m0, s46, 0x2000
	s_add_i32 s46, s71, s52
	global_load_lds_dwordx4 v134, s[44:45]
	s_add_u32 s44, s44, 0x80000
	s_addc_u32 s45, s45, 0
	s_mov_b32 m0, s46
	s_nop 0
	global_load_lds_dwordx4 v130, s[44:45]
	s_add_i32 m0, s46, 0x2000
	s_nop 0
	global_load_lds_dwordx4 v134, s[44:45]
	s_mov_b32 m0, s59
	s_nop 0
	global_load_lds_dwordx4 v128, s[100:101]
	s_mov_b32 m0, s60
	s_nop 0
	global_load_lds_dwordx4 v132, s[100:101]
	s_waitcnt vmcnt(8)
	s_waitcnt lgkmcnt(0)
	s_barrier
	s_setprio 1
	s_waitcnt lgkmcnt(0)
	v_mfma_f32_16x16x32_bf16 v[60:63], v[152:155], v[184:187], v[60:63]
	v_mfma_f32_16x16x32_bf16 v[56:59], v[160:163], v[184:187], v[56:59]
	v_mfma_f32_16x16x32_bf16 v[44:47], v[152:155], v[192:195], v[44:47]
	v_mfma_f32_16x16x32_bf16 v[40:43], v[160:163], v[192:195], v[40:43]
	v_mfma_f32_16x16x32_bf16 v[28:31], v[152:155], v[200:203], v[28:31]
	v_mfma_f32_16x16x32_bf16 v[24:27], v[160:163], v[200:203], v[24:27]
	v_mfma_f32_16x16x32_bf16 v[12:15], v[152:155], v[208:211], v[12:15]
	v_mfma_f32_16x16x32_bf16 v[8:11], v[160:163], v[208:211], v[8:11]
	v_mfma_f32_16x16x32_bf16 v[60:63], v[156:159], v[188:191], v[60:63]
	v_mfma_f32_16x16x32_bf16 v[56:59], v[164:167], v[188:191], v[56:59]
	v_mfma_f32_16x16x32_bf16 v[44:47], v[156:159], v[196:199], v[44:47]
	v_mfma_f32_16x16x32_bf16 v[40:43], v[164:167], v[196:199], v[40:43]
	v_mfma_f32_16x16x32_bf16 v[28:31], v[156:159], v[204:207], v[28:31]
	v_mfma_f32_16x16x32_bf16 v[24:27], v[164:167], v[204:207], v[24:27]
	v_mfma_f32_16x16x32_bf16 v[12:15], v[156:159], v[212:215], v[12:15]
	v_mfma_f32_16x16x32_bf16 v[8:11], v[164:167], v[212:215], v[8:11]
	s_setprio 0
	s_setprio 1
	v_mfma_f32_16x16x32_bf16 v[52:55], v[168:171], v[184:187], v[52:55]
	v_mfma_f32_16x16x32_bf16 v[48:51], v[176:179], v[184:187], v[48:51]
	v_mfma_f32_16x16x32_bf16 v[36:39], v[168:171], v[192:195], v[36:39]
	v_mfma_f32_16x16x32_bf16 v[32:35], v[176:179], v[192:195], v[32:35]
	v_mfma_f32_16x16x32_bf16 v[20:23], v[168:171], v[200:203], v[20:23]
	v_mfma_f32_16x16x32_bf16 v[16:19], v[176:179], v[200:203], v[16:19]
	v_mfma_f32_16x16x32_bf16 v[4:7], v[168:171], v[208:211], v[4:7]
	v_mfma_f32_16x16x32_bf16 v[0:3], v[176:179], v[208:211], v[0:3]
	v_mfma_f32_16x16x32_bf16 v[52:55], v[172:175], v[188:191], v[52:55]
	v_mfma_f32_16x16x32_bf16 v[48:51], v[180:183], v[188:191], v[48:51]
	v_mfma_f32_16x16x32_bf16 v[36:39], v[172:175], v[196:199], v[36:39]
	v_mfma_f32_16x16x32_bf16 v[32:35], v[180:183], v[196:199], v[32:35]
	v_mfma_f32_16x16x32_bf16 v[20:23], v[172:175], v[204:207], v[20:23]
	v_mfma_f32_16x16x32_bf16 v[16:19], v[180:183], v[204:207], v[16:19]
	v_mfma_f32_16x16x32_bf16 v[4:7], v[172:175], v[212:215], v[4:7]
	v_mfma_f32_16x16x32_bf16 v[0:3], v[180:183], v[212:215], v[0:3]
	s_setprio 0
	s_barrier
	s_add_i32 s69, s69, 2
	s_add_u32 s67, s67, 0x100
	s_addc_u32 s68, s68, 0
	s_add_u32 s42, s42, 0x100
	s_addc_u32 s43, s43, 0
	s_cmp_gt_u32 s69, 29
	s_cbranch_scc0 .LBB0_1099
	s_and_b64 vcc, exec, s[12:13]
	s_cbranch_vccz .LBB0_1102
	s_barrier

; __global__ void __launch_bounds__(512, 2) fwd_megakernel(Args a) {
;     extern __shared__ __attribute__((aligned(16))) unsigned char lds_raw[];
	.amdhsa_kernel _Z14fwd_megakernel4Args
		.amdhsa_group_segment_fixed_size 0
		.amdhsa_private_segment_fixed_size 0
		.amdhsa_kernarg_size 696
		.amdhsa_user_sgpr_count 2
		.amdhsa_user_sgpr_dispatch_ptr 0
		.amdhsa_user_sgpr_queue_ptr 0
		.amdhsa_user_sgpr_kernarg_segment_ptr 1
		.amdhsa_user_sgpr_dispatch_id 0
		.amdhsa_user_sgpr_kernarg_preload_length 0
		.amdhsa_user_sgpr_kernarg_preload_offset 0
		.amdhsa_user_sgpr_private_segment_size 0
		.amdhsa_uses_dynamic_stack 0
		.amdhsa_enable_private_segment 0
		.amdhsa_system_sgpr_workgroup_id_x 1
		.amdhsa_system_sgpr_workgroup_id_y 0
		.amdhsa_system_sgpr_workgroup_id_z 0
		.amdhsa_system_sgpr_workgroup_info 0
		.amdhsa_system_vgpr_workitem_id 2
		.amdhsa_next_free_vgpr 256
		.amdhsa_next_free_sgpr 102
		.amdhsa_accum_offset 256
		.amdhsa_reserve_vcc 1
		.amdhsa_float_round_mode_32 0
		.amdhsa_float_round_mode_16_64 0
		.amdhsa_float_denorm_mode_32 3
		.amdhsa_float_denorm_mode_16_64 3
		.amdhsa_dx10_clamp 1
		.amdhsa_ieee_mode 1
		.amdhsa_fp16_overflow 0
		.amdhsa_tg_split 0
		.amdhsa_exception_fp_ieee_invalid_op 0
		.amdhsa_exception_fp_denorm_src 0
		.amdhsa_exception_fp_ieee_div_zero 0
		.amdhsa_exception_fp_ieee_overflow 0
		.amdhsa_exception_fp_ieee_underflow 0
		.amdhsa_exception_fp_ieee_inexact 0
		.amdhsa_exception_int_div_zero 0
	.end_amdhsa_kernel

amdhsa.kernels:
  - .agpr_count:     0
    .args:
      - .offset:         0
        .size:           440
        .value_kind:     by_value
      - .offset:         440
        .size:           4
        .value_kind:     hidden_block_count_x
      - .offset:         444
        .size:           4
        .value_kind:     hidden_block_count_y
      - .offset:         448
        .size:           4
        .value_kind:     hidden_block_count_z
      - .offset:         452
        .size:           2
        .value_kind:     hidden_group_size_x
      - .offset:         454
        .size:           2
        .value_kind:     hidden_group_size_y
      - .offset:         456
        .size:           2
        .value_kind:     hidden_group_size_z
      - .offset:         458
        .size:           2
        .value_kind:     hidden_remainder_x
      - .offset:         460
        .size:           2
        .value_kind:     hidden_remainder_y
      - .offset:         462
        .size:           2
        .value_kind:     hidden_remainder_z
      - .offset:         480
        .size:           8
        .value_kind:     hidden_global_offset_x
      - .offset:         488
        .size:           8
        .value_kind:     hidden_global_offset_y
      - .offset:         496
        .size:           8
        .value_kind:     hidden_global_offset_z
      - .offset:         504
        .size:           2
        .value_kind:     hidden_grid_dims
      - .offset:         528
        .size:           8
        .value_kind:     hidden_multigrid_sync_arg
      - .offset:         560
        .size:           4
        .value_kind:     hidden_dynamic_lds_size
    .group_segment_fixed_size: 0
    .kernarg_segment_align: 8
    .kernarg_segment_size: 696
    .language:       OpenCL C
    .language_version:
      - 2
      - 0
    .max_flat_workgroup_size: 512
    .name:           _Z14fwd_megakernel4Args
    .private_segment_fixed_size: 0
    .sgpr_count:     108
    .sgpr_spill_count: 97
    .symbol:         _Z14fwd_megakernel4Args.kd
    .uniform_work_group_size: 1
    .uses_dynamic_stack: false
    .vgpr_count:     256
    .vgpr_spill_count: 0
    .wavefront_size: 64
